# no final barrier; hgrn ushort load ladders de-serialized; all hgrn stage-1 units on the hgrn workgroups
# speedup vs baseline: 1.1062x; 1.1062x over previous
.LBB0_6:
	s_lshl_b32 s82, s80, 3
	s_lshl_b32 s6, s78, 3
	s_cmpk_lg_i32 s80, 0x100
	s_cselect_b64 s[0:1], -1, 0
	v_writelane_b32 v252, s0, 6
	s_cmpk_lt_i32 s78, 0xc0
	v_mov_b32_e32 v208, 0x358637bd
	v_writelane_b32 v252, s1, 7
	s_cselect_b64 s[0:1], -1, 0
	v_writelane_b32 v252, s0, 8
	v_mov_b32_e32 v209, 0x260
	v_mov_b32_e32 v220, 1
	v_writelane_b32 v252, s1, 9
	s_add_i32 s0, s80, -1
	s_cmp_eq_u32 s78, s0
	s_cselect_b64 s[0:1], -1, 0
	v_writelane_b32 v252, s0, 10
	s_cmpk_eq_i32 s80, 0x100
	v_mov_b32_e32 v212, 0x3c0881c4
	v_writelane_b32 v252, s1, 11
	s_cselect_b64 s[0:1], -1, 0
	v_writelane_b32 v252, s0, 12
	v_mov_b32_e32 v213, 0xbab64f3b
	v_mov_b64_e32 v[182:183], 0x100
	v_writelane_b32 v252, s1, 13
	s_and_b64 s[0:1], s[0:1], exec
	s_cselect_b32 s7, 0x4000, 0
	s_cmpk_lt_u32 s78, 0x100
	s_cselect_b64 s[0:1], -1, 0
	v_writelane_b32 v252, s0, 14
	s_ashr_i32 s79, s80, 31
	s_ashr_i32 s84, s78, 31
	v_writelane_b32 v252, s1, 15
	s_and_b32 s0, s6, 56
	s_bfe_u32 s1, s78, 0x30003
	s_or_b32 s0, s1, s0
	v_writelane_b32 v252, s0, 16
	s_lshr_b32 s0, s78, 6
	v_writelane_b32 v252, s0, 17
	s_mul_i32 s0, s80, 3
	s_ashr_i32 s1, s0, 31
	s_lshr_b32 s1, s1, 30
	s_add_i32 s0, s0, s1
	s_ashr_i32 s0, s0, 2
	s_cmp_gt_i32 s80, 1
	s_cselect_b32 s8, s0, 1
	s_mov_b32 s0, 0
	s_sub_i32 s3, s80, s8
	s_sub_i32 s5, s78, s8
	s_lshl_b32 s0, s0, 3
	s_min_i32 s9, s8, 0x180
	v_writelane_b32 v252, s0, 18
	s_add_i32 s0, s0, s5
	s_lshl_b32 s2, s3, 3
	s_cmp_ge_i32 s78, s8
	v_writelane_b32 v252, s0, 19
	s_cselect_b64 s[0:1], -1, 0
	v_writelane_b32 v252, s0, 20
	v_mov_b64_e32 v[184:185], 0xff
	v_mov_b32_e32 v215, 0x7fc00000
	v_writelane_b32 v252, s1, 21
	s_and_b64 s[0:1], s[0:1], exec
	s_cselect_b32 s0, s2, 0x840
	v_writelane_b32 v252, s0, 22
	s_lshl_b32 s0, s3, 9
	v_writelane_b32 v252, s0, 23
	s_lshl_b32 s0, s5, 9
	v_writelane_b32 v252, s0, 24
	s_lshl_b32 s0, s3, 10
	v_writelane_b32 v252, s0, 25
	s_add_i32 s0, s3, s80
	s_cmp_lt_i32 s5, 32
	v_writelane_b32 v252, s0, 26
	s_cselect_b64 s[0:1], -1, 0
	v_writelane_b32 v252, s0, 27
	s_lshl_b32 s85, s3, 2
	v_mov_b32_e32 v216, 0x79
	v_writelane_b32 v252, s1, 28
	v_writelane_b32 v252, s3, 29
	s_add_i32 s0, s9, s5
	v_writelane_b32 v252, s5, 30
	s_cmpk_lt_i32 s0, 0x180
	v_writelane_b32 v252, s0, 31
	s_cselect_b64 s[0:1], -1, 0
	v_writelane_b32 v252, s0, 32
	s_cmpk_lt_i32 s78, 0x180
	v_mov_b32_e32 v217, 0xe00
	v_writelane_b32 v252, s1, 33
	s_cselect_b64 s[0:1], -1, 0
	v_writelane_b32 v252, s0, 34
	s_cmp_lt_i32 s78, s9
	v_mov_b32_e32 v218, 0x7c
	v_writelane_b32 v252, s1, 35
	v_writelane_b32 v252, s9, 36
	s_cselect_b64 s[0:1], -1, 0
	v_writelane_b32 v252, s0, 37
	s_cmp_lt_i32 s78, 24
	v_mov_b32_e32 v219, 0xff800000
	v_writelane_b32 v252, s1, 38
	s_cselect_b64 s[0:1], -1, 0
	v_writelane_b32 v252, s0, 39
	s_cmpk_lt_i32 s78, 0x318
	v_not_b32_e32 v221, 63
	v_writelane_b32 v252, s1, 40
	s_cselect_b64 s[0:1], -1, 0
	v_writelane_b32 v252, s0, 41
	v_not_b32_e32 v222, 31
	s_movk_i32 s87, 0x3000
	v_writelane_b32 v252, s1, 42
	s_lshr_b32 s0, s84, 29
	s_add_i32 s0, s78, s0
	s_ashr_i32 s2, s0, 3
	s_and_b32 s0, s0, -8
	s_sub_i32 s3, s78, s0
	s_cmp_lt_i32 s54, 0
	s_cselect_b64 s[0:1], -1, 0
	v_writelane_b32 v252, s0, 43
	s_movk_i32 s90, 0x1800
	s_mov_b32 s91, 0x12000
	v_writelane_b32 v252, s1, 44
	s_add_u32 s0, s52, 0x200
	s_addc_u32 s1, s53, 0
	v_writelane_b32 v252, s0, 45
	s_movk_i32 s92, 0x5000
	s_movk_i32 s93, 0x2000
	v_writelane_b32 v252, s1, 46
	s_add_u32 s0, s52, 0x1000
	s_addc_u32 s1, s53, 0
	v_writelane_b32 v252, s0, 47
	s_mov_b32 s94, 0x10000
	s_movk_i32 s95, 0x6000
	v_writelane_b32 v252, s1, 48
	s_add_u32 s0, s52, 0x1100
	s_addc_u32 s1, s53, 0
	v_writelane_b32 v252, s0, 49
	s_mov_b32 s96, 0x18000
	s_mov_b32 s97, 0x8000
	v_writelane_b32 v252, s1, 50
	s_add_u32 s0, s52, 0x1200
	s_addc_u32 s1, s53, 0
	v_writelane_b32 v252, s0, 51
	s_mov_b32 s72, 0xa000
	s_mov_b32 s73, 0x1e000
	v_writelane_b32 v252, s1, 52
	s_add_u32 s0, s52, 0x1300
	s_addc_u32 s1, s53, 0
	v_writelane_b32 v252, s0, 53
	s_cmp_eq_u32 s4, 15
	s_mov_b32 s74, 0xc000
	v_writelane_b32 v252, s1, 54
	s_cselect_b64 s[0:1], -1, 0
	v_writelane_b32 v252, s0, 55
	s_cmp_eq_u32 s4, 14
	s_mov_b32 s75, 0xe000
	v_writelane_b32 v252, s1, 56
	s_cselect_b64 s[0:1], -1, 0
	v_writelane_b32 v252, s0, 57
	s_cmp_eq_u32 s4, 13
	s_mov_b32 s77, 0x42000
	v_writelane_b32 v252, s1, 58
	s_cselect_b64 s[0:1], -1, 0
	v_writelane_b32 v252, s0, 59
	s_cmp_eq_u32 s4, 12
	s_mov_b32 s76, 0x5a000
	v_writelane_b32 v252, s1, 60
	s_cselect_b64 s[0:1], -1, 0
	v_writelane_b32 v252, s0, 61
	s_cmp_eq_u32 s4, 11
	s_mov_b32 s23, 0x84000
	v_writelane_b32 v252, s1, 62
	s_cselect_b64 s[0:1], -1, 0
	v_writelane_b32 v252, s0, 63
	s_cmp_eq_u32 s4, 10
	s_mov_b32 s24, 0x9c000
	v_writelane_b32 v253, s1, 0
	s_cselect_b64 s[0:1], -1, 0
	v_writelane_b32 v253, s0, 1
	s_cmp_eq_u32 s4, 9
	s_mov_b32 s39, 0xe7000
	v_writelane_b32 v253, s1, 2
	s_cselect_b64 s[0:1], -1, 0
	v_writelane_b32 v253, s0, 3
	s_cmp_eq_u32 s4, 8
	s_mov_b32 s29, 0x108000
	v_writelane_b32 v253, s1, 4
	s_cselect_b64 s[0:1], -1, 0
	v_writelane_b32 v253, s0, 5
	s_cmp_eq_u32 s4, 7
	s_mov_b32 s30, 0x129000
	v_writelane_b32 v253, s1, 6
	s_cselect_b64 s[0:1], -1, 0
	v_writelane_b32 v253, s0, 7
	s_cmp_eq_u32 s4, 6
	s_mov_b32 s31, 0x14a000
	v_writelane_b32 v253, s1, 8
	s_cselect_b64 s[0:1], -1, 0
	v_writelane_b32 v253, s0, 9
	s_cmp_eq_u32 s4, 5
	s_movk_i32 s46, 0xffd0
	v_writelane_b32 v253, s1, 10
	s_cselect_b64 s[0:1], -1, 0
	v_writelane_b32 v253, s0, 11
	s_cmp_eq_u32 s4, 4
	s_movk_i32 s50, 0xffc0
	v_writelane_b32 v253, s1, 12
	s_cselect_b64 s[0:1], -1, 0
	v_writelane_b32 v253, s0, 13
	s_cmp_eq_u32 s4, 3
	s_mov_b32 s51, 0x41000000
	v_writelane_b32 v253, s1, 14
	s_cselect_b64 s[0:1], -1, 0
	v_writelane_b32 v253, s0, 15
	s_cmp_eq_u32 s4, 2
	s_mov_b32 s33, 0x24000
	v_writelane_b32 v253, s1, 16
	s_cselect_b64 s[0:1], -1, 0
	v_writelane_b32 v253, s0, 17
	s_cmp_eq_u32 s4, 1
	s_mov_b32 s34, 0x2a000
	v_writelane_b32 v253, s1, 18
	s_cselect_b64 s[0:1], -1, 0
	v_writelane_b32 v253, s0, 19
	s_cmp_eq_u32 s4, 0
	s_mov_b64 s[48:49], 0xca00100
	v_writelane_b32 v253, s1, 20
	s_cselect_b64 s[0:1], -1, 0
	v_writelane_b32 v253, s0, 21
	s_nop 1
	v_writelane_b32 v253, s1, 22
	s_lshl_b32 s0, s4, 8
	s_add_u32 s0, s52, s0
	s_addc_u32 s1, s53, 0
	s_add_u32 s4, s0, 0x1400
	s_addc_u32 s5, s1, 0
	v_writelane_b32 v253, s4, 23
	s_add_u32 s0, s0, 0x2400
	s_addc_u32 s1, s1, 0
	v_writelane_b32 v253, s5, 24
	v_writelane_b32 v253, s0, 25
	s_nop 1
	v_writelane_b32 v253, s1, 26
	s_add_u32 s0, s52, 0x3400
	s_addc_u32 s1, s53, 0
	v_writelane_b32 v253, s0, 27
	s_nop 1
	v_writelane_b32 v253, s1, 28
	s_add_u32 s0, s52, 0x3500
	s_addc_u32 s1, s53, 0
	v_writelane_b32 v253, s0, 29
	s_cmp_lt_i32 s3, 0
	s_nop 0
	v_writelane_b32 v253, s1, 30
	s_movk_i32 s0, 0x64
	s_cselect_b32 s0, s0, 0x63
	s_mul_i32 s0, s3, s0
	s_add_i32 s0, s0, s2
	v_writelane_b32 v253, s3, 31
	s_mul_hi_i32 s1, s0, 0x2aaaaaab
	v_writelane_b32 v253, s2, 32
	s_lshr_b32 s2, s1, 31
	s_ashr_i32 s1, s1, 4
	s_add_i32 s1, s1, s2
	s_mul_i32 s2, s1, 0x60
	s_lshl_b32 s3, s1, 3
	s_sub_i32 s2, s0, s2
	s_sub_i32 s0, 0x42, s3
	s_min_u32 s4, s0, 8
	v_cvt_f32_ubyte0_e32 v2, s4
	v_cvt_f32_i32_e32 v1, s2
	v_rcp_iflag_f32_e32 v3, v2
	s_ashr_i32 s0, s2, 30
	s_or_b32 s5, s0, 1
	s_abs_i32 s0, s78
	v_mul_f32_e32 v3, v1, v3
	v_trunc_f32_e32 v3, v3
	v_fma_f32 v1, -v3, v2, v1
	v_writelane_b32 v253, s0, 33
	v_cmp_ge_f32_e64 s[0:1], |v1|, v2
	v_lshrrev_b32_e32 v1, 20, v0
	v_lshrrev_b32_e32 v0, 10, v0
	v_or_b32_e32 v0, v0, v1
	v_cvt_i32_f32_e32 v1, v3
	s_and_b64 s[0:1], s[0:1], exec
	s_movk_i32 s0, 0x3ff
	v_and_or_b32 v0, v0, s0, v191
	s_cselect_b32 s0, s5, 0
	v_readfirstlane_b32 s1, v1
	s_add_i32 s0, s1, s0
	s_mul_i32 s1, s0, s4
	s_sub_i32 s1, s2, s1
	s_sext_i32_i8 s1, s1
	s_add_i32 s1, s3, s1
	v_writelane_b32 v253, s1, 34
	s_lshl_b32 s1, s78, 9
	s_lshl_b32 s2, s8, 9
	s_sub_i32 s1, s1, s2
	v_writelane_b32 v253, s1, 35
	s_lshl_b32 s1, s80, 10
	s_lshl_b32 s2, s8, 10
	s_sub_i32 s1, s1, s2
	v_writelane_b32 v253, s1, 36
	s_lshl_b32 s1, s78, 4
	s_lshl_b32 s2, s8, 4
	s_sub_i32 s1, s1, s2
	v_writelane_b32 v253, s1, 37
	s_lshl_b32 s1, s80, 4
	s_sub_i32 s1, s1, s2
	v_writelane_b32 v253, s1, 38
	s_lshl_b32 s1, s80, 6
	s_lshl_b32 s2, s8, 6
	s_sub_i32 s86, s1, s2
	v_readlane_b32 s2, v252, 0
	v_readlane_b32 s3, v252, 1
	s_load_dword s1, s[2:3], 0xa8
	v_writelane_b32 v253, s8, 39
	s_sext_i32_i8 s0, s0
	s_ashr_i32 s83, s82, 31
	v_mov_b32_e32 v1, 0
	s_waitcnt lgkmcnt(0)
	s_mul_i32 s1, s1, s81
	s_mul_i32 s1, s1, s80
	v_writelane_b32 v253, s1, 40
	v_writelane_b32 v253, s0, 41
	v_writelane_b32 v253, s6, 42
	s_add_i32 s0, s7, s6
	v_writelane_b32 v253, s7, 43
	s_addk_i32 s0, 0xc000
	v_writelane_b32 v253, s0, 44
	s_add_i32 s0, 0, 0x20800
	v_writelane_b32 v253, s0, 45
	s_add_i32 s0, 0, 0x20400
	v_writelane_b32 v253, s0, 46
	s_add_i32 s0, 0, 0x20000
	v_writelane_b32 v253, s0, 47
	s_add_i32 s0, 0, 0x24004
	v_writelane_b32 v253, s0, 48
	s_mov_b32 s1, 0
	v_writelane_b32 v253, s0, 49
	s_movk_i32 s81, 0x4000
	v_mbcnt_lo_u32_b32 v2, -1, 0
	v_writelane_b32 v253, s1, 50
	v_cmp_eq_u32_e64 s[0:1], 0, v0
	v_mbcnt_hi_u32_b32 v214, -1, v2
	s_nop 0
	v_writelane_b32 v253, s0, 51
	s_nop 1
	v_writelane_b32 v253, s1, 52
	s_lshl_b64 s[0:1], s[82:83], 12
	v_writelane_b32 v253, s0, 53
	s_nop 1
	v_writelane_b32 v253, s1, 54
	v_writelane_b32 v253, s78, 55
	v_writelane_b32 v253, s80, 56
	s_nop 1
	v_writelane_b32 v253, s81, 57
	v_writelane_b32 v253, s82, 58
	s_nop 1
	v_writelane_b32 v253, s83, 59
	v_writelane_b32 v253, s79, 60
	v_writelane_b32 v253, s84, 61
	v_writelane_b32 v253, s85, 62
	v_writelane_b32 v253, s86, 63
	s_branch .LBB0_10

.LBB0_431:
	s_ashr_i32 s21, s20, 31
	s_lshl_b64 s[0:1], s[20:21], 9
	v_readlane_b32 s4, v254, 46
	v_readlane_b32 s5, v254, 47
	s_add_u32 s0, s4, s0
	s_addc_u32 s1, s5, s1
	s_lshl_b32 s3, s33, 5
	s_and_b32 s3, s3, 0xc0
	s_lshl_b32 s4, s3, 1
	s_add_u32 s0, s0, s4
	s_addc_u32 s1, s1, 0
	v_ashrrev_i32_e32 v35, 31, v34
	s_ashr_i32 s37, s36, 31
	v_lshl_add_u64 v[30:31], v[34:35], 1, s[0:1]
	s_lshl_b64 s[0:1], s[36:37], 9
	v_lshl_add_u64 v[2:3], v[30:31], 0, s[0:1]
	global_load_ushort v100, v[30:31], off
	s_lshl_b32 s0, s36, 1
	global_load_ushort v101, v[2:3], off
	s_ashr_i32 s1, s0, 31
	s_mul_i32 s90, s36, 15
	v_writelane_b32 v255, s0, 0
	s_ashr_i32 s91, s90, 31
	s_mul_i32 s12, s36, 21
	v_writelane_b32 v255, s1, 1
	s_lshl_b64 s[0:1], s[0:1], 9
	v_lshl_add_u64 v[4:5], v[30:31], 0, s[0:1]
	s_mul_i32 s0, s36, 3
	s_ashr_i32 s1, s0, 31
	v_writelane_b32 v255, s0, 2
	s_ashr_i32 s13, s12, 31
	s_mul_i32 s34, s36, 22
	v_writelane_b32 v255, s1, 3
	s_lshl_b64 s[0:1], s[0:1], 9
	s_ashr_i32 s35, s34, 31
	s_mul_i32 s28, s36, 23
	s_ashr_i32 s29, s28, 31
	s_mul_i32 s14, s36, 24
	s_ashr_i32 s15, s14, 31
	s_mul_i32 s96, s36, 25
	s_ashr_i32 s97, s96, 31
	s_mul_i32 s52, s36, 26
	s_ashr_i32 s53, s52, 31
	s_mul_i32 s16, s36, 27
	s_ashr_i32 s17, s16, 31
	s_mul_i32 s4, s36, 28
	s_ashr_i32 s5, s4, 31
	s_mul_i32 s92, s36, 29
	s_ashr_i32 s93, s92, 31
	s_mul_i32 s38, s36, 30
	s_ashr_i32 s39, s38, 31
	s_mul_i32 s18, s36, 31
	s_ashr_i32 s19, s18, 31
	s_lshl_b32 s22, s36, 5
	s_ashr_i32 s23, s22, 31
	s_mul_i32 s24, s36, 33
	s_ashr_i32 s25, s24, 31
	s_mul_i32 s30, s36, 34
	s_ashr_i32 s31, s30, 31
	s_mul_i32 s6, s36, 35
	s_ashr_i32 s7, s6, 31
	s_mul_i32 s72, s36, 36
	s_ashr_i32 s73, s72, 31
	s_mul_i32 s74, s36, 37
	s_ashr_i32 s75, s74, 31
	s_mul_i32 s26, s36, 38
	s_ashr_i32 s27, s26, 31
	s_mul_i32 s84, s36, 39
	s_ashr_i32 s85, s84, 31
	s_mul_i32 s8, s36, 40
	s_ashr_i32 s9, s8, 31
	s_mul_i32 s94, s36, 41
	s_ashr_i32 s95, s94, 31
	s_mul_i32 s82, s36, 42
	s_ashr_i32 s83, s82, 31
	s_mul_i32 s86, s36, 43
	s_ashr_i32 s87, s86, 31
	s_mul_i32 s78, s36, 44
	s_ashr_i32 s79, s78, 31
	s_mul_i32 s80, s36, 45
	s_ashr_i32 s81, s80, 31
	s_mul_i32 s42, s36, 47
	s_ashr_i32 s43, s42, 31
	s_lshl_b64 s[20:21], s[20:21], 10
	v_and_b32_e32 v46, 31, v34
	v_bfe_u32 v79, v34, 4, 1
	v_and_b32_e32 v48, 15, v34
	v_or_b32_e32 v67, 32, v46
	v_lshrrev_b32_e32 v80, 4, v67
	global_load_ushort v102, v[4:5], off
	v_lshl_add_u64 v[4:5], v[30:31], 0, s[0:1]
	global_load_ushort v103, v[4:5], off
	s_lshl_b32 s0, s36, 2
	s_ashr_i32 s1, s0, 31
	v_writelane_b32 v255, s0, 4
	v_writelane_b32 v255, s1, 5
	s_lshl_b64 s[0:1], s[0:1], 9
	v_lshl_add_u64 v[4:5], v[30:31], 0, s[0:1]
	s_mul_i32 s0, s36, 5
	s_ashr_i32 s1, s0, 31
	v_writelane_b32 v255, s0, 6
	global_load_ushort v104, v[4:5], off
	s_nop 0
	v_writelane_b32 v255, s1, 7
	s_lshl_b64 s[0:1], s[0:1], 9
	v_lshl_add_u64 v[4:5], v[30:31], 0, s[0:1]
	global_load_ushort v105, v[4:5], off
	s_mul_i32 s0, s36, 6
	s_ashr_i32 s1, s0, 31
	v_writelane_b32 v255, s0, 8
	v_writelane_b32 v255, s1, 9
	s_lshl_b64 s[0:1], s[0:1], 9
	v_lshl_add_u64 v[6:7], v[30:31], 0, s[0:1]
	s_mul_i32 s0, s36, 7
	s_ashr_i32 s1, s0, 31
	v_writelane_b32 v255, s0, 10
	global_load_ushort v106, v[6:7], off
	s_nop 0
	v_writelane_b32 v255, s1, 11
	s_lshl_b64 s[0:1], s[0:1], 9
	v_lshl_add_u64 v[6:7], v[30:31], 0, s[0:1]
	global_load_ushort v107, v[6:7], off
	s_lshl_b32 s0, s36, 3
	s_ashr_i32 s1, s0, 31
	v_writelane_b32 v255, s0, 12
	v_writelane_b32 v255, s1, 13
	s_lshl_b64 s[0:1], s[0:1], 9
	v_lshl_add_u64 v[6:7], v[30:31], 0, s[0:1]
	s_mul_i32 s0, s36, 9
	s_ashr_i32 s1, s0, 31
	v_writelane_b32 v255, s0, 14
	global_load_ushort v108, v[6:7], off
	s_nop 0
	v_writelane_b32 v255, s1, 15
	s_lshl_b64 s[0:1], s[0:1], 9
	v_lshl_add_u64 v[6:7], v[30:31], 0, s[0:1]
	global_load_ushort v109, v[6:7], off
	s_mul_i32 s0, s36, 10
	s_ashr_i32 s1, s0, 31
	v_writelane_b32 v255, s0, 16
	v_writelane_b32 v255, s1, 17
	s_lshl_b64 s[0:1], s[0:1], 9
	v_lshl_add_u64 v[8:9], v[30:31], 0, s[0:1]
	s_mul_i32 s0, s36, 11
	s_ashr_i32 s1, s0, 31
	v_writelane_b32 v255, s0, 18
	global_load_ushort v110, v[8:9], off
	s_nop 0
	v_writelane_b32 v255, s1, 19
	s_lshl_b64 s[0:1], s[0:1], 9
	v_lshl_add_u64 v[8:9], v[30:31], 0, s[0:1]
	global_load_ushort v111, v[8:9], off
	s_mul_i32 s0, s36, 12
	s_ashr_i32 s1, s0, 31
	v_writelane_b32 v255, s0, 20
	v_writelane_b32 v255, s1, 21
	s_lshl_b64 s[0:1], s[0:1], 9
	v_lshl_add_u64 v[8:9], v[30:31], 0, s[0:1]
	s_mul_i32 s0, s36, 13
	s_ashr_i32 s1, s0, 31
	v_writelane_b32 v255, s0, 22
	global_load_ushort v112, v[8:9], off
	s_nop 0
	v_writelane_b32 v255, s1, 23
	s_lshl_b64 s[0:1], s[0:1], 9
	v_lshl_add_u64 v[8:9], v[30:31], 0, s[0:1]
	global_load_ushort v113, v[8:9], off
	s_mul_i32 s0, s36, 14
	s_ashr_i32 s1, s0, 31
	v_writelane_b32 v255, s0, 24
	v_writelane_b32 v255, s1, 25
	s_lshl_b64 s[0:1], s[0:1], 9
	v_lshl_add_u64 v[10:11], v[30:31], 0, s[0:1]
	s_lshl_b64 s[0:1], s[90:91], 9
	global_load_ushort v114, v[10:11], off
	v_lshl_add_u64 v[10:11], v[30:31], 0, s[0:1]
	global_load_ushort v115, v[10:11], off
	s_lshl_b32 s0, s36, 4
	s_ashr_i32 s1, s0, 31
	v_writelane_b32 v255, s0, 26
	v_writelane_b32 v255, s1, 27
	s_lshl_b64 s[0:1], s[0:1], 9
	v_lshl_add_u64 v[10:11], v[30:31], 0, s[0:1]
	s_mul_i32 s0, s36, 17
	s_ashr_i32 s1, s0, 31
	v_writelane_b32 v255, s0, 28
	global_load_ushort v116, v[10:11], off
	s_nop 0
	v_writelane_b32 v255, s1, 29
	s_lshl_b64 s[0:1], s[0:1], 9
	v_lshl_add_u64 v[10:11], v[30:31], 0, s[0:1]
	global_load_ushort v117, v[10:11], off
	s_mul_i32 s0, s36, 18
	s_ashr_i32 s1, s0, 31
	v_writelane_b32 v255, s0, 30
	v_writelane_b32 v255, s1, 31
	s_lshl_b64 s[0:1], s[0:1], 9
	v_lshl_add_u64 v[12:13], v[30:31], 0, s[0:1]
	s_mul_i32 s0, s36, 19
	s_ashr_i32 s1, s0, 31
	v_writelane_b32 v255, s0, 32
	global_load_ushort v118, v[12:13], off
	s_nop 0
	v_writelane_b32 v255, s1, 33
	s_lshl_b64 s[0:1], s[0:1], 9
	v_lshl_add_u64 v[12:13], v[30:31], 0, s[0:1]
	global_load_ushort v119, v[12:13], off
	s_mul_i32 s0, s36, 20
	s_ashr_i32 s1, s0, 31
	v_writelane_b32 v255, s0, 34
	v_writelane_b32 v255, s1, 35
	s_lshl_b64 s[0:1], s[0:1], 9
	v_lshl_add_u64 v[12:13], v[30:31], 0, s[0:1]
	s_lshl_b64 s[0:1], s[12:13], 9
	global_load_ushort v120, v[12:13], off
	v_lshl_add_u64 v[12:13], v[30:31], 0, s[0:1]
	global_load_ushort v121, v[12:13], off
	s_lshl_b64 s[0:1], s[34:35], 9
	v_lshl_add_u64 v[14:15], v[30:31], 0, s[0:1]
	s_lshl_b64 s[0:1], s[28:29], 9
	global_load_ushort v122, v[14:15], off
	v_lshl_add_u64 v[14:15], v[30:31], 0, s[0:1]
	global_load_ushort v123, v[14:15], off
	s_lshl_b64 s[0:1], s[14:15], 9
	v_lshl_add_u64 v[14:15], v[30:31], 0, s[0:1]
	s_lshl_b64 s[0:1], s[96:97], 9
	global_load_ushort v124, v[14:15], off
	v_lshl_add_u64 v[14:15], v[30:31], 0, s[0:1]
	global_load_ushort v125, v[14:15], off
	s_lshl_b64 s[0:1], s[52:53], 9
	v_lshl_add_u64 v[16:17], v[30:31], 0, s[0:1]
	s_lshl_b64 s[0:1], s[16:17], 9
	global_load_ushort v126, v[16:17], off
	v_lshl_add_u64 v[16:17], v[30:31], 0, s[0:1]
	global_load_ushort v127, v[16:17], off
	s_lshl_b64 s[0:1], s[4:5], 9
	v_lshl_add_u64 v[16:17], v[30:31], 0, s[0:1]
	s_lshl_b64 s[0:1], s[92:93], 9
	global_load_ushort v128, v[16:17], off
	v_lshl_add_u64 v[16:17], v[30:31], 0, s[0:1]
	global_load_ushort v129, v[16:17], off
	s_lshl_b64 s[0:1], s[38:39], 9
	v_lshl_add_u64 v[18:19], v[30:31], 0, s[0:1]
	s_lshl_b64 s[0:1], s[18:19], 9
	global_load_ushort v130, v[18:19], off
	v_lshl_add_u64 v[18:19], v[30:31], 0, s[0:1]
	global_load_ushort v131, v[18:19], off
	s_lshl_b64 s[0:1], s[22:23], 9
	v_lshl_add_u64 v[18:19], v[30:31], 0, s[0:1]
	s_lshl_b64 s[0:1], s[24:25], 9
	global_load_ushort v132, v[18:19], off
	v_lshl_add_u64 v[18:19], v[30:31], 0, s[0:1]
	global_load_ushort v133, v[18:19], off
	s_lshl_b64 s[0:1], s[30:31], 9
	v_lshl_add_u64 v[20:21], v[30:31], 0, s[0:1]
	s_lshl_b64 s[0:1], s[6:7], 9
	global_load_ushort v134, v[20:21], off
	v_lshl_add_u64 v[20:21], v[30:31], 0, s[0:1]
	global_load_ushort v135, v[20:21], off
	s_lshl_b64 s[0:1], s[72:73], 9
	v_lshl_add_u64 v[20:21], v[30:31], 0, s[0:1]
	s_lshl_b64 s[0:1], s[74:75], 9
	global_load_ushort v136, v[20:21], off
	v_lshl_add_u64 v[20:21], v[30:31], 0, s[0:1]
	global_load_ushort v137, v[20:21], off
	s_lshl_b64 s[0:1], s[26:27], 9
	v_lshl_add_u64 v[22:23], v[30:31], 0, s[0:1]
	s_lshl_b64 s[0:1], s[84:85], 9
	global_load_ushort v138, v[22:23], off
	v_lshl_add_u64 v[22:23], v[30:31], 0, s[0:1]
	global_load_ushort v139, v[22:23], off
	s_lshl_b64 s[0:1], s[8:9], 9
	v_lshl_add_u64 v[22:23], v[30:31], 0, s[0:1]
	s_lshl_b64 s[0:1], s[94:95], 9
	global_load_ushort v140, v[22:23], off
	v_lshl_add_u64 v[22:23], v[30:31], 0, s[0:1]
	global_load_ushort v141, v[22:23], off
	s_lshl_b64 s[0:1], s[82:83], 9
	v_lshl_add_u64 v[24:25], v[30:31], 0, s[0:1]
	s_lshl_b64 s[0:1], s[86:87], 9
	global_load_ushort v142, v[24:25], off
	v_lshl_add_u64 v[24:25], v[30:31], 0, s[0:1]
	global_load_ushort v143, v[24:25], off
	s_lshl_b64 s[0:1], s[78:79], 9
	v_lshl_add_u64 v[24:25], v[30:31], 0, s[0:1]
	s_lshl_b64 s[0:1], s[80:81], 9
	global_load_ushort v144, v[24:25], off
	v_lshl_add_u64 v[24:25], v[30:31], 0, s[0:1]
	global_load_ushort v145, v[24:25], off
	s_mul_i32 s0, s36, 46
	s_ashr_i32 s1, s0, 31
	s_lshl_b64 s[10:11], s[0:1], 9
	v_lshl_add_u64 v[26:27], v[30:31], 0, s[10:11]
	s_lshl_b64 s[10:11], s[42:43], 9
	global_load_ushort v146, v[26:27], off
	v_lshl_add_u64 v[26:27], v[30:31], 0, s[10:11]
	global_load_ushort v147, v[26:27], off
	s_mul_i32 s10, s36, 48
	s_ashr_i32 s11, s10, 31
	s_lshl_b64 s[40:41], s[10:11], 9
	v_lshl_add_u64 v[26:27], v[30:31], 0, s[40:41]
	s_mul_i32 s40, s36, 49
	s_ashr_i32 s41, s40, 31
	s_lshl_b64 s[44:45], s[40:41], 9
	global_load_ushort v148, v[26:27], off
	v_lshl_add_u64 v[26:27], v[30:31], 0, s[44:45]
	global_load_ushort v149, v[26:27], off
	s_mul_i32 s44, s36, 50
	s_ashr_i32 s45, s44, 31
	s_lshl_b64 s[46:47], s[44:45], 9
	v_lshl_add_u64 v[28:29], v[30:31], 0, s[46:47]
	s_mul_i32 s46, s36, 51
	s_ashr_i32 s47, s46, 31
	s_lshl_b64 s[48:49], s[46:47], 9
	global_load_ushort v150, v[28:29], off
	v_lshl_add_u64 v[28:29], v[30:31], 0, s[48:49]
	global_load_ushort v151, v[28:29], off
	s_mul_i32 s48, s36, 52
	s_ashr_i32 s49, s48, 31
	s_lshl_b64 s[50:51], s[48:49], 9
	v_lshl_add_u64 v[28:29], v[30:31], 0, s[50:51]
	s_mul_i32 s50, s36, 53
	s_ashr_i32 s51, s50, 31
	s_lshl_b64 s[54:55], s[50:51], 9
	global_load_ushort v152, v[28:29], off
	v_lshl_add_u64 v[28:29], v[30:31], 0, s[54:55]
	global_load_ushort v153, v[28:29], off
	s_mul_i32 s54, s36, 54
	s_ashr_i32 s55, s54, 31
	s_lshl_b64 s[56:57], s[54:55], 9
	v_lshl_add_u64 v[32:33], v[30:31], 0, s[56:57]
	s_mul_i32 s56, s36, 55
	s_ashr_i32 s57, s56, 31
	s_lshl_b64 s[58:59], s[56:57], 9
	global_load_ushort v154, v[32:33], off
	v_lshl_add_u64 v[32:33], v[30:31], 0, s[58:59]
	global_load_ushort v155, v[32:33], off
	s_mul_i32 s58, s36, 56
	s_ashr_i32 s59, s58, 31
	s_lshl_b64 s[60:61], s[58:59], 9
	v_lshl_add_u64 v[32:33], v[30:31], 0, s[60:61]
	s_mul_i32 s60, s36, 57
	s_ashr_i32 s61, s60, 31
	s_lshl_b64 s[62:63], s[60:61], 9
	global_load_ushort v156, v[32:33], off
	v_lshl_add_u64 v[32:33], v[30:31], 0, s[62:63]
	global_load_ushort v157, v[32:33], off
	s_mul_i32 s62, s36, 58
	s_ashr_i32 s63, s62, 31
	s_lshl_b64 s[64:65], s[62:63], 9
	v_lshl_add_u64 v[32:33], v[30:31], 0, s[64:65]
	s_mul_i32 s64, s36, 59
	s_ashr_i32 s65, s64, 31
	s_lshl_b64 s[66:67], s[64:65], 9
	global_load_ushort v158, v[32:33], off
	v_lshl_add_u64 v[32:33], v[30:31], 0, s[66:67]
	global_load_ushort v159, v[32:33], off
	s_mul_i32 s66, s36, 60
	s_ashr_i32 s67, s66, 31
	s_lshl_b64 s[68:69], s[66:67], 9
	v_lshl_add_u64 v[32:33], v[30:31], 0, s[68:69]
	s_mul_i32 s68, s36, 61
	s_ashr_i32 s69, s68, 31
	s_lshl_b64 s[70:71], s[68:69], 9
	global_load_ushort v160, v[32:33], off
	v_lshl_add_u64 v[32:33], v[30:31], 0, s[70:71]
	global_load_ushort v161, v[32:33], off
	s_mul_i32 s70, s36, 62
	s_ashr_i32 s71, s70, 31
	s_lshl_b64 s[76:77], s[70:71], 9
	v_lshl_add_u64 v[32:33], v[30:31], 0, s[76:77]
	s_mul_i32 s76, s36, 63
	s_ashr_i32 s77, s76, 31
	s_lshl_b64 vcc, s[76:77], 9
	v_lshl_add_u64 v[30:31], v[30:31], 0, vcc
	global_load_ushort v162, v[32:33], off
	s_movk_i32 vcc_lo, 0x90
	global_load_ushort v163, v[30:31], off
	s_add_u32 s20, s88, s20
	s_addc_u32 s21, s89, s21
	s_lshl_b32 s3, s3, 2
	s_add_u32 s20, s20, s3
	s_addc_u32 s21, s21, 0
	s_lshl_b64 s[6:7], s[6:7], 10
	s_lshl_b64 s[0:1], s[0:1], 10
	s_ashr_i32 s3, s2, 31
	s_waitcnt vmcnt(0)
	v_lshl_or_b32 v2, v101, 16, v100
	v_lshl_or_b32 v3, v103, 16, v102
	v_lshl_or_b32 v4, v105, 16, v104
	v_lshl_or_b32 v5, v107, 16, v106
	v_lshl_or_b32 v6, v109, 16, v108
	v_lshl_or_b32 v7, v111, 16, v110
	v_lshl_or_b32 v8, v113, 16, v112
	v_lshl_or_b32 v9, v115, 16, v114
	v_lshl_or_b32 v10, v117, 16, v116
	v_lshl_or_b32 v11, v119, 16, v118
	v_lshl_or_b32 v12, v121, 16, v120
	v_lshl_or_b32 v13, v123, 16, v122
	v_lshl_or_b32 v14, v125, 16, v124
	v_lshl_or_b32 v15, v127, 16, v126
	v_lshl_or_b32 v16, v129, 16, v128
	v_lshl_or_b32 v17, v131, 16, v130
	v_lshl_or_b32 v18, v133, 16, v132
	v_lshl_or_b32 v19, v135, 16, v134
	v_lshl_or_b32 v20, v137, 16, v136
	v_lshl_or_b32 v21, v139, 16, v138
	v_lshl_or_b32 v22, v141, 16, v140
	v_lshl_or_b32 v23, v143, 16, v142
	v_lshl_or_b32 v24, v145, 16, v144
	v_lshl_or_b32 v25, v147, 16, v146
	v_lshl_or_b32 v26, v149, 16, v148
	v_lshl_or_b32 v27, v151, 16, v150
	v_lshl_or_b32 v28, v153, 16, v152
	v_lshl_or_b32 v29, v155, 16, v154
	v_lshl_or_b32 v36, v157, 16, v156
	v_lshl_or_b32 v37, v159, 16, v158
	v_lshl_or_b32 v38, v161, 16, v160
	v_lshl_or_b32 v39, v163, 16, v162
	v_mul_lo_u32 v0, v34, vcc_lo
	v_readlane_b32 vcc_lo, v254, 58
	s_nop 1
	v_add_u32_e32 v0, vcc_lo, v0
	ds_write_b128 v0, v[2:5] offset:9216
	ds_write_b128 v0, v[6:9] offset:9232
	ds_write_b128 v0, v[10:13] offset:9248
	ds_write_b128 v0, v[14:17] offset:9264
	ds_write_b128 v0, v[18:21] offset:9280
	ds_write_b128 v0, v[22:25] offset:9296
	ds_write_b128 v0, v[26:29] offset:9312
	ds_write_b128 v0, v[36:39] offset:9328
	v_lshlrev_b64 v[2:3], 2, v[34:35]
	v_lshl_add_u64 v[6:7], s[20:21], 0, v[2:3]
	s_lshl_b64 s[20:21], s[22:23], 10
	v_lshl_add_u64 v[4:5], v[6:7], 0, s[20:21]
	s_lshl_b64 s[20:21], s[24:25], 10
	v_lshl_add_u64 v[8:9], v[6:7], 0, s[20:21]
	s_lshl_b64 s[20:21], s[30:31], 10
	global_load_dword v4, v[4:5], off
	v_lshl_add_u64 v[10:11], v[6:7], 0, s[6:7]
	global_load_dword v5, v[8:9], off
	v_lshl_add_u64 v[8:9], v[6:7], 0, s[20:21]
	s_lshl_b64 s[6:7], s[72:73], 10
	global_load_dword v8, v[8:9], off
	s_mov_b32 s72, 0xa000
	global_load_dword v9, v[10:11], off
	v_lshl_add_u64 v[10:11], v[6:7], 0, s[6:7]
	s_lshl_b64 s[6:7], s[74:75], 10
	v_lshl_add_u64 v[12:13], v[6:7], 0, s[6:7]
	s_lshl_b64 s[6:7], s[26:27], 10
	global_load_dword v10, v[10:11], off
	s_mov_b32 s73, 0x1e000
	global_load_dword v11, v[12:13], off
	v_lshl_add_u64 v[12:13], v[6:7], 0, s[6:7]
	s_lshl_b64 s[6:7], s[84:85], 10
	v_lshl_add_u64 v[14:15], v[6:7], 0, s[6:7]
	s_lshl_b64 s[6:7], s[8:9], 10
	global_load_dword v12, v[12:13], off
	v_readlane_b32 s84, v253, 61
	global_load_dword v13, v[14:15], off
	v_lshl_add_u64 v[14:15], v[6:7], 0, s[6:7]
	s_lshl_b64 s[6:7], s[94:95], 10
	v_lshl_add_u64 v[16:17], v[6:7], 0, s[6:7]
	s_lshl_b64 s[6:7], s[82:83], 10
	global_load_dword v14, v[14:15], off
	v_readlane_b32 s82, v253, 58
	global_load_dword v15, v[16:17], off
	v_lshl_add_u64 v[16:17], v[6:7], 0, s[6:7]
	s_lshl_b64 s[6:7], s[86:87], 10
	v_lshl_add_u64 v[18:19], v[6:7], 0, s[6:7]
	s_lshl_b64 s[6:7], s[78:79], 10
	global_load_dword v16, v[16:17], off
	v_readlane_b32 s78, v253, 55
	global_load_dword v17, v[18:19], off
	v_lshl_add_u64 v[18:19], v[6:7], 0, s[6:7]
	s_lshl_b64 s[6:7], s[80:81], 10
	v_lshl_add_u64 v[20:21], v[6:7], 0, s[6:7]
	global_load_dword v18, v[18:19], off
	v_readlane_b32 s7, v254, 54
	global_load_dword v19, v[20:21], off
	v_lshl_add_u64 v[20:21], v[6:7], 0, s[0:1]
	s_lshl_b64 s[0:1], s[42:43], 10
	v_lshl_add_u64 v[22:23], v[6:7], 0, s[0:1]
	s_lshl_b64 s[0:1], s[10:11], 10
	global_load_dword v20, v[20:21], off
	v_readlane_b32 s80, v253, 56
	global_load_dword v21, v[22:23], off
	v_lshl_add_u64 v[22:23], v[6:7], 0, s[0:1]
	s_lshl_b64 s[0:1], s[40:41], 10
	v_lshl_add_u64 v[24:25], v[6:7], 0, s[0:1]
	s_lshl_b64 s[0:1], s[44:45], 10
	global_load_dword v22, v[22:23], off
	v_readlane_b32 s81, v253, 57
	global_load_dword v23, v[24:25], off
	v_lshl_add_u64 v[24:25], v[6:7], 0, s[0:1]
	s_lshl_b64 s[0:1], s[46:47], 10
	v_lshl_add_u64 v[26:27], v[6:7], 0, s[0:1]
	s_lshl_b64 s[0:1], s[48:49], 10
	global_load_dword v24, v[24:25], off
	v_readlane_b32 s42, v254, 31
	global_load_dword v25, v[26:27], off
	v_lshl_add_u64 v[26:27], v[6:7], 0, s[0:1]
	s_lshl_b64 s[0:1], s[50:51], 10
	v_lshl_add_u64 v[28:29], v[6:7], 0, s[0:1]
	s_lshl_b64 s[0:1], s[54:55], 10
	global_load_dword v26, v[26:27], off
	v_readlane_b32 s54, v254, 12
	global_load_dword v27, v[28:29], off
	v_lshl_add_u64 v[28:29], v[6:7], 0, s[0:1]
	s_lshl_b64 s[0:1], s[56:57], 10
	v_lshl_add_u64 v[30:31], v[6:7], 0, s[0:1]
	s_lshl_b64 s[0:1], s[58:59], 10
	global_load_dword v28, v[28:29], off
	v_readlane_b32 s83, v253, 59
	global_load_dword v29, v[30:31], off
	v_lshl_add_u64 v[30:31], v[6:7], 0, s[0:1]
	s_lshl_b64 s[0:1], s[60:61], 10
	v_lshl_add_u64 v[32:33], v[6:7], 0, s[0:1]
	s_lshl_b64 s[0:1], s[62:63], 10
	global_load_dword v30, v[30:31], off
	v_readlane_b32 s79, v253, 60
	global_load_dword v31, v[32:33], off
	v_lshl_add_u64 v[32:33], v[6:7], 0, s[0:1]
	s_lshl_b64 s[0:1], s[64:65], 10
	v_lshl_add_u64 v[36:37], v[6:7], 0, s[0:1]
	s_lshl_b64 s[0:1], s[66:67], 10
	global_load_dword v32, v[32:33], off
	v_readlane_b32 s85, v253, 62
	global_load_dword v33, v[36:37], off
	v_lshl_add_u64 v[36:37], v[6:7], 0, s[0:1]
	s_lshl_b64 s[0:1], s[68:69], 10
	v_lshl_add_u64 v[38:39], v[6:7], 0, s[0:1]
	s_lshl_b64 s[0:1], s[70:71], 10
	global_load_dword v36, v[36:37], off
	v_readlane_b32 s86, v253, 63
	global_load_dword v37, v[38:39], off
	v_lshl_add_u64 v[38:39], v[6:7], 0, s[0:1]
	s_lshl_b64 s[0:1], s[76:77], 10
	global_load_dword v35, v[38:39], off
	v_lshl_add_u64 v[38:39], v[6:7], 0, s[0:1]
	global_load_dword v38, v[38:39], off
	s_lshl_b64 s[0:1], s[36:37], 10
	v_readlane_b32 s36, v254, 56
	v_readlane_b32 s37, v254, 57
	s_movk_i32 s81, 0x4000
	s_movk_i32 s87, 0x3000
	s_mov_b32 s94, 0x10000
	s_movk_i32 s95, 0x6000
	s_mov_b32 s74, 0xc000
	s_mov_b32 s75, 0xe000
	s_mov_b32 s10, 0xca01000
	s_mov_b32 s11, 0xeb01000
	s_mov_b32 s77, 0x42000
	s_mov_b32 s20, 0x4a000
	s_mov_b32 s21, 0x52000
	s_mov_b32 s76, 0x5a000
	s_mov_b32 s24, 0x63000
	s_mov_b32 s31, 0xa5000
	s_movk_i32 s46, 0xffd0
	s_movk_i32 s50, 0xffc0
	s_mov_b32 s51, 0x41000000
	s_mov_b64 s[48:49], 0xca00100
	v_readlane_b32 s43, v254, 32
	v_readlane_b32 s55, v254, 13
	s_waitcnt vmcnt(2)
	v_pk_add_f32 v[40:41], v[36:37], 1.0 op_sel_hi:[1,0] neg_lo:[1,0] neg_hi:[1,0]
	s_waitcnt vmcnt(1)
	v_sub_f32_e32 v39, 1.0, v35
	s_waitcnt vmcnt(0)
	v_mul_f32_e32 v45, v38, v39
	v_mul_f32_e32 v39, v35, v38
	v_sub_f32_e32 v44, 1.0, v38
	v_mul_f32_e32 v38, v37, v39
	v_mul_f32_e32 v37, v36, v38
	v_mul_f32_e32 v36, v33, v37
	v_pk_mul_f32 v[40:41], v[40:41], v[38:39]
	v_pk_add_f32 v[38:39], v[32:33], 1.0 op_sel_hi:[1,0] neg_lo:[1,0] neg_hi:[1,0]
	v_mul_f32_e32 v33, v32, v36
	v_mul_f32_e32 v32, v31, v33
	v_pk_mul_f32 v[38:39], v[38:39], v[36:37]
	v_pk_add_f32 v[36:37], v[30:31], 1.0 op_sel_hi:[1,0] neg_lo:[1,0] neg_hi:[1,0]
	v_mul_f32_e32 v31, v30, v32
	v_mul_f32_e32 v30, v29, v31
	v_pk_mul_f32 v[36:37], v[36:37], v[32:33]
	v_pk_add_f32 v[32:33], v[28:29], 1.0 op_sel_hi:[1,0] neg_lo:[1,0] neg_hi:[1,0]
	v_mul_f32_e32 v29, v28, v30
	v_mul_f32_e32 v28, v27, v29
	v_pk_mul_f32 v[32:33], v[32:33], v[30:31]
	v_pk_add_f32 v[30:31], v[26:27], 1.0 op_sel_hi:[1,0] neg_lo:[1,0] neg_hi:[1,0]
	v_mul_f32_e32 v27, v26, v28
	v_mul_f32_e32 v26, v25, v27
	v_pk_mul_f32 v[30:31], v[30:31], v[28:29]
	v_pk_add_f32 v[28:29], v[24:25], 1.0 op_sel_hi:[1,0] neg_lo:[1,0] neg_hi:[1,0]
	v_mul_f32_e32 v25, v24, v26
	v_mul_f32_e32 v24, v23, v25
	v_pk_mul_f32 v[28:29], v[28:29], v[26:27]
	v_pk_add_f32 v[26:27], v[22:23], 1.0 op_sel_hi:[1,0] neg_lo:[1,0] neg_hi:[1,0]
	v_mul_f32_e32 v23, v22, v24
	v_mul_f32_e32 v22, v21, v23
	v_pk_mul_f32 v[26:27], v[26:27], v[24:25]
	v_pk_add_f32 v[24:25], v[20:21], 1.0 op_sel_hi:[1,0] neg_lo:[1,0] neg_hi:[1,0]
	v_mul_f32_e32 v21, v20, v22
	v_mul_f32_e32 v20, v19, v21
	v_pk_mul_f32 v[24:25], v[24:25], v[22:23]
	v_pk_add_f32 v[22:23], v[18:19], 1.0 op_sel_hi:[1,0] neg_lo:[1,0] neg_hi:[1,0]
	v_mul_f32_e32 v19, v18, v20
	v_mul_f32_e32 v18, v17, v19
	v_pk_mul_f32 v[22:23], v[22:23], v[20:21]
	v_pk_add_f32 v[20:21], v[16:17], 1.0 op_sel_hi:[1,0] neg_lo:[1,0] neg_hi:[1,0]
	v_mul_f32_e32 v17, v16, v18
	v_mul_f32_e32 v16, v15, v17
	v_pk_mul_f32 v[20:21], v[20:21], v[18:19]
	v_pk_add_f32 v[18:19], v[14:15], 1.0 op_sel_hi:[1,0] neg_lo:[1,0] neg_hi:[1,0]
	v_mul_f32_e32 v15, v14, v16
	v_mul_f32_e32 v14, v13, v15
	v_pk_mul_f32 v[18:19], v[18:19], v[16:17]
	v_pk_add_f32 v[16:17], v[12:13], 1.0 op_sel_hi:[1,0] neg_lo:[1,0] neg_hi:[1,0]
	v_mul_f32_e32 v13, v12, v14
	v_mul_f32_e32 v12, v11, v13
	v_pk_mul_f32 v[42:43], v[16:17], v[14:15]
	v_pk_add_f32 v[14:15], v[10:11], 1.0 op_sel_hi:[1,0] neg_lo:[1,0] neg_hi:[1,0]
	v_mul_f32_e32 v11, v10, v12
	v_mul_f32_e32 v10, v9, v11
	v_mul_f32_e32 v17, v8, v10
	v_pk_mul_f32 v[14:15], v[14:15], v[12:13]
	v_pk_add_f32 v[12:13], v[8:9], 1.0 op_sel_hi:[1,0] neg_lo:[1,0] neg_hi:[1,0]
	v_mul_f32_e32 v16, v5, v17
	v_pk_add_f32 v[8:9], v[4:5], 1.0 op_sel_hi:[1,0] neg_lo:[1,0] neg_hi:[1,0]
	v_pk_mul_f32 v[12:13], v[12:13], v[10:11]
	v_pk_mul_f32 v[8:9], v[8:9], v[16:17]
	v_cvt_pk_bf16_f32 v10, v14, v15
	v_cvt_pk_bf16_f32 v8, v8, v9
	v_cvt_pk_bf16_f32 v9, v12, v13
	v_cvt_pk_bf16_f32 v11, v42, v43
	ds_write_b128 v0, v[8:11] offset:64
	v_cvt_pk_bf16_f32 v8, v18, v19
	v_cvt_pk_bf16_f32 v9, v20, v21
	v_cvt_pk_bf16_f32 v10, v22, v23
	v_cvt_pk_bf16_f32 v11, v24, v25
	ds_write_b128 v0, v[8:11] offset:80
	v_cvt_pk_bf16_f32 v8, v26, v27
	v_cvt_pk_bf16_f32 v9, v28, v29
	v_cvt_pk_bf16_f32 v10, v30, v31
	v_cvt_pk_bf16_f32 v11, v32, v33
	ds_write_b128 v0, v[8:11] offset:96
	v_cvt_pk_bf16_f32 v8, v36, v37
	v_cvt_pk_bf16_f32 v9, v38, v39
	v_cvt_pk_bf16_f32 v10, v40, v41
	v_cvt_pk_bf16_f32 v11, v45, v44
	ds_write_b128 v0, v[8:11] offset:112
	v_lshl_add_u64 v[10:11], v[6:7], 0, s[0:1]
	v_readlane_b32 s0, v255, 0
	v_readlane_b32 s1, v255, 1
	s_lshl_b64 s[0:1], s[0:1], 10
	global_load_dword v8, v[6:7], off
	global_load_dword v9, v[10:11], off
	v_lshl_add_u64 v[10:11], v[6:7], 0, s[0:1]
	v_readlane_b32 s0, v255, 2
	v_readlane_b32 s1, v255, 3
	s_lshl_b64 s[0:1], s[0:1], 10
	global_load_dword v10, v[10:11], off
	v_lshl_add_u64 v[12:13], v[6:7], 0, s[0:1]
	v_readlane_b32 s0, v255, 4
	v_readlane_b32 s1, v255, 5
	s_lshl_b64 s[0:1], s[0:1], 10
	global_load_dword v11, v[12:13], off
	v_lshl_add_u64 v[12:13], v[6:7], 0, s[0:1]
	v_readlane_b32 s0, v255, 6
	v_readlane_b32 s1, v255, 7
	s_lshl_b64 s[0:1], s[0:1], 10
	global_load_dword v12, v[12:13], off
	v_lshl_add_u64 v[14:15], v[6:7], 0, s[0:1]
	v_readlane_b32 s0, v255, 8
	v_readlane_b32 s1, v255, 9
	s_lshl_b64 s[0:1], s[0:1], 10
	global_load_dword v13, v[14:15], off
	v_lshl_add_u64 v[14:15], v[6:7], 0, s[0:1]
	v_readlane_b32 s0, v255, 10
	v_readlane_b32 s1, v255, 11
	s_lshl_b64 s[0:1], s[0:1], 10
	global_load_dword v14, v[14:15], off
	v_lshl_add_u64 v[18:19], v[6:7], 0, s[0:1]
	v_readlane_b32 s0, v255, 12
	v_readlane_b32 s1, v255, 13
	s_lshl_b64 s[0:1], s[0:1], 10
	global_load_dword v15, v[18:19], off
	v_lshl_add_u64 v[18:19], v[6:7], 0, s[0:1]
	v_readlane_b32 s0, v255, 14
	v_readlane_b32 s1, v255, 15
	s_lshl_b64 s[0:1], s[0:1], 10
	global_load_dword v18, v[18:19], off
	v_lshl_add_u64 v[20:21], v[6:7], 0, s[0:1]
	v_readlane_b32 s0, v255, 16
	v_readlane_b32 s1, v255, 17
	s_lshl_b64 s[0:1], s[0:1], 10
	global_load_dword v19, v[20:21], off
	v_lshl_add_u64 v[20:21], v[6:7], 0, s[0:1]
	v_readlane_b32 s0, v255, 18
	v_readlane_b32 s1, v255, 19
	s_lshl_b64 s[0:1], s[0:1], 10
	global_load_dword v20, v[20:21], off
	v_lshl_add_u64 v[22:23], v[6:7], 0, s[0:1]
	v_readlane_b32 s0, v255, 20
	v_readlane_b32 s1, v255, 21
	s_lshl_b64 s[0:1], s[0:1], 10
	global_load_dword v21, v[22:23], off
	v_lshl_add_u64 v[22:23], v[6:7], 0, s[0:1]
	v_readlane_b32 s0, v255, 22
	v_readlane_b32 s1, v255, 23
	s_lshl_b64 s[0:1], s[0:1], 10
	global_load_dword v22, v[22:23], off
	v_lshl_add_u64 v[24:25], v[6:7], 0, s[0:1]
	v_readlane_b32 s0, v255, 24
	v_readlane_b32 s1, v255, 25
	s_lshl_b64 s[0:1], s[0:1], 10
	global_load_dword v23, v[24:25], off
	v_lshl_add_u64 v[24:25], v[6:7], 0, s[0:1]
	s_lshl_b64 s[0:1], s[90:91], 10
	v_lshl_add_u64 v[26:27], v[6:7], 0, s[0:1]
	v_readlane_b32 s0, v255, 26
	v_readlane_b32 s1, v255, 27
	s_lshl_b64 s[0:1], s[0:1], 10
	global_load_dword v24, v[24:25], off
	v_mul_f32_e32 v5, v4, v16
	global_load_dword v25, v[26:27], off
	v_lshl_add_u64 v[26:27], v[6:7], 0, s[0:1]
	v_readlane_b32 s0, v255, 28
	v_readlane_b32 s1, v255, 29
	s_lshl_b64 s[0:1], s[0:1], 10
	global_load_dword v26, v[26:27], off
	v_lshl_add_u64 v[28:29], v[6:7], 0, s[0:1]
	v_readlane_b32 s0, v255, 30
	v_readlane_b32 s1, v255, 31
	s_lshl_b64 s[0:1], s[0:1], 10
	global_load_dword v27, v[28:29], off
	v_lshl_add_u64 v[28:29], v[6:7], 0, s[0:1]
	v_readlane_b32 s0, v255, 32
	v_readlane_b32 s1, v255, 33
	s_lshl_b64 s[0:1], s[0:1], 10
	global_load_dword v28, v[28:29], off
	v_lshl_add_u64 v[30:31], v[6:7], 0, s[0:1]
	v_readlane_b32 s0, v255, 34
	v_readlane_b32 s1, v255, 35
	s_lshl_b64 s[0:1], s[0:1], 10
	global_load_dword v29, v[30:31], off
	v_lshl_add_u64 v[30:31], v[6:7], 0, s[0:1]
	s_lshl_b64 s[0:1], s[12:13], 10
	v_lshl_add_u64 v[32:33], v[6:7], 0, s[0:1]
	s_lshl_b64 s[0:1], s[34:35], 10
	global_load_dword v30, v[30:31], off
	s_movk_i32 s90, 0x1800
	global_load_dword v31, v[32:33], off
	v_lshl_add_u64 v[32:33], v[6:7], 0, s[0:1]
	s_lshl_b64 s[0:1], s[28:29], 10
	v_lshl_add_u64 v[36:37], v[6:7], 0, s[0:1]
	s_lshl_b64 s[0:1], s[14:15], 10
	global_load_dword v32, v[32:33], off
	s_movk_i32 s14, 0x90
	global_load_dword v33, v[36:37], off
	v_lshl_add_u64 v[36:37], v[6:7], 0, s[0:1]
	s_lshl_b64 s[0:1], s[96:97], 10
	v_lshl_add_u64 v[38:39], v[6:7], 0, s[0:1]
	s_lshl_b64 s[0:1], s[52:53], 10
	global_load_dword v36, v[36:37], off
	s_mov_b32 s91, 0x12000
	global_load_dword v37, v[38:39], off
	v_lshl_add_u64 v[38:39], v[6:7], 0, s[0:1]
	s_lshl_b64 s[0:1], s[16:17], 10
	v_lshl_add_u64 v[40:41], v[6:7], 0, s[0:1]
	s_lshl_b64 s[0:1], s[4:5], 10
	global_load_dword v38, v[38:39], off
	v_readlane_b32 s4, v254, 63
	global_load_dword v39, v[40:41], off
	v_lshl_add_u64 v[40:41], v[6:7], 0, s[0:1]
	s_lshl_b64 s[0:1], s[92:93], 10
	v_lshl_add_u64 v[42:43], v[6:7], 0, s[0:1]
	s_lshl_b64 s[0:1], s[38:39], 10
	global_load_dword v40, v[40:41], off
	s_movk_i32 s92, 0x5000
	global_load_dword v41, v[42:43], off
	v_lshl_add_u64 v[42:43], v[6:7], 0, s[0:1]
	s_lshl_b64 s[0:1], s[18:19], 10
	v_lshl_add_u64 v[6:7], v[6:7], 0, s[0:1]
	global_load_dword v42, v[42:43], off
	s_lshl_b64 s[0:1], s[2:3], 8
	global_load_dword v43, v[6:7], off
	v_readlane_b32 s3, v254, 59
	s_add_u32 s0, s3, s0
	v_readlane_b32 s3, v254, 60
	s_addc_u32 s1, s3, s1
	v_lshl_add_u64 v[2:3], s[0:1], 0, v[2:3]
	v_readlane_b32 s0, v254, 52
	s_ashr_i32 s3, s0, 31
	s_mul_hi_i32 s1, s33, 0x2100
	s_add_u32 s0, s4, s0
	s_addc_u32 s1, s1, s3
	s_lshl_b64 s[0:1], s[0:1], 8
	s_add_u32 s0, s36, s0
	s_addc_u32 s1, s37, s1
	s_movk_i32 s93, 0x2000
	s_mov_b32 s96, 0x18000
	s_mov_b32 s97, 0x8000
	s_movk_i32 s15, 0x1000
	s_mov_b32 s16, 0x21000
	s_mov_b32 s17, 0x29000
	s_mov_b32 s18, 0x31000
	s_mov_b32 s19, 0x39000
	s_mov_b32 s33, 0xad000
	s_mov_b32 s34, 0xb5000
	s_mov_b32 s35, 0xbd000
	s_mov_b32 s38, 0xc6000
	s_mov_b32 s39, 0xce000
	s_mov_b32 s52, 0xd6000
	s_mov_b32 s53, 0xde000
	s_waitcnt vmcnt(0)
	v_mul_f32_e32 v4, v5, v43
	v_pk_add_f32 v[6:7], v[42:43], 1.0 op_sel_hi:[1,0] neg_lo:[1,0] neg_hi:[1,0]
	s_nop 0
	v_pk_mul_f32 v[16:17], v[6:7], v[4:5]
	v_mul_f32_e32 v5, v42, v4
	v_mul_f32_e32 v4, v41, v5
	v_pk_add_f32 v[6:7], v[40:41], 1.0 op_sel_hi:[1,0] neg_lo:[1,0] neg_hi:[1,0]
	s_nop 0
	v_pk_mul_f32 v[42:43], v[6:7], v[4:5]
	v_mul_f32_e32 v5, v40, v4
	v_mul_f32_e32 v4, v39, v5
	v_pk_add_f32 v[6:7], v[38:39], 1.0 op_sel_hi:[1,0] neg_lo:[1,0] neg_hi:[1,0]
	s_nop 0
	v_pk_mul_f32 v[40:41], v[6:7], v[4:5]
	v_mul_f32_e32 v5, v38, v4
	v_mul_f32_e32 v4, v37, v5
	v_pk_add_f32 v[6:7], v[36:37], 1.0 op_sel_hi:[1,0] neg_lo:[1,0] neg_hi:[1,0]
	s_nop 0
	v_pk_mul_f32 v[38:39], v[6:7], v[4:5]
	v_mul_f32_e32 v5, v36, v4
	v_mul_f32_e32 v4, v33, v5
	v_pk_add_f32 v[6:7], v[32:33], 1.0 op_sel_hi:[1,0] neg_lo:[1,0] neg_hi:[1,0]
	s_nop 0
	v_pk_mul_f32 v[36:37], v[6:7], v[4:5]
	v_mul_f32_e32 v5, v32, v4
	v_mul_f32_e32 v4, v31, v5
	v_pk_add_f32 v[6:7], v[30:31], 1.0 op_sel_hi:[1,0] neg_lo:[1,0] neg_hi:[1,0]
	s_nop 0
	v_pk_mul_f32 v[32:33], v[6:7], v[4:5]
	v_mul_f32_e32 v5, v30, v4
	v_mul_f32_e32 v4, v29, v5
	v_pk_add_f32 v[6:7], v[28:29], 1.0 op_sel_hi:[1,0] neg_lo:[1,0] neg_hi:[1,0]
	s_nop 0
	v_pk_mul_f32 v[30:31], v[6:7], v[4:5]
	v_mul_f32_e32 v5, v28, v4
	v_mul_f32_e32 v4, v27, v5
	v_pk_add_f32 v[6:7], v[26:27], 1.0 op_sel_hi:[1,0] neg_lo:[1,0] neg_hi:[1,0]
	s_nop 0
	v_pk_mul_f32 v[28:29], v[6:7], v[4:5]
	v_mul_f32_e32 v5, v26, v4
	v_mul_f32_e32 v4, v25, v5
	v_pk_add_f32 v[6:7], v[24:25], 1.0 op_sel_hi:[1,0] neg_lo:[1,0] neg_hi:[1,0]
	s_nop 0
	v_pk_mul_f32 v[26:27], v[6:7], v[4:5]
	v_mul_f32_e32 v5, v24, v4
	v_mul_f32_e32 v4, v23, v5
	v_pk_add_f32 v[6:7], v[22:23], 1.0 op_sel_hi:[1,0] neg_lo:[1,0] neg_hi:[1,0]
	s_nop 0
	v_pk_mul_f32 v[24:25], v[6:7], v[4:5]
	v_mul_f32_e32 v5, v22, v4
	v_mul_f32_e32 v4, v21, v5
	v_pk_add_f32 v[6:7], v[20:21], 1.0 op_sel_hi:[1,0] neg_lo:[1,0] neg_hi:[1,0]
	s_nop 0
	v_pk_mul_f32 v[22:23], v[6:7], v[4:5]
	v_mul_f32_e32 v5, v20, v4
	v_mul_f32_e32 v4, v19, v5
	v_pk_add_f32 v[6:7], v[18:19], 1.0 op_sel_hi:[1,0] neg_lo:[1,0] neg_hi:[1,0]
	s_nop 0
	v_pk_mul_f32 v[20:21], v[6:7], v[4:5]
	v_mul_f32_e32 v5, v18, v4
	v_mul_f32_e32 v4, v15, v5
	v_pk_add_f32 v[6:7], v[14:15], 1.0 op_sel_hi:[1,0] neg_lo:[1,0] neg_hi:[1,0]
	s_nop 0
	v_pk_mul_f32 v[18:19], v[6:7], v[4:5]
	v_mul_f32_e32 v5, v14, v4
	v_mul_f32_e32 v4, v13, v5
	v_pk_add_f32 v[6:7], v[12:13], 1.0 op_sel_hi:[1,0] neg_lo:[1,0] neg_hi:[1,0]
	s_nop 0
	v_pk_mul_f32 v[6:7], v[6:7], v[4:5]
	v_mul_f32_e32 v5, v12, v4
	v_mul_f32_e32 v4, v11, v5
	v_pk_add_f32 v[12:13], v[10:11], 1.0 op_sel_hi:[1,0] neg_lo:[1,0] neg_hi:[1,0]
	v_mul_f32_e32 v11, v10, v4
	v_pk_mul_f32 v[12:13], v[12:13], v[4:5]
	v_mul_f32_e32 v10, v9, v11
	v_pk_add_f32 v[4:5], v[8:9], 1.0 op_sel_hi:[1,0] neg_lo:[1,0] neg_hi:[1,0]
	v_cvt_pk_bf16_f32 v6, v6, v7
	v_pk_mul_f32 v[4:5], v[4:5], v[10:11]
	v_cvt_pk_bf16_f32 v7, v18, v19
	v_cvt_pk_bf16_f32 v4, v4, v5
	v_cvt_pk_bf16_f32 v5, v12, v13
	ds_write_b128 v0, v[4:7]
	v_cvt_pk_bf16_f32 v4, v20, v21
	v_cvt_pk_bf16_f32 v5, v22, v23
	v_cvt_pk_bf16_f32 v6, v24, v25
	v_cvt_pk_bf16_f32 v7, v26, v27
	ds_write_b128 v0, v[4:7] offset:16
	v_cvt_pk_bf16_f32 v4, v28, v29
	v_cvt_pk_bf16_f32 v5, v30, v31
	v_cvt_pk_bf16_f32 v6, v32, v33
	v_cvt_pk_bf16_f32 v7, v36, v37
	ds_write_b128 v0, v[4:7] offset:32
	v_cvt_pk_bf16_f32 v4, v38, v39
	v_cvt_pk_bf16_f32 v5, v40, v41
	v_cvt_pk_bf16_f32 v6, v42, v43
	v_cvt_pk_bf16_f32 v7, v16, v17
	ds_write_b128 v0, v[4:7] offset:48
	v_mul_f32_e32 v0, v8, v10
	v_ashrrev_i32_e32 v4, 5, v34
	global_store_dword v[2:3], v0, off
	v_lshlrev_b32_e32 v0, 4, v4
	v_add_u32_e32 v47, vcc_lo, v0
	v_mad_u32_u24 v18, v46, s14, v47
	ds_read_b128 v[22:25], v18 offset:9216
	ds_read_b128 v[42:45], v18
	ds_read_b128 v[38:41], v18 offset:32
	v_lshlrev_b32_e32 v78, 2, v4
	s_waitcnt lgkmcnt(1)
	v_mfma_f32_32x32x16_bf16 v[2:17], v[42:45], v[22:25], 0
	ds_read_b128 v[26:29], v18 offset:9248
	ds_read_b128 v[54:57], v18 offset:64
	ds_read_b128 v[30:33], v18 offset:9280
	ds_read_b128 v[50:53], v18 offset:96
	ds_read_b128 v[18:21], v18 offset:9312
	v_and_b32_e32 v66, 48, v0
	v_or_b32_e32 v0, v66, v79
	v_mul_u32_u24_e32 v0, 0x2100, v0
	v_and_b32_e32 v34, -16, v78
	s_waitcnt lgkmcnt(4)
	v_mfma_f32_32x32x16_bf16 v[2:17], v[38:41], v[26:29], v[2:17]
	v_ashrrev_i32_e32 v35, 31, v34
	v_lshlrev_b32_e32 v0, 2, v0
	v_lshl_add_u64 v[36:37], s[0:1], 0, v[0:1]
	v_lshlrev_b64 v[72:73], 2, v[34:35]
	v_lshl_add_u64 v[34:35], v[36:37], 0, v[72:73]
	v_lshlrev_b32_e32 v0, 2, v48
	v_lshl_add_u64 v[58:59], v[34:35], 0, v[0:1]
	s_waitcnt lgkmcnt(2)
	v_mfma_f32_32x32x16_bf16 v[2:17], v[54:57], v[30:33], v[2:17]
	v_or_b32_e32 v68, 4, v66
	v_mov_b32_e32 v35, v1
	v_or_b32_e32 v70, 8, v66
	v_or_b32_e32 v81, 12, v66
	v_mad_u32_u24 v90, v67, s14, v47
	s_waitcnt lgkmcnt(0)
	v_mfma_f32_32x32x16_bf16 v[2:17], v[50:53], v[18:21], v[2:17]
	s_nop 11
	global_store_dword v[58:59], v2, off
	v_or_b32_e32 v2, v68, v79
	v_mul_u32_u24_e32 v2, 0x2100, v2
	v_lshlrev_b32_e32 v34, 2, v2
	v_lshl_add_u64 v[34:35], s[0:1], 0, v[34:35]
	v_lshl_add_u64 v[34:35], v[34:35], 0, v[72:73]
	v_or_b32_e32 v2, v70, v79
	v_lshl_add_u64 v[60:61], v[34:35], 0, v[0:1]
	v_mul_u32_u24_e32 v2, 0x2100, v2
	global_store_dword v[60:61], v3, off
	v_lshlrev_b32_e32 v2, 2, v2
	v_mov_b32_e32 v3, v1
	v_lshl_add_u64 v[2:3], s[0:1], 0, v[2:3]
	v_lshl_add_u64 v[2:3], v[2:3], 0, v[72:73]
	v_lshl_add_u64 v[62:63], v[2:3], 0, v[0:1]
	v_or_b32_e32 v2, v81, v79
	v_mul_u32_u24_e32 v2, 0x2100, v2
	v_lshlrev_b32_e32 v2, 2, v2
	v_mov_b32_e32 v3, v1
	v_lshl_add_u64 v[2:3], s[0:1], 0, v[2:3]
	v_lshl_add_u64 v[2:3], v[2:3], 0, v[72:73]
	v_lshl_add_u64 v[64:65], v[2:3], 0, v[0:1]
	v_add_u32_e32 v2, 8, v78
	v_lshlrev_b32_e32 v3, 2, v2
	v_and_b32_e32 v82, 48, v3
	v_or_b32_e32 v3, v82, v79
	global_store_dword v[62:63], v4, off
	v_mul_u32_u24_e32 v4, 0x2100, v3
	v_and_b32_e32 v2, -16, v2
	global_store_dword v[64:65], v5, off
	v_ashrrev_i32_e32 v3, 31, v2
	v_lshlrev_b32_e32 v4, 2, v4
	v_mov_b32_e32 v5, v1
	v_lshl_add_u64 v[4:5], s[0:1], 0, v[4:5]
	v_lshlrev_b64 v[74:75], 2, v[2:3]
	v_lshl_add_u64 v[2:3], v[4:5], 0, v[74:75]
	v_lshl_add_u64 v[2:3], v[2:3], 0, v[0:1]
	v_or_b32_e32 v83, 4, v82
	global_store_dword v[2:3], v6, off
	v_or_b32_e32 v2, v83, v79
	v_mul_u32_u24_e32 v2, 0x2100, v2
	v_lshlrev_b32_e32 v2, 2, v2
	v_mov_b32_e32 v3, v1
	v_lshl_add_u64 v[2:3], s[0:1], 0, v[2:3]
	v_lshl_add_u64 v[2:3], v[2:3], 0, v[74:75]
	v_lshl_add_u64 v[2:3], v[2:3], 0, v[0:1]
	v_or_b32_e32 v84, 8, v82
	global_store_dword v[2:3], v7, off
	v_or_b32_e32 v2, v84, v79
	v_mul_u32_u24_e32 v2, 0x2100, v2
	v_lshlrev_b32_e32 v2, 2, v2
	v_mov_b32_e32 v3, v1
	v_lshl_add_u64 v[2:3], s[0:1], 0, v[2:3]
	v_lshl_add_u64 v[2:3], v[2:3], 0, v[74:75]
	v_lshl_add_u64 v[2:3], v[2:3], 0, v[0:1]
	v_or_b32_e32 v85, 12, v82
	global_store_dword v[2:3], v8, off
	v_or_b32_e32 v2, v85, v79
	v_mul_u32_u24_e32 v2, 0x2100, v2
	v_lshlrev_b32_e32 v2, 2, v2
	v_mov_b32_e32 v3, v1
	v_lshl_add_u64 v[2:3], s[0:1], 0, v[2:3]
	v_lshl_add_u64 v[2:3], v[2:3], 0, v[74:75]
	v_lshl_add_u64 v[2:3], v[2:3], 0, v[0:1]
	global_store_dword v[2:3], v9, off
	global_store_dword v[58:59], v10, off offset:64
	global_store_dword v[60:61], v11, off offset:64
	global_store_dword v[62:63], v12, off offset:64
	global_store_dword v[64:65], v13, off offset:64
	v_add_u32_e32 v2, 24, v78
	v_lshlrev_b32_e32 v3, 2, v2
	v_and_b32_e32 v86, 48, v3
	v_or_b32_e32 v3, v86, v79
	v_mul_u32_u24_e32 v4, 0x2100, v3
	v_and_b32_e32 v2, -16, v2
	v_ashrrev_i32_e32 v3, 31, v2
	v_lshlrev_b32_e32 v4, 2, v4
	v_mov_b32_e32 v5, v1
	v_lshl_add_u64 v[4:5], s[0:1], 0, v[4:5]
	v_lshlrev_b64 v[76:77], 2, v[2:3]
	v_lshl_add_u64 v[2:3], v[4:5], 0, v[76:77]
	v_lshl_add_u64 v[2:3], v[2:3], 0, v[0:1]
	v_or_b32_e32 v87, 4, v86
	global_store_dword v[2:3], v14, off
	v_or_b32_e32 v2, v87, v79
	v_mul_u32_u24_e32 v2, 0x2100, v2
	v_lshlrev_b32_e32 v2, 2, v2
	v_mov_b32_e32 v3, v1
	v_lshl_add_u64 v[2:3], s[0:1], 0, v[2:3]
	v_lshl_add_u64 v[2:3], v[2:3], 0, v[76:77]
	v_lshl_add_u64 v[2:3], v[2:3], 0, v[0:1]
	v_or_b32_e32 v88, 8, v86
	global_store_dword v[2:3], v15, off
	v_or_b32_e32 v2, v88, v79
	v_mul_u32_u24_e32 v2, 0x2100, v2
	v_lshlrev_b32_e32 v2, 2, v2
	v_mov_b32_e32 v3, v1
	v_lshl_add_u64 v[2:3], s[0:1], 0, v[2:3]
	v_lshl_add_u64 v[2:3], v[2:3], 0, v[76:77]
	v_lshl_add_u64 v[2:3], v[2:3], 0, v[0:1]
	v_or_b32_e32 v89, 12, v86
	global_store_dword v[2:3], v16, off
	v_or_b32_e32 v2, v89, v79
	v_mul_u32_u24_e32 v2, 0x2100, v2
	v_lshlrev_b32_e32 v2, 2, v2
	v_mov_b32_e32 v3, v1
	v_lshl_add_u64 v[2:3], s[0:1], 0, v[2:3]
	v_lshl_add_u64 v[2:3], v[2:3], 0, v[76:77]
	v_lshl_add_u64 v[2:3], v[2:3], 0, v[0:1]
	global_store_dword v[2:3], v17, off
	ds_read_b128 v[46:49], v90 offset:9216
	ds_read_b128 v[34:37], v90 offset:9248
	s_waitcnt lgkmcnt(1)
	v_mfma_f32_32x32x16_bf16 v[2:17], v[42:45], v[46:49], 0
	ds_read_b128 v[42:45], v90 offset:9280
	s_waitcnt lgkmcnt(1)
	v_mfma_f32_32x32x16_bf16 v[2:17], v[38:41], v[34:37], v[2:17]
	ds_read_b128 v[38:41], v90 offset:9312
	s_waitcnt lgkmcnt(1)
	v_mfma_f32_32x32x16_bf16 v[2:17], v[54:57], v[42:45], v[2:17]
	s_waitcnt lgkmcnt(0)
	v_mfma_f32_32x32x16_bf16 v[2:17], v[50:53], v[38:41], v[2:17]
	v_or_b32_e32 v50, v66, v80
	v_mul_u32_u24_e32 v50, 0x2100, v50
	v_lshlrev_b32_e32 v50, 2, v50
	v_mov_b32_e32 v51, v1
	v_lshl_add_u64 v[50:51], s[0:1], 0, v[50:51]
	v_lshl_add_u64 v[50:51], v[50:51], 0, v[72:73]
	v_lshl_add_u64 v[66:67], v[50:51], 0, v[0:1]
	s_nop 4
	global_store_dword v[66:67], v2, off
	v_or_b32_e32 v2, v68, v80
	v_mul_u32_u24_e32 v2, 0x2100, v2
	v_lshlrev_b32_e32 v50, 2, v2
	v_mov_b32_e32 v51, v1
	v_lshl_add_u64 v[50:51], s[0:1], 0, v[50:51]
	v_lshl_add_u64 v[50:51], v[50:51], 0, v[72:73]
	v_or_b32_e32 v2, v70, v80
	v_lshl_add_u64 v[68:69], v[50:51], 0, v[0:1]
	v_mul_u32_u24_e32 v2, 0x2100, v2
	global_store_dword v[68:69], v3, off
	v_lshlrev_b32_e32 v2, 2, v2
	v_mov_b32_e32 v3, v1
	v_lshl_add_u64 v[2:3], s[0:1], 0, v[2:3]
	v_lshl_add_u64 v[2:3], v[2:3], 0, v[72:73]
	v_lshl_add_u64 v[70:71], v[2:3], 0, v[0:1]
	v_or_b32_e32 v2, v81, v80
	v_mul_u32_u24_e32 v2, 0x2100, v2
	v_lshlrev_b32_e32 v2, 2, v2
	v_mov_b32_e32 v3, v1
	v_lshl_add_u64 v[2:3], s[0:1], 0, v[2:3]
	v_lshl_add_u64 v[2:3], v[2:3], 0, v[72:73]
	v_lshl_add_u64 v[72:73], v[2:3], 0, v[0:1]
	v_or_b32_e32 v2, v82, v80
	v_mul_u32_u24_e32 v2, 0x2100, v2
	v_lshlrev_b32_e32 v2, 2, v2
	v_mov_b32_e32 v3, v1
	v_lshl_add_u64 v[2:3], s[0:1], 0, v[2:3]
	v_lshl_add_u64 v[2:3], v[2:3], 0, v[74:75]
	v_lshl_add_u64 v[2:3], v[2:3], 0, v[0:1]
	global_store_dword v[70:71], v4, off
	global_store_dword v[72:73], v5, off
	global_store_dword v[2:3], v6, off
	v_or_b32_e32 v2, v83, v80
	v_mul_u32_u24_e32 v2, 0x2100, v2
	v_lshlrev_b32_e32 v2, 2, v2
	v_mov_b32_e32 v3, v1
	v_lshl_add_u64 v[2:3], s[0:1], 0, v[2:3]
	v_lshl_add_u64 v[2:3], v[2:3], 0, v[74:75]
	v_lshl_add_u64 v[2:3], v[2:3], 0, v[0:1]
	global_store_dword v[2:3], v7, off
	v_or_b32_e32 v2, v84, v80
	v_mul_u32_u24_e32 v2, 0x2100, v2
	v_lshlrev_b32_e32 v2, 2, v2
	v_mov_b32_e32 v3, v1
	v_lshl_add_u64 v[2:3], s[0:1], 0, v[2:3]
	v_lshl_add_u64 v[2:3], v[2:3], 0, v[74:75]
	v_lshl_add_u64 v[2:3], v[2:3], 0, v[0:1]
	global_store_dword v[2:3], v8, off
	v_or_b32_e32 v2, v85, v80
	v_mul_u32_u24_e32 v2, 0x2100, v2
	v_lshlrev_b32_e32 v2, 2, v2
	v_mov_b32_e32 v3, v1
	v_lshl_add_u64 v[2:3], s[0:1], 0, v[2:3]
	v_lshl_add_u64 v[2:3], v[2:3], 0, v[74:75]
	v_lshl_add_u64 v[2:3], v[2:3], 0, v[0:1]
	global_store_dword v[2:3], v9, off
	global_store_dword v[66:67], v10, off offset:64
	global_store_dword v[68:69], v11, off offset:64
	global_store_dword v[70:71], v12, off offset:64
	global_store_dword v[72:73], v13, off offset:64
	v_or_b32_e32 v2, v86, v80
	v_mul_u32_u24_e32 v2, 0x2100, v2
	v_lshlrev_b32_e32 v2, 2, v2
	v_mov_b32_e32 v3, v1
	v_lshl_add_u64 v[2:3], s[0:1], 0, v[2:3]
	v_lshl_add_u64 v[2:3], v[2:3], 0, v[76:77]
	v_lshl_add_u64 v[2:3], v[2:3], 0, v[0:1]
	global_store_dword v[2:3], v14, off
	v_or_b32_e32 v2, v87, v80
	v_mul_u32_u24_e32 v2, 0x2100, v2
	v_lshlrev_b32_e32 v2, 2, v2
	v_mov_b32_e32 v3, v1
	v_lshl_add_u64 v[2:3], s[0:1], 0, v[2:3]
	v_lshl_add_u64 v[2:3], v[2:3], 0, v[76:77]
	v_lshl_add_u64 v[2:3], v[2:3], 0, v[0:1]
	global_store_dword v[2:3], v15, off
	v_or_b32_e32 v2, v88, v80
	v_mul_u32_u24_e32 v2, 0x2100, v2
	v_lshlrev_b32_e32 v2, 2, v2
	v_mov_b32_e32 v3, v1
	v_lshl_add_u64 v[2:3], s[0:1], 0, v[2:3]
	v_lshl_add_u64 v[2:3], v[2:3], 0, v[76:77]
	v_lshl_add_u64 v[2:3], v[2:3], 0, v[0:1]
	global_store_dword v[2:3], v16, off
	v_or_b32_e32 v2, v89, v80
	v_mul_u32_u24_e32 v2, 0x2100, v2
	v_lshlrev_b32_e32 v2, 2, v2
	v_mov_b32_e32 v3, v1
	v_lshl_add_u64 v[2:3], s[0:1], 0, v[2:3]
	v_lshl_add_u64 v[2:3], v[2:3], 0, v[76:77]
	v_lshl_add_u64 v[2:3], v[2:3], 0, v[0:1]
	global_store_dword v[2:3], v17, off
	ds_read_b128 v[54:57], v90
	ds_read_b128 v[50:53], v90 offset:32
	s_waitcnt lgkmcnt(1)
	v_mfma_f32_32x32x16_bf16 v[2:17], v[54:57], v[22:25], 0
	ds_read_b128 v[22:25], v90 offset:64
	s_waitcnt lgkmcnt(1)
	v_mfma_f32_32x32x16_bf16 v[2:17], v[50:53], v[26:29], v[2:17]
	ds_read_b128 v[26:29], v90 offset:96
	s_waitcnt lgkmcnt(1)
	v_mfma_f32_32x32x16_bf16 v[2:17], v[22:25], v[30:33], v[2:17]
	s_waitcnt lgkmcnt(0)
	v_mfma_f32_32x32x16_bf16 v[2:17], v[26:29], v[18:21], v[2:17]
	s_nop 11
	global_store_dword v[58:59], v2, off offset:128
	global_store_dword v[60:61], v3, off offset:128
	global_store_dword v[62:63], v4, off offset:128
	global_store_dword v[64:65], v5, off offset:128
	v_add_u32_e32 v2, 40, v78
	v_lshlrev_b32_e32 v3, 2, v2
	v_and_b32_e32 v30, 48, v3
	v_or_b32_e32 v3, v30, v79
	v_mul_u32_u24_e32 v4, 0x2100, v3
	v_and_b32_e32 v2, -16, v2
	v_ashrrev_i32_e32 v3, 31, v2
	v_lshlrev_b32_e32 v4, 2, v4
	v_mov_b32_e32 v5, v1
	v_lshl_add_u64 v[4:5], s[0:1], 0, v[4:5]
	v_lshlrev_b64 v[18:19], 2, v[2:3]
	v_lshl_add_u64 v[2:3], v[4:5], 0, v[18:19]
	v_lshl_add_u64 v[2:3], v[2:3], 0, v[0:1]
	v_or_b32_e32 v31, 4, v30
	global_store_dword v[2:3], v6, off
	v_or_b32_e32 v2, v31, v79
	v_mul_u32_u24_e32 v2, 0x2100, v2
	v_lshlrev_b32_e32 v2, 2, v2
	v_mov_b32_e32 v3, v1
	v_lshl_add_u64 v[2:3], s[0:1], 0, v[2:3]
	v_lshl_add_u64 v[2:3], v[2:3], 0, v[18:19]
	v_lshl_add_u64 v[2:3], v[2:3], 0, v[0:1]
	v_or_b32_e32 v32, 8, v30
	global_store_dword v[2:3], v7, off
	v_or_b32_e32 v2, v32, v79
	v_mul_u32_u24_e32 v2, 0x2100, v2
	v_lshlrev_b32_e32 v2, 2, v2
	v_mov_b32_e32 v3, v1
	v_lshl_add_u64 v[2:3], s[0:1], 0, v[2:3]
	v_lshl_add_u64 v[2:3], v[2:3], 0, v[18:19]
	v_lshl_add_u64 v[2:3], v[2:3], 0, v[0:1]
	v_or_b32_e32 v33, 12, v30
	global_store_dword v[2:3], v8, off
	v_or_b32_e32 v2, v33, v79
	v_mul_u32_u24_e32 v2, 0x2100, v2
	v_lshlrev_b32_e32 v2, 2, v2
	v_mov_b32_e32 v3, v1
	v_lshl_add_u64 v[2:3], s[0:1], 0, v[2:3]
	v_lshl_add_u64 v[2:3], v[2:3], 0, v[18:19]
	v_lshl_add_u64 v[2:3], v[2:3], 0, v[0:1]
	global_store_dword v[2:3], v9, off
	global_store_dword v[58:59], v10, off offset:192
	global_store_dword v[60:61], v11, off offset:192
	global_store_dword v[62:63], v12, off offset:192
	global_store_dword v[64:65], v13, off offset:192
	v_add_u32_e32 v2, 56, v78
	v_lshlrev_b32_e32 v3, 2, v2
	v_and_b32_e32 v58, 48, v3
	v_or_b32_e32 v3, v58, v79
	v_mul_u32_u24_e32 v4, 0x2100, v3
	v_and_b32_e32 v2, -16, v2
	v_ashrrev_i32_e32 v3, 31, v2
	v_lshlrev_b32_e32 v4, 2, v4
	v_mov_b32_e32 v5, v1
	v_lshl_add_u64 v[4:5], s[0:1], 0, v[4:5]
	v_lshlrev_b64 v[20:21], 2, v[2:3]
	v_lshl_add_u64 v[2:3], v[4:5], 0, v[20:21]
	v_lshl_add_u64 v[2:3], v[2:3], 0, v[0:1]
	v_or_b32_e32 v59, 4, v58
	global_store_dword v[2:3], v14, off
	v_or_b32_e32 v2, v59, v79
	v_mul_u32_u24_e32 v2, 0x2100, v2
	v_lshlrev_b32_e32 v2, 2, v2
	v_mov_b32_e32 v3, v1
	v_lshl_add_u64 v[2:3], s[0:1], 0, v[2:3]
	v_lshl_add_u64 v[2:3], v[2:3], 0, v[20:21]
	v_lshl_add_u64 v[2:3], v[2:3], 0, v[0:1]
	v_or_b32_e32 v60, 8, v58
	global_store_dword v[2:3], v15, off
	v_or_b32_e32 v2, v60, v79
	v_mul_u32_u24_e32 v2, 0x2100, v2
	v_lshlrev_b32_e32 v2, 2, v2
	v_mov_b32_e32 v3, v1
	v_lshl_add_u64 v[2:3], s[0:1], 0, v[2:3]
	v_lshl_add_u64 v[2:3], v[2:3], 0, v[20:21]
	v_lshl_add_u64 v[2:3], v[2:3], 0, v[0:1]
	v_or_b32_e32 v61, 12, v58
	global_store_dword v[2:3], v16, off
	v_or_b32_e32 v2, v61, v79
	v_mul_u32_u24_e32 v2, 0x2100, v2
	v_lshlrev_b32_e32 v2, 2, v2
	v_mov_b32_e32 v3, v1
	v_lshl_add_u64 v[2:3], s[0:1], 0, v[2:3]
	v_lshl_add_u64 v[2:3], v[2:3], 0, v[20:21]
	v_lshl_add_u64 v[2:3], v[2:3], 0, v[0:1]
	global_store_dword v[2:3], v17, off
	v_mfma_f32_32x32x16_bf16 v[2:17], v[54:57], v[46:49], 0
	v_mfma_f32_32x32x16_bf16 v[2:17], v[50:53], v[34:37], v[2:17]
	v_mfma_f32_32x32x16_bf16 v[2:17], v[22:25], v[42:45], v[2:17]
	v_mfma_f32_32x32x16_bf16 v[2:17], v[26:29], v[38:41], v[2:17]
	s_nop 11
	global_store_dword v[66:67], v2, off offset:128
	global_store_dword v[68:69], v3, off offset:128
	global_store_dword v[70:71], v4, off offset:128
	global_store_dword v[72:73], v5, off offset:128
	v_or_b32_e32 v2, v30, v80
	v_mul_u32_u24_e32 v2, 0x2100, v2
	v_lshlrev_b32_e32 v2, 2, v2
	v_mov_b32_e32 v3, v1
	v_lshl_add_u64 v[2:3], s[0:1], 0, v[2:3]
	v_lshl_add_u64 v[2:3], v[2:3], 0, v[18:19]
	v_lshl_add_u64 v[2:3], v[2:3], 0, v[0:1]
	global_store_dword v[2:3], v6, off
	v_or_b32_e32 v2, v31, v80
	v_mul_u32_u24_e32 v2, 0x2100, v2
	v_lshlrev_b32_e32 v2, 2, v2
	v_mov_b32_e32 v3, v1
	v_lshl_add_u64 v[2:3], s[0:1], 0, v[2:3]
	v_lshl_add_u64 v[2:3], v[2:3], 0, v[18:19]
	v_lshl_add_u64 v[2:3], v[2:3], 0, v[0:1]
	global_store_dword v[2:3], v7, off
	v_or_b32_e32 v2, v32, v80
	v_mul_u32_u24_e32 v2, 0x2100, v2
	v_lshlrev_b32_e32 v2, 2, v2
	v_mov_b32_e32 v3, v1
	v_lshl_add_u64 v[2:3], s[0:1], 0, v[2:3]
	v_lshl_add_u64 v[2:3], v[2:3], 0, v[18:19]
	v_lshl_add_u64 v[2:3], v[2:3], 0, v[0:1]
	global_store_dword v[2:3], v8, off
	v_or_b32_e32 v2, v33, v80
	v_mul_u32_u24_e32 v2, 0x2100, v2
	v_lshlrev_b32_e32 v2, 2, v2
	v_mov_b32_e32 v3, v1
	v_lshl_add_u64 v[2:3], s[0:1], 0, v[2:3]
	v_lshl_add_u64 v[2:3], v[2:3], 0, v[18:19]
	v_lshl_add_u64 v[2:3], v[2:3], 0, v[0:1]
	global_store_dword v[2:3], v9, off
	global_store_dword v[66:67], v10, off offset:192
	global_store_dword v[68:69], v11, off offset:192
	global_store_dword v[70:71], v12, off offset:192
	global_store_dword v[72:73], v13, off offset:192
	v_or_b32_e32 v2, v58, v80
	v_mul_u32_u24_e32 v2, 0x2100, v2
	v_lshlrev_b32_e32 v2, 2, v2
	v_mov_b32_e32 v3, v1
	v_lshl_add_u64 v[2:3], s[0:1], 0, v[2:3]
	v_lshl_add_u64 v[2:3], v[2:3], 0, v[20:21]
	v_lshl_add_u64 v[2:3], v[2:3], 0, v[0:1]
	global_store_dword v[2:3], v14, off
	v_or_b32_e32 v2, v59, v80
	v_mul_u32_u24_e32 v2, 0x2100, v2
	v_lshlrev_b32_e32 v2, 2, v2
	v_mov_b32_e32 v3, v1
	v_lshl_add_u64 v[2:3], s[0:1], 0, v[2:3]
	v_lshl_add_u64 v[2:3], v[2:3], 0, v[20:21]
	v_lshl_add_u64 v[2:3], v[2:3], 0, v[0:1]
	global_store_dword v[2:3], v15, off
	v_or_b32_e32 v2, v60, v80
	v_mul_u32_u24_e32 v2, 0x2100, v2
	v_lshlrev_b32_e32 v2, 2, v2
	v_mov_b32_e32 v3, v1
	v_lshl_add_u64 v[2:3], s[0:1], 0, v[2:3]
	v_lshl_add_u64 v[2:3], v[2:3], 0, v[20:21]
	v_lshl_add_u64 v[2:3], v[2:3], 0, v[0:1]
	global_store_dword v[2:3], v16, off
	v_or_b32_e32 v2, v61, v80
	v_mul_u32_u24_e32 v2, 0x2100, v2
	v_lshlrev_b32_e32 v2, 2, v2
	v_mov_b32_e32 v3, v1
	v_lshl_add_u64 v[2:3], s[0:1], 0, v[2:3]
	v_lshl_add_u64 v[2:3], v[2:3], 0, v[20:21]
	v_lshl_add_u64 v[2:3], v[2:3], 0, v[0:1]
	global_store_dword v[2:3], v17, off
	v_readlane_b32 s0, v252, 22
	s_waitcnt lgkmcnt(0)
	s_add_i32 s2, s2, s0
	v_readlane_b32 s0, v254, 61
	s_sub_i32 s7, s7, s0
	v_readlane_b32 s1, v254, 62
	s_cmp_ge_i32 s2, s1
	s_cbranch_scc1 .LBB0_443

.LBB0_590:
	s_and_b32 s4, s6, 0x7f
	s_ashr_i32 s5, s6, 7
	s_and_b32 s0, s8, 0xffffe000
	s_lshl_b32 s1, s4, 6
	s_lshl_b32 s11, s5, 1
	s_or_b32 s76, s0, s1
	s_or_b32 s0, s11, 1
	s_mul_hi_i32 s1, s0, 0x2100
	s_mulk_i32 s0, 0x2100
	s_sub_i32 s0, s0, s4
	s_addk_i32 s0, 0x83
	v_mov_b32_e32 v130, v223
	v_mov_b32_e32 v70, v223
	s_lshl_b64 s[0:1], s[0:1], 8
	s_add_u32 s0, s36, s0
	v_ashrrev_i32_e32 v71, 31, v70
	s_addc_u32 s1, s37, s1
	v_lshlrev_b64 v[2:3], 2, v[70:71]
	s_ashr_i32 s77, s76, 31
	v_lshl_add_u64 v[4:5], s[0:1], 0, v[2:3]
	s_lshl_b64 s[36:37], s[76:77], 10
	v_readlane_b32 s0, v254, 29
	v_readlane_b32 s1, v254, 30
	s_add_u32 s0, s0, s36
	s_addc_u32 s1, s1, s37
	s_lshl_b32 s2, s5, 6
	s_and_b32 s2, s2, 0xc0
	s_lshl_b32 s10, s2, 2
	s_add_u32 s0, s0, s10
	v_add_co_u32_e32 v6, vcc, s16, v4
	s_addc_u32 s1, s1, 0
	s_lshl_b64 s[40:41], s[76:77], 9
	s_mov_b32 s77, 0x42000
	v_readlane_b32 s12, v254, 48
	v_addc_co_u32_e32 v7, vcc, 0, v5, vcc
	v_readlane_b32 s13, v254, 49
	s_add_u32 s3, s12, s40
	global_load_dword v8, v[4:5], off
	global_load_dword v9, v[6:7], off
	v_add_co_u32_e32 v6, vcc, s77, v4
	s_addc_u32 s12, s13, s41
	s_lshl_b32 s9, s2, 1
	v_addc_co_u32_e32 v7, vcc, 0, v5, vcc
	s_add_u32 s2, s3, s9
	global_load_dword v10, v[6:7], off
	v_add_co_u32_e32 v6, vcc, s24, v4
	s_addc_u32 s3, s12, 0
	s_nop 0
	v_addc_co_u32_e32 v7, vcc, 0, v5, vcc
	s_mov_b32 s12, 0x84000
	global_load_dword v11, v[6:7], off
	v_add_co_u32_e32 v6, vcc, s12, v4
	s_mov_b32 s12, 0xe7000
	s_nop 0
	v_addc_co_u32_e32 v7, vcc, 0, v5, vcc
	global_load_dword v12, v[6:7], off
	v_add_co_u32_e32 v6, vcc, s31, v4
	s_mov_b32 s30, 0x120000
	s_nop 0
	v_addc_co_u32_e32 v7, vcc, 0, v5, vcc
	global_load_dword v13, v[6:7], off
	v_add_co_u32_e32 v6, vcc, s38, v4
	s_mov_b32 s29, 0x141000
	s_nop 0
	v_addc_co_u32_e32 v7, vcc, 0, v5, vcc
	global_load_dword v14, v[6:7], off
	v_add_co_u32_e32 v6, vcc, s12, v4
	s_mov_b32 s12, 0x108000
	s_nop 0
	v_addc_co_u32_e32 v7, vcc, 0, v5, vcc
	global_load_dword v15, v[6:7], off
	v_add_co_u32_e32 v6, vcc, s12, v4
	s_mov_b32 s12, 0x129000
	s_nop 0
	v_addc_co_u32_e32 v7, vcc, 0, v5, vcc
	global_load_dword v16, v[6:7], off
	v_add_co_u32_e32 v6, vcc, s12, v4
	s_mov_b32 s12, 0x14a000
	s_nop 0
	v_addc_co_u32_e32 v7, vcc, 0, v5, vcc
	global_load_dword v17, v[6:7], off
	v_add_co_u32_e32 v6, vcc, s12, v4
	s_mov_b32 s12, 0x16b000
	s_nop 0
	v_addc_co_u32_e32 v7, vcc, 0, v5, vcc
	global_load_dword v18, v[6:7], off
	v_add_co_u32_e32 v6, vcc, s12, v4
	s_mov_b32 s12, 0x18c000
	s_nop 0
	v_addc_co_u32_e32 v7, vcc, 0, v5, vcc
	global_load_dword v19, v[6:7], off
	v_add_co_u32_e32 v6, vcc, s12, v4
	s_mov_b32 s12, 0x1ad000
	s_nop 0
	v_addc_co_u32_e32 v7, vcc, 0, v5, vcc
	global_load_dword v21, v[6:7], off
	v_add_co_u32_e32 v6, vcc, s12, v4
	s_mov_b32 s12, 0x1ce000
	s_nop 0
	v_addc_co_u32_e32 v7, vcc, 0, v5, vcc
	global_load_dword v23, v[6:7], off
	v_add_co_u32_e32 v6, vcc, s12, v4
	s_mov_b32 s12, 0x1ef000
	s_nop 0
	v_addc_co_u32_e32 v7, vcc, 0, v5, vcc
	global_load_dword v25, v[6:7], off
	v_add_co_u32_e32 v6, vcc, s12, v4
	s_mov_b32 s12, 0x6b000
	s_nop 0
	v_addc_co_u32_e32 v7, vcc, 0, v5, vcc
	global_load_dword v27, v[6:7], off
	v_add_co_u32_e32 v6, vcc, s97, v4
	s_mov_b32 s28, 0x162000
	s_nop 0
	v_addc_co_u32_e32 v7, vcc, 0, v5, vcc
	global_load_dword v20, v[6:7], off offset:1024
	v_add_co_u32_e32 v6, vcc, s17, v4
	s_mov_b32 s27, 0x183000
	s_nop 0
	v_addc_co_u32_e32 v7, vcc, 0, v5, vcc
	global_load_dword v22, v[6:7], off offset:1024
	v_add_co_u32_e32 v6, vcc, s20, v4
	s_mov_b32 s26, 0x1a4000
	s_nop 0
	v_addc_co_u32_e32 v7, vcc, 0, v5, vcc
	global_load_dword v24, v[6:7], off offset:1024
	v_add_co_u32_e32 v6, vcc, s12, v4
	s_mov_b32 s12, 0x8c000
	s_nop 0
	v_addc_co_u32_e32 v7, vcc, 0, v5, vcc
	global_load_dword v26, v[6:7], off offset:1024
	v_add_co_u32_e32 v6, vcc, s12, v4
	s_mov_b32 s12, 0xef000
	s_nop 0
	v_addc_co_u32_e32 v7, vcc, 0, v5, vcc
	global_load_dword v28, v[6:7], off offset:1024
	v_add_co_u32_e32 v6, vcc, s33, v4
	s_mov_b32 s25, 0x1c5000
	s_nop 0
	v_addc_co_u32_e32 v7, vcc, 0, v5, vcc
	global_load_dword v29, v[6:7], off offset:1024
	v_add_co_u32_e32 v6, vcc, s39, v4
	s_mov_b32 s23, 0x1e6000
	s_nop 0
	v_addc_co_u32_e32 v7, vcc, 0, v5, vcc
	global_load_dword v30, v[6:7], off offset:1024
	v_add_co_u32_e32 v6, vcc, s12, v4
	s_mov_b32 s12, 0x110000
	s_nop 0
	v_addc_co_u32_e32 v7, vcc, 0, v5, vcc
	global_load_dword v31, v[6:7], off offset:1024
	v_add_co_u32_e32 v6, vcc, s12, v4
	s_mov_b32 s12, 0x131000
	s_nop 0
	v_addc_co_u32_e32 v7, vcc, 0, v5, vcc
	global_load_dword v32, v[6:7], off offset:1024
	v_add_co_u32_e32 v6, vcc, s12, v4
	s_mov_b32 s12, 0x152000
	s_nop 0
	v_addc_co_u32_e32 v7, vcc, 0, v5, vcc
	global_load_dword v33, v[6:7], off offset:1024
	v_add_co_u32_e32 v6, vcc, s12, v4
	s_mov_b32 s12, 0x173000
	s_nop 0
	v_addc_co_u32_e32 v7, vcc, 0, v5, vcc
	global_load_dword v34, v[6:7], off offset:1024
	v_add_co_u32_e32 v6, vcc, s12, v4
	s_mov_b32 s12, 0x194000
	s_nop 0
	v_addc_co_u32_e32 v7, vcc, 0, v5, vcc
	global_load_dword v35, v[6:7], off offset:1024
	v_add_co_u32_e32 v6, vcc, s12, v4
	s_mov_b32 s12, 0x1b5000
	s_nop 0
	v_addc_co_u32_e32 v7, vcc, 0, v5, vcc
	global_load_dword v36, v[6:7], off offset:1024
	v_add_co_u32_e32 v6, vcc, s12, v4
	s_mov_b32 s12, 0x1d6000
	s_nop 0
	v_addc_co_u32_e32 v7, vcc, 0, v5, vcc
	global_load_dword v37, v[6:7], off offset:1024
	v_add_co_u32_e32 v6, vcc, s12, v4
	s_mov_b32 s12, 0x1f7000
	s_nop 0
	v_addc_co_u32_e32 v7, vcc, 0, v5, vcc
	global_load_dword v38, v[6:7], off offset:1024
	v_add_co_u32_e32 v6, vcc, s12, v4
	s_mov_b32 s12, 0x73000
	s_nop 0
	v_addc_co_u32_e32 v7, vcc, 0, v5, vcc
	global_load_dword v39, v[6:7], off offset:1024
	v_add_co_u32_e32 v6, vcc, s94, v4
	s_mov_b32 s22, 0x207000
	s_nop 0
	v_addc_co_u32_e32 v7, vcc, 0, v5, vcc
	global_load_dword v40, v[6:7], off offset:2048
	v_add_co_u32_e32 v6, vcc, s18, v4
	v_and_b32_e32 v106, 0x7ffffff0, v70
	s_nop 0
	v_addc_co_u32_e32 v7, vcc, 0, v5, vcc
	global_load_dword v41, v[6:7], off offset:2048
	v_add_co_u32_e32 v6, vcc, s21, v4
	v_lshlrev_b32_e32 v106, 1, v106
	s_nop 0
	v_addc_co_u32_e32 v7, vcc, 0, v5, vcc
	global_load_dword v42, v[6:7], off offset:2048
	v_add_co_u32_e32 v6, vcc, s12, v4
	s_mov_b32 s12, 0x94000
	s_nop 0
	v_addc_co_u32_e32 v7, vcc, 0, v5, vcc
	global_load_dword v43, v[6:7], off offset:2048
	v_add_co_u32_e32 v6, vcc, s12, v4
	s_mov_b32 s12, 0xf7000
	s_nop 0
	v_addc_co_u32_e32 v7, vcc, 0, v5, vcc
	global_load_dword v44, v[6:7], off offset:2048
	v_add_co_u32_e32 v6, vcc, s34, v4
	s_waitcnt vmcnt(35)
	v_cvt_pk_bf16_f32 v8, v8, v9
	v_addc_co_u32_e32 v7, vcc, 0, v5, vcc
	global_load_dword v45, v[6:7], off offset:2048
	v_add_co_u32_e32 v6, vcc, s52, v4
	s_waitcnt vmcnt(34)
	v_cvt_pk_bf16_f32 v9, v10, v11
	v_addc_co_u32_e32 v7, vcc, 0, v5, vcc
	global_load_dword v46, v[6:7], off offset:2048
	v_add_co_u32_e32 v6, vcc, s12, v4
	s_mov_b32 s12, 0x118000
	s_nop 0
	v_addc_co_u32_e32 v7, vcc, 0, v5, vcc
	global_load_dword v47, v[6:7], off offset:2048
	v_add_co_u32_e32 v6, vcc, s12, v4
	s_mov_b32 s12, 0x139000
	s_nop 0
	v_addc_co_u32_e32 v7, vcc, 0, v5, vcc
	global_load_dword v48, v[6:7], off offset:2048
	v_add_co_u32_e32 v6, vcc, s12, v4
	s_mov_b32 s12, 0x15a000
	s_nop 0
	v_addc_co_u32_e32 v7, vcc, 0, v5, vcc
	global_load_dword v49, v[6:7], off offset:2048
	v_add_co_u32_e32 v6, vcc, s12, v4
	s_mov_b32 s12, 0x17b000
	s_nop 0
	v_addc_co_u32_e32 v7, vcc, 0, v5, vcc
	global_load_dword v50, v[6:7], off offset:2048
	v_add_co_u32_e32 v6, vcc, s12, v4
	s_mov_b32 s12, 0x19c000
	s_nop 0
	v_addc_co_u32_e32 v7, vcc, 0, v5, vcc
	global_load_dword v51, v[6:7], off offset:2048
	v_add_co_u32_e32 v6, vcc, s12, v4
	s_mov_b32 s12, 0x1bd000
	s_nop 0
	v_addc_co_u32_e32 v7, vcc, 0, v5, vcc
	global_load_dword v54, v[6:7], off offset:2048
	v_add_co_u32_e32 v6, vcc, s12, v4
	s_mov_b32 s12, 0x1de000
	s_nop 0
	v_addc_co_u32_e32 v7, vcc, 0, v5, vcc
	global_load_dword v55, v[6:7], off offset:2048
	v_add_co_u32_e32 v6, vcc, s12, v4
	s_mov_b32 s12, 0x1ff000
	s_nop 0
	v_addc_co_u32_e32 v7, vcc, 0, v5, vcc
	global_load_dword v56, v[6:7], off offset:2048
	v_add_co_u32_e32 v6, vcc, s12, v4
	s_mov_b32 s12, 0x5a000
	s_nop 0
	v_addc_co_u32_e32 v7, vcc, 0, v5, vcc
	global_load_dword v57, v[6:7], off offset:2048
	v_add_co_u32_e32 v6, vcc, s96, v4
	s_waitcnt vmcnt(42)
	v_cvt_pk_bf16_f32 v10, v12, v13
	v_addc_co_u32_e32 v7, vcc, 0, v5, vcc
	global_load_dword v58, v[6:7], off offset:3072
	v_add_co_u32_e32 v6, vcc, s19, v4
	s_waitcnt vmcnt(39)
	v_cvt_pk_bf16_f32 v12, v16, v17
	v_addc_co_u32_e32 v7, vcc, 0, v5, vcc
	global_load_dword v59, v[6:7], off offset:3072
	v_add_co_u32_e32 v6, vcc, s12, v4
	s_mov_b32 s12, 0x7b000
	s_nop 0
	v_addc_co_u32_e32 v7, vcc, 0, v5, vcc
	global_load_dword v60, v[6:7], off offset:3072
	v_add_co_u32_e32 v6, vcc, s12, v4
	s_mov_b32 s12, 0x9c000
	s_nop 0
	v_addc_co_u32_e32 v7, vcc, 0, v5, vcc
	global_load_dword v61, v[6:7], off offset:3072
	v_add_co_u32_e32 v6, vcc, s12, v4
	s_mov_b32 s12, 0xff000
	s_nop 0
	v_addc_co_u32_e32 v7, vcc, 0, v5, vcc
	global_load_dword v62, v[6:7], off offset:3072
	v_add_co_u32_e32 v6, vcc, s35, v4
	s_mov_b32 s13, s85
	s_nop 0
	v_addc_co_u32_e32 v7, vcc, 0, v5, vcc
	global_load_dword v63, v[6:7], off offset:3072
	v_add_co_u32_e32 v6, vcc, s53, v4
	s_movk_i32 s85, 0x7000
	s_nop 0
	v_addc_co_u32_e32 v7, vcc, 0, v5, vcc
	global_load_dword v64, v[6:7], off offset:3072
	v_add_co_u32_e32 v6, vcc, s12, v4
	s_waitcnt vmcnt(43)
	v_cvt_pk_bf16_f32 v13, v18, v19
	v_addc_co_u32_e32 v7, vcc, 0, v5, vcc
	global_load_dword v65, v[6:7], off offset:3072
	v_add_co_u32_e32 v6, vcc, s30, v4
	v_cvt_pk_bf16_f32 v11, v14, v15
	s_nop 0
	v_addc_co_u32_e32 v7, vcc, 0, v5, vcc
	global_load_dword v66, v[6:7], off offset:3072
	v_add_co_u32_e32 v6, vcc, s29, v4
	s_waitcnt vmcnt(43)
	v_cvt_pk_bf16_f32 v14, v21, v23
	v_addc_co_u32_e32 v7, vcc, 0, v5, vcc
	global_load_dword v67, v[6:7], off offset:3072
	v_add_co_u32_e32 v6, vcc, s28, v4
	s_waitcnt vmcnt(42)
	v_cvt_pk_bf16_f32 v15, v25, v27
	v_addc_co_u32_e32 v7, vcc, 0, v5, vcc
	global_load_dword v68, v[6:7], off offset:3072
	v_add_co_u32_e32 v6, vcc, s27, v4
	s_mov_b32 s12, s44
	s_nop 0
	v_addc_co_u32_e32 v7, vcc, 0, v5, vcc
	global_load_dword v69, v[6:7], off offset:3072
	v_add_co_u32_e32 v6, vcc, s26, v4
	s_mulk_i32 s5, 0x4200
	s_nop 0
	v_addc_co_u32_e32 v7, vcc, 0, v5, vcc
	global_load_dword v72, v[6:7], off offset:3072
	v_add_co_u32_e32 v6, vcc, s25, v4
	v_and_b32_e32 v0, 31, v130
	s_nop 0
	v_addc_co_u32_e32 v7, vcc, 0, v5, vcc
	global_load_dword v73, v[6:7], off offset:3072
	v_add_co_u32_e32 v6, vcc, s23, v4
	s_nop 1
	v_addc_co_u32_e32 v7, vcc, 0, v5, vcc
	v_add_co_u32_e32 v4, vcc, s22, v4
	global_load_dword v74, v[6:7], off offset:3072
	s_nop 0
	v_addc_co_u32_e32 v5, vcc, 0, v5, vcc
	global_load_dword v75, v[4:5], off offset:3072
	v_lshl_add_u64 v[6:7], s[0:1], 0, v[2:3]
	s_mov_b32 s0, 0xf000
	v_add_co_u32_e32 v52, vcc, s0, v6
	v_lshlrev_b64 v[2:3], 1, v[70:71]
	s_nop 0
	v_addc_co_u32_e32 v53, vcc, 0, v7, vcc
	global_load_dword v71, v[52:53], off offset:3072
	global_load_dword v76, v[52:53], off offset:2048
	global_load_dword v77, v[52:53], off offset:1024
	global_load_dword v78, v[52:53], off
	v_add_co_u32_e32 v52, vcc, s75, v6
	s_mov_b32 s0, 0xd000
	s_nop 0
	v_addc_co_u32_e32 v53, vcc, 0, v7, vcc
	global_load_dword v79, v[52:53], off offset:3072
	global_load_dword v80, v[52:53], off offset:2048
	global_load_dword v81, v[52:53], off offset:1024
	global_load_dword v82, v[52:53], off
	v_add_co_u32_e32 v52, vcc, s0, v6
	s_mov_b32 s0, 0xb000
	s_nop 0
	v_addc_co_u32_e32 v53, vcc, 0, v7, vcc
	global_load_dword v83, v[52:53], off offset:3072
	global_load_dword v84, v[52:53], off offset:2048
	global_load_dword v85, v[52:53], off offset:1024
	global_load_dword v86, v[52:53], off
	v_add_co_u32_e32 v52, vcc, s74, v6
	v_lshl_add_u64 v[4:5], s[2:3], 0, v[2:3]
	s_nop 0
	v_addc_co_u32_e32 v53, vcc, 0, v7, vcc
	global_load_dword v87, v[52:53], off offset:3072
	global_load_dword v88, v[52:53], off offset:2048
	global_load_dword v89, v[52:53], off offset:1024
	global_load_dword v90, v[52:53], off
	v_add_co_u32_e32 v52, vcc, s0, v6
	s_mov_b32 s0, 0x9000
	s_nop 0
	v_addc_co_u32_e32 v53, vcc, 0, v7, vcc
	global_load_dword v91, v[52:53], off offset:3072
	global_load_dword v92, v[52:53], off offset:2048
	global_load_dword v93, v[52:53], off offset:1024
	global_load_dword v94, v[52:53], off
	v_add_co_u32_e32 v52, vcc, s72, v6
	s_nop 1
	v_addc_co_u32_e32 v53, vcc, 0, v7, vcc
	global_load_dword v95, v[52:53], off offset:3072
	global_load_dword v96, v[52:53], off offset:2048
	global_load_dword v97, v[52:53], off offset:1024
	global_load_dword v98, v[52:53], off
	v_add_co_u32_e32 v52, vcc, s0, v6
	s_nop 1
	v_addc_co_u32_e32 v53, vcc, 0, v7, vcc
	global_load_dword v99, v[52:53], off offset:3072
	global_load_dword v100, v[52:53], off offset:2048
	global_load_dword v101, v[52:53], off offset:1024
	global_load_dword v102, v[52:53], off
	v_add_co_u32_e32 v52, vcc, s97, v6
	s_nop 1
	v_addc_co_u32_e32 v53, vcc, 0, v7, vcc
	global_load_dword v103, v[52:53], off offset:3072
	global_load_dword v104, v[52:53], off offset:2048
	global_load_dword v105, v[52:53], off offset:1024
	s_nop 0
	global_load_dword v52, v[52:53], off
	v_and_b32_e32 v53, 15, v70
	v_mul_u32_u24_e32 v16, 0x90, v53
	v_add3_u32 v18, s7, v106, v16
	v_add_co_u32_e32 v16, vcc, s85, v4
	s_nop 1
	v_addc_co_u32_e32 v17, vcc, 0, v5, vcc
	global_load_ushort v19, v[16:17], off offset:3584
	global_load_ushort v21, v[16:17], off offset:3072
	global_load_ushort v23, v[16:17], off offset:2560
	global_load_ushort v25, v[16:17], off offset:2048
	global_load_ushort v27, v[16:17], off offset:1536
	global_load_ushort v53, v[16:17], off offset:1024
	global_load_ushort v106, v[16:17], off offset:512
	global_load_ushort v107, v[16:17], off
	v_add_co_u32_e32 v16, vcc, s95, v4
	s_nop 1
	v_addc_co_u32_e32 v17, vcc, 0, v5, vcc
	global_load_ushort v108, v[16:17], off offset:3584
	global_load_ushort v109, v[16:17], off offset:3072
	global_load_ushort v110, v[16:17], off offset:2560
	global_load_ushort v111, v[16:17], off offset:2048
	global_load_ushort v112, v[16:17], off offset:1536
	global_load_ushort v113, v[16:17], off offset:1024
	global_load_ushort v114, v[16:17], off offset:512
	global_load_ushort v115, v[16:17], off
	v_add_co_u32_e32 v16, vcc, s92, v4
	s_nop 1
	v_addc_co_u32_e32 v17, vcc, 0, v5, vcc
	global_load_ushort v116, v[16:17], off offset:3584
	global_load_ushort v117, v[16:17], off offset:3072
	global_load_ushort v118, v[16:17], off offset:2560
	global_load_ushort v119, v[16:17], off offset:2048
	global_load_ushort v120, v[16:17], off offset:1536
	global_load_ushort v121, v[16:17], off offset:1024
	global_load_ushort v122, v[16:17], off offset:512
	global_load_ushort v123, v[16:17], off
	v_add_co_u32_e32 v16, vcc, s81, v4
	s_nop 1
	v_addc_co_u32_e32 v17, vcc, 0, v5, vcc
	global_load_ushort v124, v[16:17], off offset:3584
	global_load_ushort v125, v[16:17], off offset:3072
	global_load_ushort v126, v[16:17], off offset:2560
	global_load_ushort v127, v[16:17], off offset:2048
	global_load_ushort v128, v[16:17], off offset:1536
	global_load_ushort v129, v[16:17], off offset:1024
	global_load_ushort v131, v[16:17], off offset:512
	s_nop 0
	global_load_ushort v16, v[16:17], off
	ds_write_b128 v18, v[8:11] offset:23040
	ds_write_b128 v18, v[12:15] offset:23056
	s_waitcnt vmcnt(62)
	v_cvt_pk_bf16_f32 v8, v20, v22
	v_cvt_pk_bf16_f32 v9, v24, v26
	v_cvt_pk_bf16_f32 v10, v28, v29
	v_cvt_pk_bf16_f32 v11, v30, v31
	v_cvt_pk_bf16_f32 v12, v32, v33
	v_cvt_pk_bf16_f32 v13, v34, v35
	v_cvt_pk_bf16_f32 v14, v36, v37
	v_cvt_pk_bf16_f32 v15, v38, v39
	ds_write_b128 v18, v[8:11] offset:25344
	ds_write_b128 v18, v[12:15] offset:25360
	v_cvt_pk_bf16_f32 v8, v40, v41
	v_cvt_pk_bf16_f32 v9, v42, v43
	v_cvt_pk_bf16_f32 v10, v44, v45
	v_cvt_pk_bf16_f32 v11, v46, v47
	v_cvt_pk_bf16_f32 v12, v48, v49
	v_cvt_pk_bf16_f32 v13, v50, v51
	v_cvt_pk_bf16_f32 v14, v54, v55
	v_cvt_pk_bf16_f32 v15, v56, v57
	ds_write_b128 v18, v[8:11] offset:27648
	ds_write_b128 v18, v[12:15] offset:27664
	v_cvt_pk_bf16_f32 v8, v58, v59
	v_cvt_pk_bf16_f32 v9, v60, v61
	v_cvt_pk_bf16_f32 v10, v62, v63
	v_cvt_pk_bf16_f32 v11, v64, v65
	v_cvt_pk_bf16_f32 v12, v66, v67
	v_cvt_pk_bf16_f32 v13, v68, v69
	v_cvt_pk_bf16_f32 v14, v72, v73
	v_cvt_pk_bf16_f32 v15, v74, v75
	ds_write_b128 v18, v[8:11] offset:29952
	ds_write_b128 v18, v[12:15] offset:29968
	v_rcp_f32_e32 v11, v71
	v_sub_f32_e32 v10, 1.0, v71
	v_lshl_add_u32 v8, v70, 1, s7
	v_mul_f32_e32 v10, v10, v11
	v_sub_f32_e32 v11, 1.0, v76
	s_waitcnt vmcnt(31)
	v_lshlrev_b32_e32 v9, 16, v19
	v_mul_f32_e32 v9, v71, v9
	v_cvt_pk_bf16_f32 v9, v9, s0
	ds_write_b16 v8, v9 offset:9216
	v_cvt_pk_bf16_f32 v9, v10, s0
	v_mul_f32_e32 v10, v71, v76
	v_rcp_f32_e32 v12, v10
	ds_write_b16 v8, v9
	s_waitcnt vmcnt(30)
	v_lshlrev_b32_e32 v9, 16, v21
	v_mul_f32_e32 v9, v10, v9
	v_mul_f32_e32 v10, v10, v77
	v_mul_f32_e32 v11, v11, v12
	v_cvt_pk_bf16_f32 v9, v9, s0
	v_rcp_f32_e32 v12, v10
	ds_write_b16 v8, v9 offset:9360
	v_cvt_pk_bf16_f32 v9, v11, s0
	ds_write_b16 v8, v9 offset:144
	s_waitcnt vmcnt(29)
	v_lshlrev_b32_e32 v9, 16, v23
	v_mul_f32_e32 v9, v10, v9
	v_sub_f32_e32 v11, 1.0, v77
	v_mul_f32_e32 v10, v10, v78
	v_mul_f32_e32 v11, v11, v12
	v_cvt_pk_bf16_f32 v9, v9, s0
	v_rcp_f32_e32 v12, v10
	ds_write_b16 v8, v9 offset:9504
	v_cvt_pk_bf16_f32 v9, v11, s0
	ds_write_b16 v8, v9 offset:288
	s_waitcnt vmcnt(28)
	v_lshlrev_b32_e32 v9, 16, v25
	v_mul_f32_e32 v9, v10, v9
	v_sub_f32_e32 v11, 1.0, v78
	v_mul_f32_e32 v10, v10, v79
	v_mul_f32_e32 v11, v11, v12
	v_cvt_pk_bf16_f32 v9, v9, s0
	v_rcp_f32_e32 v12, v10
	ds_write_b16 v8, v9 offset:9648
	v_cvt_pk_bf16_f32 v9, v11, s0
	ds_write_b16 v8, v9 offset:432
	s_waitcnt vmcnt(27)
	v_lshlrev_b32_e32 v9, 16, v27
	v_mul_f32_e32 v9, v10, v9
	v_sub_f32_e32 v11, 1.0, v79
	v_mul_f32_e32 v10, v10, v80
	v_mul_f32_e32 v11, v11, v12
	v_cvt_pk_bf16_f32 v9, v9, s0
	v_rcp_f32_e32 v12, v10
	ds_write_b16 v8, v9 offset:9792
	v_cvt_pk_bf16_f32 v9, v11, s0
	ds_write_b16 v8, v9 offset:576
	s_waitcnt vmcnt(26)
	v_lshlrev_b32_e32 v9, 16, v53
	v_mul_f32_e32 v9, v10, v9
	v_sub_f32_e32 v11, 1.0, v80
	v_mul_f32_e32 v10, v10, v81
	v_mul_f32_e32 v11, v11, v12
	v_cvt_pk_bf16_f32 v9, v9, s0
	v_rcp_f32_e32 v12, v10
	ds_write_b16 v8, v9 offset:9936
	v_cvt_pk_bf16_f32 v9, v11, s0
	ds_write_b16 v8, v9 offset:720
	s_waitcnt vmcnt(25)
	v_lshlrev_b32_e32 v9, 16, v106
	v_mul_f32_e32 v9, v10, v9
	v_sub_f32_e32 v11, 1.0, v81
	v_mul_f32_e32 v10, v10, v82
	v_mul_f32_e32 v11, v11, v12
	v_cvt_pk_bf16_f32 v9, v9, s0
	v_rcp_f32_e32 v12, v10
	ds_write_b16 v8, v9 offset:10080
	v_cvt_pk_bf16_f32 v9, v11, s0
	ds_write_b16 v8, v9 offset:864
	s_waitcnt vmcnt(24)
	v_lshlrev_b32_e32 v9, 16, v107
	v_mul_f32_e32 v9, v10, v9
	v_sub_f32_e32 v11, 1.0, v82
	v_mul_f32_e32 v10, v10, v83
	v_mul_f32_e32 v11, v11, v12
	v_cvt_pk_bf16_f32 v9, v9, s0
	v_rcp_f32_e32 v12, v10
	ds_write_b16 v8, v9 offset:10224
	v_cvt_pk_bf16_f32 v9, v11, s0
	ds_write_b16 v8, v9 offset:1008
	s_waitcnt vmcnt(23)
	v_lshlrev_b32_e32 v9, 16, v108
	v_mul_f32_e32 v9, v10, v9
	v_sub_f32_e32 v11, 1.0, v83
	v_mul_f32_e32 v10, v10, v84
	v_mul_f32_e32 v11, v11, v12
	v_cvt_pk_bf16_f32 v9, v9, s0
	v_rcp_f32_e32 v12, v10
	ds_write_b16 v8, v9 offset:10368
	v_cvt_pk_bf16_f32 v9, v11, s0
	ds_write_b16 v8, v9 offset:1152
	s_waitcnt vmcnt(22)
	v_lshlrev_b32_e32 v9, 16, v109
	v_mul_f32_e32 v9, v10, v9
	v_sub_f32_e32 v11, 1.0, v84
	v_mul_f32_e32 v10, v10, v85
	v_mul_f32_e32 v11, v11, v12
	v_cvt_pk_bf16_f32 v9, v9, s0
	v_rcp_f32_e32 v12, v10
	ds_write_b16 v8, v9 offset:10512
	v_cvt_pk_bf16_f32 v9, v11, s0
	ds_write_b16 v8, v9 offset:1296
	s_waitcnt vmcnt(21)
	v_lshlrev_b32_e32 v9, 16, v110
	v_mul_f32_e32 v9, v10, v9
	v_sub_f32_e32 v11, 1.0, v85
	v_mul_f32_e32 v10, v10, v86
	v_mul_f32_e32 v11, v11, v12
	v_cvt_pk_bf16_f32 v9, v9, s0
	v_rcp_f32_e32 v12, v10
	ds_write_b16 v8, v9 offset:10656
	v_cvt_pk_bf16_f32 v9, v11, s0
	ds_write_b16 v8, v9 offset:1440
	s_waitcnt vmcnt(20)
	v_lshlrev_b32_e32 v9, 16, v111
	v_mul_f32_e32 v9, v10, v9
	v_sub_f32_e32 v11, 1.0, v86
	v_mul_f32_e32 v10, v10, v87
	v_mul_f32_e32 v11, v11, v12
	v_cvt_pk_bf16_f32 v9, v9, s0
	v_rcp_f32_e32 v12, v10
	ds_write_b16 v8, v9 offset:10800
	v_cvt_pk_bf16_f32 v9, v11, s0
	ds_write_b16 v8, v9 offset:1584
	s_waitcnt vmcnt(19)
	v_lshlrev_b32_e32 v9, 16, v112
	v_mul_f32_e32 v9, v10, v9
	v_sub_f32_e32 v11, 1.0, v87
	v_mul_f32_e32 v10, v10, v88
	v_mul_f32_e32 v11, v11, v12
	v_cvt_pk_bf16_f32 v9, v9, s0
	v_rcp_f32_e32 v12, v10
	ds_write_b16 v8, v9 offset:10944
	v_cvt_pk_bf16_f32 v9, v11, s0
	ds_write_b16 v8, v9 offset:1728
	s_waitcnt vmcnt(18)
	v_lshlrev_b32_e32 v9, 16, v113
	v_mul_f32_e32 v9, v10, v9
	v_sub_f32_e32 v11, 1.0, v88
	v_mul_f32_e32 v10, v10, v89
	v_mul_f32_e32 v11, v11, v12
	v_cvt_pk_bf16_f32 v9, v9, s0
	v_rcp_f32_e32 v12, v10
	ds_write_b16 v8, v9 offset:11088
	v_cvt_pk_bf16_f32 v9, v11, s0
	ds_write_b16 v8, v9 offset:1872
	s_waitcnt vmcnt(17)
	v_lshlrev_b32_e32 v9, 16, v114
	v_mul_f32_e32 v9, v10, v9
	v_sub_f32_e32 v11, 1.0, v89
	v_mul_f32_e32 v10, v10, v90
	v_mul_f32_e32 v11, v11, v12
	v_cvt_pk_bf16_f32 v9, v9, s0
	v_rcp_f32_e32 v12, v10
	ds_write_b16 v8, v9 offset:11232
	v_cvt_pk_bf16_f32 v9, v11, s0
	ds_write_b16 v8, v9 offset:2016
	s_waitcnt vmcnt(16)
	v_lshlrev_b32_e32 v9, 16, v115
	v_mul_f32_e32 v9, v10, v9
	v_sub_f32_e32 v11, 1.0, v90
	v_mul_f32_e32 v10, v10, v91
	v_mul_f32_e32 v11, v11, v12
	v_cvt_pk_bf16_f32 v9, v9, s0
	v_rcp_f32_e32 v12, v10
	ds_write_b16 v8, v9 offset:11376
	v_cvt_pk_bf16_f32 v9, v11, s0
	ds_write_b16 v8, v9 offset:2160
	s_waitcnt vmcnt(15)
	v_lshlrev_b32_e32 v9, 16, v116
	v_mul_f32_e32 v9, v10, v9
	v_sub_f32_e32 v11, 1.0, v91
	v_mul_f32_e32 v10, v10, v92
	v_mul_f32_e32 v11, v11, v12
	v_cvt_pk_bf16_f32 v9, v9, s0
	v_rcp_f32_e32 v12, v10
	ds_write_b16 v8, v9 offset:11520
	v_cvt_pk_bf16_f32 v9, v11, s0
	ds_write_b16 v8, v9 offset:2304
	s_waitcnt vmcnt(14)
	v_lshlrev_b32_e32 v9, 16, v117
	v_mul_f32_e32 v9, v10, v9
	v_sub_f32_e32 v11, 1.0, v92
	v_mul_f32_e32 v10, v10, v93
	v_mul_f32_e32 v11, v11, v12
	v_cvt_pk_bf16_f32 v9, v9, s0
	v_rcp_f32_e32 v12, v10
	ds_write_b16 v8, v9 offset:11664
	v_cvt_pk_bf16_f32 v9, v11, s0
	ds_write_b16 v8, v9 offset:2448
	s_waitcnt vmcnt(13)
	v_lshlrev_b32_e32 v9, 16, v118
	v_mul_f32_e32 v9, v10, v9
	v_sub_f32_e32 v11, 1.0, v93
	v_mul_f32_e32 v10, v10, v94
	v_mul_f32_e32 v11, v11, v12
	v_cvt_pk_bf16_f32 v9, v9, s0
	v_rcp_f32_e32 v12, v10
	ds_write_b16 v8, v9 offset:11808
	v_cvt_pk_bf16_f32 v9, v11, s0
	ds_write_b16 v8, v9 offset:2592
	s_waitcnt vmcnt(12)
	v_lshlrev_b32_e32 v9, 16, v119
	v_mul_f32_e32 v9, v10, v9
	v_sub_f32_e32 v11, 1.0, v94
	v_mul_f32_e32 v10, v10, v95
	v_mul_f32_e32 v11, v11, v12
	v_cvt_pk_bf16_f32 v9, v9, s0
	v_rcp_f32_e32 v12, v10
	ds_write_b16 v8, v9 offset:11952
	v_cvt_pk_bf16_f32 v9, v11, s0
	ds_write_b16 v8, v9 offset:2736
	s_waitcnt vmcnt(11)
	v_lshlrev_b32_e32 v9, 16, v120
	v_mul_f32_e32 v9, v10, v9
	v_sub_f32_e32 v11, 1.0, v95
	v_mul_f32_e32 v10, v10, v96
	v_mul_f32_e32 v11, v11, v12
	v_cvt_pk_bf16_f32 v9, v9, s0
	v_rcp_f32_e32 v12, v10
	ds_write_b16 v8, v9 offset:12096
	v_cvt_pk_bf16_f32 v9, v11, s0
	ds_write_b16 v8, v9 offset:2880
	s_waitcnt vmcnt(10)
	v_lshlrev_b32_e32 v9, 16, v121
	v_mul_f32_e32 v9, v10, v9
	v_sub_f32_e32 v11, 1.0, v96
	v_mul_f32_e32 v10, v10, v97
	v_mul_f32_e32 v11, v11, v12
	v_cvt_pk_bf16_f32 v9, v9, s0
	v_rcp_f32_e32 v12, v10
	ds_write_b16 v8, v9 offset:12240
	v_cvt_pk_bf16_f32 v9, v11, s0
	ds_write_b16 v8, v9 offset:3024
	s_waitcnt vmcnt(9)
	v_lshlrev_b32_e32 v9, 16, v122
	v_mul_f32_e32 v9, v10, v9
	v_sub_f32_e32 v11, 1.0, v97
	v_mul_f32_e32 v10, v10, v98
	v_mul_f32_e32 v11, v11, v12
	v_cvt_pk_bf16_f32 v9, v9, s0
	v_rcp_f32_e32 v12, v10
	ds_write_b16 v8, v9 offset:12384
	v_cvt_pk_bf16_f32 v9, v11, s0
	ds_write_b16 v8, v9 offset:3168
	s_waitcnt vmcnt(8)
	v_lshlrev_b32_e32 v9, 16, v123
	v_mul_f32_e32 v9, v10, v9
	v_sub_f32_e32 v11, 1.0, v98
	v_mul_f32_e32 v10, v10, v99
	v_mul_f32_e32 v11, v11, v12
	v_cvt_pk_bf16_f32 v9, v9, s0
	v_rcp_f32_e32 v12, v10
	ds_write_b16 v8, v9 offset:12528
	v_cvt_pk_bf16_f32 v9, v11, s0
	ds_write_b16 v8, v9 offset:3312
	s_waitcnt vmcnt(7)
	v_lshlrev_b32_e32 v9, 16, v124
	v_mul_f32_e32 v9, v10, v9
	v_sub_f32_e32 v11, 1.0, v99
	v_mul_f32_e32 v10, v10, v100
	v_mul_f32_e32 v11, v11, v12
	v_cvt_pk_bf16_f32 v9, v9, s0
	v_rcp_f32_e32 v12, v10
	ds_write_b16 v8, v9 offset:12672
	v_cvt_pk_bf16_f32 v9, v11, s0
	ds_write_b16 v8, v9 offset:3456
	s_waitcnt vmcnt(6)
	v_lshlrev_b32_e32 v9, 16, v125
	v_mul_f32_e32 v9, v10, v9
	v_sub_f32_e32 v11, 1.0, v100
	v_mul_f32_e32 v10, v10, v101
	v_mul_f32_e32 v11, v11, v12
	v_cvt_pk_bf16_f32 v9, v9, s0
	v_rcp_f32_e32 v12, v10
	ds_write_b16 v8, v9 offset:12816
	v_cvt_pk_bf16_f32 v9, v11, s0
	ds_write_b16 v8, v9 offset:3600
	s_waitcnt vmcnt(5)
	v_lshlrev_b32_e32 v9, 16, v126
	v_mul_f32_e32 v9, v10, v9
	v_sub_f32_e32 v11, 1.0, v101
	v_mul_f32_e32 v10, v10, v102
	v_mul_f32_e32 v11, v11, v12
	v_cvt_pk_bf16_f32 v9, v9, s0
	v_rcp_f32_e32 v12, v10
	ds_write_b16 v8, v9 offset:12960
	v_cvt_pk_bf16_f32 v9, v11, s0
	ds_write_b16 v8, v9 offset:3744
	s_waitcnt vmcnt(4)
	v_lshlrev_b32_e32 v9, 16, v127
	v_mul_f32_e32 v9, v10, v9
	v_sub_f32_e32 v11, 1.0, v102
	v_mul_f32_e32 v10, v10, v103
	v_mul_f32_e32 v11, v11, v12
	v_cvt_pk_bf16_f32 v9, v9, s0
	v_rcp_f32_e32 v12, v10
	ds_write_b16 v8, v9 offset:13104
	v_cvt_pk_bf16_f32 v9, v11, s0
	ds_write_b16 v8, v9 offset:3888
	s_waitcnt vmcnt(3)
	v_lshlrev_b32_e32 v9, 16, v128
	v_mul_f32_e32 v9, v10, v9
	v_sub_f32_e32 v11, 1.0, v103
	v_mul_f32_e32 v10, v10, v104
	v_mul_f32_e32 v11, v11, v12
	v_cvt_pk_bf16_f32 v9, v9, s0
	v_rcp_f32_e32 v12, v10
	ds_write_b16 v8, v9 offset:13248
	v_cvt_pk_bf16_f32 v9, v11, s0
	ds_write_b16 v8, v9 offset:4032
	s_waitcnt vmcnt(2)
	v_lshlrev_b32_e32 v9, 16, v129
	v_mul_f32_e32 v9, v10, v9
	v_sub_f32_e32 v11, 1.0, v104
	v_mul_f32_e32 v10, v10, v105
	v_mul_f32_e32 v11, v11, v12
	v_cvt_pk_bf16_f32 v9, v9, s0
	v_rcp_f32_e32 v12, v10
	ds_write_b16 v8, v9 offset:13392
	v_cvt_pk_bf16_f32 v9, v11, s0
	ds_write_b16 v8, v9 offset:4176
	s_waitcnt vmcnt(1)
	v_lshlrev_b32_e32 v9, 16, v131
	v_mul_f32_e32 v9, v10, v9
	v_sub_f32_e32 v11, 1.0, v105
	v_mul_f32_e32 v11, v11, v12
	v_cvt_pk_bf16_f32 v9, v9, s0
	ds_write_b16 v8, v9 offset:13536
	v_cvt_pk_bf16_f32 v9, v11, s0
	ds_write_b16 v8, v9 offset:4320
	v_mul_f32_e32 v9, v10, v52
	v_rcp_f32_e32 v12, v9
	s_waitcnt vmcnt(0)
	v_lshlrev_b32_e32 v11, 16, v16
	v_mul_f32_e32 v10, v9, v11
	v_sub_f32_e32 v11, 1.0, v52
	v_mul_f32_e32 v11, v11, v12
	v_cvt_pk_bf16_f32 v10, v10, s0
	ds_write_b16 v8, v10 offset:13680
	v_cvt_pk_bf16_f32 v10, v11, s0
	ds_write_b16 v8, v10 offset:4464
	v_add_co_u32_e32 v10, vcc, s85, v6
	s_nop 1
	v_addc_co_u32_e32 v11, vcc, 0, v7, vcc
	global_load_dword v26, v[10:11], off offset:3072
	global_load_dword v27, v[10:11], off offset:2048
	global_load_dword v28, v[10:11], off offset:1024
	global_load_dword v29, v[10:11], off
	v_add_co_u32_e32 v10, vcc, s95, v6
	s_waitcnt vmcnt(3)
	v_rcp_f32_e32 v44, v26
	v_addc_co_u32_e32 v11, vcc, 0, v7, vcc
	global_load_dword v30, v[10:11], off offset:3072
	global_load_dword v31, v[10:11], off offset:2048
	global_load_dword v32, v[10:11], off offset:1024
	global_load_dword v33, v[10:11], off
	v_add_co_u32_e32 v10, vcc, s92, v6
	v_sub_f32_e32 v43, 1.0, v26
	s_nop 0
	v_addc_co_u32_e32 v11, vcc, 0, v7, vcc
	global_load_dword v34, v[10:11], off offset:3072
	global_load_dword v35, v[10:11], off offset:2048
	global_load_dword v36, v[10:11], off offset:1024
	global_load_dword v37, v[10:11], off
	v_add_co_u32_e32 v10, vcc, s81, v6
	v_mul_f32_e32 v43, v43, v44
	s_nop 0
	v_addc_co_u32_e32 v11, vcc, 0, v7, vcc
	global_load_dword v38, v[10:11], off offset:3072
	global_load_dword v39, v[10:11], off offset:2048
	global_load_dword v40, v[10:11], off offset:1024
	global_load_dword v41, v[10:11], off
	v_add_co_u32_e32 v10, vcc, s87, v6
	s_nop 1
	v_addc_co_u32_e32 v11, vcc, 0, v7, vcc
	global_load_dword v42, v[10:11], off offset:3072
	global_load_dword v23, v[10:11], off offset:2048
	global_load_dword v22, v[10:11], off offset:1024
	global_load_dword v20, v[10:11], off
	v_add_co_u32_e32 v10, vcc, s93, v6
	s_nop 1
	v_addc_co_u32_e32 v11, vcc, 0, v7, vcc
	global_load_dword v21, v[10:11], off offset:3072
	global_load_dword v19, v[10:11], off offset:2048
	global_load_dword v18, v[10:11], off offset:1024
	global_load_dword v16, v[10:11], off
	v_add_co_u32_e32 v10, vcc, s15, v6
	s_nop 1
	v_addc_co_u32_e32 v11, vcc, 0, v7, vcc
	v_add_co_u32_e32 v24, vcc, s87, v4
	global_load_dword v17, v[10:11], off offset:3072
	global_load_dword v15, v[10:11], off offset:2048
	global_load_dword v14, v[10:11], off offset:1024
	global_load_dword v13, v[10:11], off
	global_load_dword v12, v[6:7], off offset:3072
	s_nop 0
	global_load_dword v11, v[6:7], off offset:2048
	global_load_dword v10, v[6:7], off offset:1024
	s_nop 0
	global_load_dword v6, v[6:7], off
	v_addc_co_u32_e32 v25, vcc, 0, v5, vcc
	global_load_ushort v7, v[24:25], off offset:3584
	global_load_ushort v45, v[24:25], off offset:3072
	global_load_ushort v46, v[24:25], off offset:2560
	global_load_ushort v47, v[24:25], off offset:2048
	global_load_ushort v48, v[24:25], off offset:1536
	global_load_ushort v49, v[24:25], off offset:1024
	global_load_ushort v50, v[24:25], off offset:512
	global_load_ushort v51, v[24:25], off
	v_add_co_u32_e32 v24, vcc, s93, v4
	s_waitcnt vmcnt(7)
	v_lshlrev_b32_e32 v7, 16, v7
	v_addc_co_u32_e32 v25, vcc, 0, v5, vcc
	global_load_ushort v52, v[24:25], off offset:3584
	global_load_ushort v53, v[24:25], off offset:3072
	global_load_ushort v54, v[24:25], off offset:2560
	global_load_ushort v55, v[24:25], off offset:2048
	global_load_ushort v56, v[24:25], off offset:1536
	global_load_ushort v57, v[24:25], off offset:1024
	global_load_ushort v58, v[24:25], off offset:512
	global_load_ushort v59, v[24:25], off
	v_add_co_u32_e32 v24, vcc, s15, v4
	v_mul_f32_e32 v7, v26, v7
	s_nop 0
	v_addc_co_u32_e32 v25, vcc, 0, v5, vcc
	global_load_ushort v60, v[24:25], off offset:3584
	global_load_ushort v61, v[24:25], off offset:3072
	global_load_ushort v62, v[24:25], off offset:2560
	global_load_ushort v63, v[24:25], off offset:2048
	global_load_ushort v64, v[24:25], off offset:1536
	global_load_ushort v65, v[24:25], off offset:1024
	global_load_ushort v66, v[24:25], off offset:512
	s_nop 0
	global_load_ushort v24, v[24:25], off
	s_nop 0
	global_load_ushort v25, v[4:5], off offset:3584
	global_load_ushort v67, v[4:5], off offset:3072
	global_load_ushort v68, v[4:5], off offset:2560
	global_load_ushort v69, v[4:5], off offset:2048
	global_load_ushort v71, v[4:5], off offset:1536
	global_load_ushort v72, v[4:5], off offset:1024
	global_load_ushort v73, v[4:5], off offset:512
	s_nop 0
	global_load_ushort v4, v[4:5], off
	v_cvt_pk_bf16_f32 v5, v43, s0
	v_cvt_pk_bf16_f32 v44, v7, s0
	ds_write_b16 v8, v5 offset:4608
	v_mul_f32_e32 v5, v9, v7
	v_mul_f32_e32 v7, v26, v27
	v_sub_f32_e32 v26, 1.0, v27
	v_rcp_f32_e32 v27, v7
	v_cvt_pk_bf16_f32 v5, v5, s0
	ds_write_b16 v8, v5 offset:18432
	s_waitcnt vmcnt(30)
	v_lshlrev_b32_e32 v5, 16, v45
	v_mul_f32_e32 v5, v7, v5
	v_mul_f32_e32 v26, v26, v27
	v_cvt_pk_bf16_f32 v27, v5, s0
	v_mul_f32_e32 v7, v7, v28
	ds_write_b16 v8, v27 offset:13968
	v_mul_f32_e32 v5, v9, v5
	v_rcp_f32_e32 v27, v7
	v_cvt_pk_bf16_f32 v5, v5, s0
	v_cvt_pk_bf16_f32 v26, v26, s0
	ds_write_b16 v8, v5 offset:18576
	s_waitcnt vmcnt(29)
	v_lshlrev_b32_e32 v5, 16, v46
	ds_write_b16 v8, v26 offset:4752
	v_mul_f32_e32 v5, v7, v5
	v_sub_f32_e32 v26, 1.0, v28
	v_mul_f32_e32 v26, v26, v27
	v_cvt_pk_bf16_f32 v27, v5, s0
	v_mul_f32_e32 v7, v7, v29
	ds_write_b16 v8, v27 offset:14112
	v_mul_f32_e32 v5, v9, v5
	v_rcp_f32_e32 v27, v7
	v_cvt_pk_bf16_f32 v5, v5, s0
	v_cvt_pk_bf16_f32 v26, v26, s0
	ds_write_b16 v8, v5 offset:18720
	s_waitcnt vmcnt(28)
	v_lshlrev_b32_e32 v5, 16, v47
	ds_write_b16 v8, v26 offset:4896
	v_mul_f32_e32 v5, v7, v5
	v_sub_f32_e32 v26, 1.0, v29
	v_mul_f32_e32 v26, v26, v27
	v_cvt_pk_bf16_f32 v27, v5, s0
	v_mul_f32_e32 v7, v7, v30
	ds_write_b16 v8, v27 offset:14256
	v_mul_f32_e32 v5, v9, v5
	v_rcp_f32_e32 v27, v7
	v_cvt_pk_bf16_f32 v5, v5, s0
	v_cvt_pk_bf16_f32 v26, v26, s0
	ds_write_b16 v8, v5 offset:18864
	s_waitcnt vmcnt(27)
	v_lshlrev_b32_e32 v5, 16, v48
	ds_write_b16 v8, v26 offset:5040
	v_mul_f32_e32 v5, v7, v5
	v_sub_f32_e32 v26, 1.0, v30
	v_mul_f32_e32 v26, v26, v27
	v_cvt_pk_bf16_f32 v27, v5, s0
	v_mul_f32_e32 v7, v7, v31
	ds_write_b16 v8, v27 offset:14400
	v_mul_f32_e32 v5, v9, v5
	v_rcp_f32_e32 v27, v7
	v_cvt_pk_bf16_f32 v5, v5, s0
	v_cvt_pk_bf16_f32 v26, v26, s0
	ds_write_b16 v8, v5 offset:19008
	s_waitcnt vmcnt(26)
	v_lshlrev_b32_e32 v5, 16, v49
	ds_write_b16 v8, v26 offset:5184
	v_mul_f32_e32 v5, v7, v5
	v_sub_f32_e32 v26, 1.0, v31
	v_mul_f32_e32 v26, v26, v27
	v_cvt_pk_bf16_f32 v27, v5, s0
	v_mul_f32_e32 v7, v7, v32
	ds_write_b16 v8, v27 offset:14544
	v_mul_f32_e32 v5, v9, v5
	v_rcp_f32_e32 v27, v7
	v_cvt_pk_bf16_f32 v5, v5, s0
	v_cvt_pk_bf16_f32 v26, v26, s0
	ds_write_b16 v8, v5 offset:19152
	s_waitcnt vmcnt(25)
	v_lshlrev_b32_e32 v5, 16, v50
	ds_write_b16 v8, v26 offset:5328
	v_mul_f32_e32 v5, v7, v5
	v_sub_f32_e32 v26, 1.0, v32
	v_mul_f32_e32 v26, v26, v27
	v_cvt_pk_bf16_f32 v27, v5, s0
	v_mul_f32_e32 v7, v7, v33
	ds_write_b16 v8, v27 offset:14688
	v_mul_f32_e32 v5, v9, v5
	v_rcp_f32_e32 v27, v7
	v_cvt_pk_bf16_f32 v5, v5, s0
	v_cvt_pk_bf16_f32 v26, v26, s0
	ds_write_b16 v8, v5 offset:19296
	s_waitcnt vmcnt(24)
	v_lshlrev_b32_e32 v5, 16, v51
	ds_write_b16 v8, v26 offset:5472
	v_mul_f32_e32 v5, v7, v5
	v_sub_f32_e32 v26, 1.0, v33
	v_mul_f32_e32 v26, v26, v27
	v_cvt_pk_bf16_f32 v27, v5, s0
	v_mul_f32_e32 v7, v7, v34
	ds_write_b16 v8, v27 offset:14832
	v_mul_f32_e32 v5, v9, v5
	v_rcp_f32_e32 v27, v7
	v_cvt_pk_bf16_f32 v5, v5, s0
	v_cvt_pk_bf16_f32 v26, v26, s0
	ds_write_b16 v8, v5 offset:19440
	s_waitcnt vmcnt(23)
	v_lshlrev_b32_e32 v5, 16, v52
	ds_write_b16 v8, v26 offset:5616
	v_mul_f32_e32 v5, v7, v5
	v_sub_f32_e32 v26, 1.0, v34
	v_mul_f32_e32 v26, v26, v27
	v_cvt_pk_bf16_f32 v27, v5, s0
	v_mul_f32_e32 v7, v7, v35
	ds_write_b16 v8, v27 offset:14976
	v_mul_f32_e32 v5, v9, v5
	v_rcp_f32_e32 v27, v7
	v_cvt_pk_bf16_f32 v5, v5, s0
	v_cvt_pk_bf16_f32 v26, v26, s0
	ds_write_b16 v8, v5 offset:19584
	s_waitcnt vmcnt(22)
	v_lshlrev_b32_e32 v5, 16, v53
	ds_write_b16 v8, v26 offset:5760
	v_mul_f32_e32 v5, v7, v5
	v_sub_f32_e32 v26, 1.0, v35
	v_mul_f32_e32 v26, v26, v27
	v_cvt_pk_bf16_f32 v27, v5, s0
	v_mul_f32_e32 v7, v7, v36
	ds_write_b16 v8, v27 offset:15120
	v_mul_f32_e32 v5, v9, v5
	v_rcp_f32_e32 v27, v7
	v_cvt_pk_bf16_f32 v5, v5, s0
	v_cvt_pk_bf16_f32 v26, v26, s0
	ds_write_b16 v8, v5 offset:19728
	s_waitcnt vmcnt(21)
	v_lshlrev_b32_e32 v5, 16, v54
	ds_write_b16 v8, v26 offset:5904
	v_mul_f32_e32 v5, v7, v5
	v_sub_f32_e32 v26, 1.0, v36
	v_mul_f32_e32 v26, v26, v27
	v_cvt_pk_bf16_f32 v27, v5, s0
	v_mul_f32_e32 v7, v7, v37
	ds_write_b16 v8, v27 offset:15264
	v_mul_f32_e32 v5, v9, v5
	v_rcp_f32_e32 v27, v7
	v_cvt_pk_bf16_f32 v5, v5, s0
	v_cvt_pk_bf16_f32 v26, v26, s0
	ds_write_b16 v8, v5 offset:19872
	s_waitcnt vmcnt(20)
	v_lshlrev_b32_e32 v5, 16, v55
	ds_write_b16 v8, v26 offset:6048
	v_mul_f32_e32 v5, v7, v5
	v_sub_f32_e32 v26, 1.0, v37
	v_mul_f32_e32 v26, v26, v27
	v_cvt_pk_bf16_f32 v27, v5, s0
	v_mul_f32_e32 v7, v7, v38
	ds_write_b16 v8, v27 offset:15408
	v_mul_f32_e32 v5, v9, v5
	v_rcp_f32_e32 v27, v7
	v_cvt_pk_bf16_f32 v5, v5, s0
	v_cvt_pk_bf16_f32 v26, v26, s0
	ds_write_b16 v8, v5 offset:20016
	s_waitcnt vmcnt(19)
	v_lshlrev_b32_e32 v5, 16, v56
	ds_write_b16 v8, v26 offset:6192
	v_mul_f32_e32 v5, v7, v5
	v_sub_f32_e32 v26, 1.0, v38
	v_mul_f32_e32 v26, v26, v27
	v_cvt_pk_bf16_f32 v27, v5, s0
	v_mul_f32_e32 v7, v7, v39
	ds_write_b16 v8, v27 offset:15552
	v_mul_f32_e32 v5, v9, v5
	v_rcp_f32_e32 v27, v7
	v_cvt_pk_bf16_f32 v5, v5, s0
	v_cvt_pk_bf16_f32 v26, v26, s0
	ds_write_b16 v8, v5 offset:20160
	s_waitcnt vmcnt(18)
	v_lshlrev_b32_e32 v5, 16, v57
	ds_write_b16 v8, v26 offset:6336
	v_mul_f32_e32 v5, v7, v5
	v_sub_f32_e32 v26, 1.0, v39
	v_mul_f32_e32 v26, v26, v27
	v_cvt_pk_bf16_f32 v27, v5, s0
	v_mul_f32_e32 v7, v7, v40
	ds_write_b16 v8, v27 offset:15696
	v_mul_f32_e32 v5, v9, v5
	v_rcp_f32_e32 v27, v7
	v_cvt_pk_bf16_f32 v5, v5, s0
	v_cvt_pk_bf16_f32 v26, v26, s0
	ds_write_b16 v8, v5 offset:20304
	s_waitcnt vmcnt(17)
	v_lshlrev_b32_e32 v5, 16, v58
	ds_write_b16 v8, v26 offset:6480
	v_mul_f32_e32 v5, v7, v5
	v_sub_f32_e32 v26, 1.0, v40
	v_mul_f32_e32 v26, v26, v27
	v_cvt_pk_bf16_f32 v27, v5, s0
	v_mul_f32_e32 v7, v7, v41
	ds_write_b16 v8, v27 offset:15840
	v_mul_f32_e32 v5, v9, v5
	v_rcp_f32_e32 v27, v7
	v_cvt_pk_bf16_f32 v5, v5, s0
	v_cvt_pk_bf16_f32 v26, v26, s0
	ds_write_b16 v8, v5 offset:20448
	s_waitcnt vmcnt(16)
	v_lshlrev_b32_e32 v5, 16, v59
	ds_write_b16 v8, v26 offset:6624
	v_mul_f32_e32 v5, v7, v5
	v_sub_f32_e32 v26, 1.0, v41
	v_mul_f32_e32 v26, v26, v27
	v_cvt_pk_bf16_f32 v27, v5, s0
	v_mul_f32_e32 v7, v7, v42
	ds_write_b16 v8, v27 offset:15984
	v_rcp_f32_e32 v27, v7
	v_cvt_pk_bf16_f32 v26, v26, s0
	v_mul_f32_e32 v5, v9, v5
	ds_write_b16 v8, v26 offset:6768
	v_cvt_pk_bf16_f32 v5, v5, s0
	v_sub_f32_e32 v26, 1.0, v42
	ds_write_b16 v8, v5 offset:20592
	s_waitcnt vmcnt(15)
	v_lshlrev_b32_e32 v5, 16, v60
	v_mul_f32_e32 v26, v26, v27
	v_mul_f32_e32 v5, v7, v5
	v_cvt_pk_bf16_f32 v26, v26, s0
	v_mul_f32_e32 v7, v7, v23
	ds_write_b16 v8, v26 offset:6912
	v_rcp_f32_e32 v26, v7
	v_cvt_pk_bf16_f32 v27, v5, s0
	v_mul_f32_e32 v5, v9, v5
	v_cvt_pk_bf16_f32 v5, v5, s0
	v_sub_f32_e32 v23, 1.0, v23
	ds_write_b16 v8, v5 offset:20736
	s_waitcnt vmcnt(14)
	v_lshlrev_b32_e32 v5, 16, v61
	v_mul_f32_e32 v23, v23, v26
	v_mul_f32_e32 v5, v7, v5
	v_cvt_pk_bf16_f32 v23, v23, s0
	v_mul_f32_e32 v7, v7, v22
	ds_write_b16 v8, v23 offset:7056
	v_rcp_f32_e32 v23, v7
	v_cvt_pk_bf16_f32 v26, v5, s0
	v_mul_f32_e32 v5, v9, v5
	v_cvt_pk_bf16_f32 v5, v5, s0
	v_sub_f32_e32 v22, 1.0, v22
	ds_write_b16 v8, v5 offset:20880
	s_waitcnt vmcnt(13)
	v_lshlrev_b32_e32 v5, 16, v62
	v_mul_f32_e32 v22, v22, v23
	v_mul_f32_e32 v5, v7, v5
	v_cvt_pk_bf16_f32 v22, v22, s0
	v_mul_f32_e32 v7, v7, v20
	ds_write_b16 v8, v22 offset:7200
	v_rcp_f32_e32 v22, v7
	v_cvt_pk_bf16_f32 v23, v5, s0
	v_mul_f32_e32 v5, v9, v5
	v_cvt_pk_bf16_f32 v5, v5, s0
	v_sub_f32_e32 v20, 1.0, v20
	ds_write_b16 v8, v5 offset:21024
	s_waitcnt vmcnt(12)
	v_lshlrev_b32_e32 v5, 16, v63
	v_mul_f32_e32 v20, v20, v22
	v_mul_f32_e32 v5, v7, v5
	v_cvt_pk_bf16_f32 v20, v20, s0
	v_mul_f32_e32 v7, v7, v21
	ds_write_b16 v8, v20 offset:7344
	v_sub_f32_e32 v20, 1.0, v21
	v_rcp_f32_e32 v21, v7
	v_cvt_pk_bf16_f32 v22, v5, s0
	v_mul_f32_e32 v5, v9, v5
	v_cvt_pk_bf16_f32 v5, v5, s0
	ds_write_b16 v8, v5 offset:21168
	s_waitcnt vmcnt(11)
	v_lshlrev_b32_e32 v5, 16, v64
	v_mul_f32_e32 v20, v20, v21
	v_mul_f32_e32 v5, v7, v5
	v_cvt_pk_bf16_f32 v20, v20, s0
	v_mul_f32_e32 v7, v7, v19
	ds_write_b16 v8, v20 offset:7488
	v_rcp_f32_e32 v20, v7
	v_cvt_pk_bf16_f32 v21, v5, s0
	v_mul_f32_e32 v5, v9, v5
	v_cvt_pk_bf16_f32 v5, v5, s0
	v_sub_f32_e32 v19, 1.0, v19
	ds_write_b16 v8, v5 offset:21312
	s_waitcnt vmcnt(10)
	v_lshlrev_b32_e32 v5, 16, v65
	v_mul_f32_e32 v19, v19, v20
	v_mul_f32_e32 v5, v7, v5
	v_cvt_pk_bf16_f32 v19, v19, s0
	v_mul_f32_e32 v7, v7, v18
	ds_write_b16 v8, v19 offset:7632
	v_rcp_f32_e32 v19, v7
	v_cvt_pk_bf16_f32 v20, v5, s0
	v_mul_f32_e32 v5, v9, v5
	v_cvt_pk_bf16_f32 v5, v5, s0
	v_sub_f32_e32 v18, 1.0, v18
	ds_write_b16 v8, v5 offset:21456
	s_waitcnt vmcnt(9)
	v_lshlrev_b32_e32 v5, 16, v66
	v_mul_f32_e32 v18, v18, v19
	v_mul_f32_e32 v5, v7, v5
	v_cvt_pk_bf16_f32 v18, v18, s0
	v_mul_f32_e32 v7, v7, v16
	ds_write_b16 v8, v18 offset:7776
	v_rcp_f32_e32 v18, v7
	v_cvt_pk_bf16_f32 v19, v5, s0
	v_mul_f32_e32 v5, v9, v5
	v_cvt_pk_bf16_f32 v5, v5, s0
	v_sub_f32_e32 v16, 1.0, v16
	ds_write_b16 v8, v5 offset:21600
	s_waitcnt vmcnt(8)
	v_lshlrev_b32_e32 v5, 16, v24
	v_mul_f32_e32 v16, v16, v18
	v_mul_f32_e32 v5, v7, v5
	v_cvt_pk_bf16_f32 v16, v16, s0
	v_mul_f32_e32 v7, v7, v17
	ds_write_b16 v8, v16 offset:7920
	v_sub_f32_e32 v16, 1.0, v17
	v_rcp_f32_e32 v17, v7
	v_cvt_pk_bf16_f32 v18, v5, s0
	v_mul_f32_e32 v5, v9, v5
	v_cvt_pk_bf16_f32 v5, v5, s0
	ds_write_b16 v8, v5 offset:21744
	s_waitcnt vmcnt(7)
	v_lshlrev_b32_e32 v5, 16, v25
	v_mul_f32_e32 v16, v16, v17
	v_mul_f32_e32 v5, v7, v5
	v_cvt_pk_bf16_f32 v16, v16, s0
	v_mul_f32_e32 v7, v7, v15
	ds_write_b16 v8, v16 offset:8064
	v_rcp_f32_e32 v16, v7
	v_cvt_pk_bf16_f32 v17, v5, s0
	v_mul_f32_e32 v5, v9, v5
	v_cvt_pk_bf16_f32 v5, v5, s0
	v_sub_f32_e32 v15, 1.0, v15
	ds_write_b16 v8, v5 offset:21888
	s_waitcnt vmcnt(6)
	v_lshlrev_b32_e32 v5, 16, v67
	v_mul_f32_e32 v15, v15, v16
	v_mul_f32_e32 v5, v7, v5
	v_cvt_pk_bf16_f32 v15, v15, s0
	v_mul_f32_e32 v7, v7, v14
	ds_write_b16 v8, v15 offset:8208
	v_rcp_f32_e32 v15, v7
	v_cvt_pk_bf16_f32 v16, v5, s0
	v_mul_f32_e32 v5, v9, v5
	v_cvt_pk_bf16_f32 v5, v5, s0
	v_sub_f32_e32 v14, 1.0, v14
	ds_write_b16 v8, v5 offset:22032
	s_waitcnt vmcnt(5)
	v_lshlrev_b32_e32 v5, 16, v68
	v_mul_f32_e32 v14, v14, v15
	v_mul_f32_e32 v5, v7, v5
	v_cvt_pk_bf16_f32 v14, v14, s0
	v_mul_f32_e32 v7, v7, v13
	ds_write_b16 v8, v14 offset:8352
	v_rcp_f32_e32 v14, v7
	v_cvt_pk_bf16_f32 v15, v5, s0
	v_mul_f32_e32 v5, v9, v5
	v_cvt_pk_bf16_f32 v5, v5, s0
	v_sub_f32_e32 v13, 1.0, v13
	ds_write_b16 v8, v5 offset:22176
	s_waitcnt vmcnt(4)
	v_lshlrev_b32_e32 v5, 16, v69
	v_mul_f32_e32 v13, v13, v14
	v_mul_f32_e32 v5, v7, v5
	v_cvt_pk_bf16_f32 v13, v13, s0
	v_mul_f32_e32 v7, v7, v12
	ds_write_b16 v8, v13 offset:8496
	v_rcp_f32_e32 v13, v7
	v_cvt_pk_bf16_f32 v14, v5, s0
	v_mul_f32_e32 v5, v9, v5
	v_cvt_pk_bf16_f32 v5, v5, s0
	v_sub_f32_e32 v12, 1.0, v12
	ds_write_b16 v8, v5 offset:22320
	s_waitcnt vmcnt(3)
	v_lshlrev_b32_e32 v5, 16, v71
	v_mul_f32_e32 v12, v12, v13
	v_mul_f32_e32 v5, v7, v5
	v_cvt_pk_bf16_f32 v12, v12, s0
	v_mul_f32_e32 v7, v7, v11
	ds_write_b16 v8, v12 offset:8640
	v_rcp_f32_e32 v12, v7
	v_cvt_pk_bf16_f32 v13, v5, s0
	v_mul_f32_e32 v5, v9, v5
	v_cvt_pk_bf16_f32 v5, v5, s0
	v_sub_f32_e32 v11, 1.0, v11
	ds_write_b16 v8, v5 offset:22464
	s_waitcnt vmcnt(2)
	v_lshlrev_b32_e32 v5, 16, v72
	v_mul_f32_e32 v11, v11, v12
	v_mul_f32_e32 v5, v7, v5
	v_cvt_pk_bf16_f32 v11, v11, s0
	v_mul_f32_e32 v7, v7, v10
	v_cvt_pk_bf16_f32 v12, v5, s0
	ds_write_b16 v8, v11 offset:8784
	v_mul_f32_e32 v5, v9, v5
	v_rcp_f32_e32 v11, v7
	v_cvt_pk_bf16_f32 v5, v5, s0
	ds_write_b16 v8, v5 offset:22608
	s_waitcnt vmcnt(1)
	v_lshlrev_b32_e32 v5, 16, v73
	v_mul_f32_e32 v5, v7, v5
	v_sub_f32_e32 v10, 1.0, v10
	v_mul_f32_e32 v10, v10, v11
	v_cvt_pk_bf16_f32 v11, v5, s0
	v_mul_f32_e32 v5, v9, v5
	v_cvt_pk_bf16_f32 v5, v5, s0
	ds_write_b16 v8, v5 offset:22752
	s_waitcnt vmcnt(0)
	v_lshlrev_b32_e32 v4, 16, v4
	v_mul_f32_e32 v5, v7, v6
	v_mul_f32_e32 v4, v5, v4
	v_rcp_f32_e32 v5, v5
	v_sub_f32_e32 v6, 1.0, v6
	v_cvt_pk_bf16_f32 v10, v10, s0
	ds_write_b16 v8, v44 offset:13824
	v_mul_f32_e32 v5, v6, v5
	v_cvt_pk_bf16_f32 v6, v4, s0
	v_mul_f32_e32 v4, v9, v4
	v_cvt_pk_bf16_f32 v5, v5, s0
	v_cvt_pk_bf16_f32 v4, v4, s0
	v_readlane_b32 s0, v254, 46
	v_readlane_b32 s1, v254, 47
	s_add_u32 s0, s0, s40
	s_addc_u32 s1, s1, s41
	s_add_u32 s88, s0, s9
	s_addc_u32 s89, s1, 0
	ds_write_b16 v8, v27 offset:16128
	ds_write_b16 v8, v26 offset:16272
	ds_write_b16 v8, v23 offset:16416
	ds_write_b16 v8, v22 offset:16560
	ds_write_b16 v8, v21 offset:16704
	ds_write_b16 v8, v20 offset:16848
	ds_write_b16 v8, v19 offset:16992
	ds_write_b16 v8, v18 offset:17136
	ds_write_b16 v8, v17 offset:17280
	ds_write_b16 v8, v16 offset:17424
	ds_write_b16 v8, v15 offset:17568
	ds_write_b16 v8, v14 offset:17712
	ds_write_b16 v8, v13 offset:17856
	ds_write_b16 v8, v12 offset:18000
	ds_write_b16 v8, v11 offset:18144
	ds_write_b16 v8, v10 offset:8928
	ds_write_b16 v8, v6 offset:18288
	ds_write_b16 v8, v5 offset:9072
	ds_write_b16 v8, v4 offset:22896
	v_lshl_add_u64 v[2:3], s[88:89], 0, v[2:3]
	v_add_co_u32_e32 v4, vcc, s85, v2
	s_waitcnt lgkmcnt(0)
	v_and_b32_e32 v71, 31, v70
	s_nop 0
	v_addc_co_u32_e32 v5, vcc, 0, v3, vcc
	global_load_ushort v136, v[4:5], off offset:3584
	global_load_ushort v137, v[4:5], off offset:3072
	v_ashrrev_i32_e32 v72, 5, v70
	v_lshlrev_b32_e32 v74, 3, v72
	s_or_b32 s0, s4, s5
	s_mul_hi_i32 s1, s11, 0x2100
	s_add_i32 s0, s0, 4
	s_lshl_b64 s[0:1], s[0:1], 8
	v_readlane_b32 s4, v254, 56
	v_readlane_b32 s5, v254, 57
	s_add_u32 s4, s4, s0
	global_load_ushort v138, v[4:5], off offset:2560
	global_load_ushort v139, v[4:5], off offset:2048
	global_load_ushort v140, v[4:5], off offset:1536
	global_load_ushort v141, v[4:5], off offset:1024
	global_load_ushort v142, v[4:5], off offset:512
	s_nop 0
	global_load_ushort v143, v[4:5], off
	v_add_co_u32_e32 v4, vcc, s95, v2
	s_nop 1
	v_addc_co_u32_e32 v5, vcc, 0, v3, vcc
	global_load_ushort v144, v[4:5], off offset:3584
	global_load_ushort v145, v[4:5], off offset:3072
	global_load_ushort v146, v[4:5], off offset:2560
	global_load_ushort v147, v[4:5], off offset:2048
	global_load_ushort v148, v[4:5], off offset:1536
	global_load_ushort v149, v[4:5], off offset:1024
	global_load_ushort v150, v[4:5], off offset:512
	s_nop 0
	global_load_ushort v151, v[4:5], off
	v_add_co_u32_e32 v4, vcc, s92, v2
	s_nop 1
	v_addc_co_u32_e32 v5, vcc, 0, v3, vcc
	global_load_ushort v152, v[4:5], off offset:3584
	global_load_ushort v153, v[4:5], off offset:3072
	global_load_ushort v154, v[4:5], off offset:2560
	global_load_ushort v155, v[4:5], off offset:2048
	global_load_ushort v156, v[4:5], off offset:1536
	global_load_ushort v157, v[4:5], off offset:1024
	global_load_ushort v158, v[4:5], off offset:512
	s_nop 0
	global_load_ushort v159, v[4:5], off
	v_add_co_u32_e32 v4, vcc, s81, v2
	s_nop 1
	v_addc_co_u32_e32 v5, vcc, 0, v3, vcc
	global_load_ushort v160, v[4:5], off offset:3584
	global_load_ushort v161, v[4:5], off offset:3072
	global_load_ushort v162, v[4:5], off offset:2560
	global_load_ushort v163, v[4:5], off offset:2048
	global_load_ushort v164, v[4:5], off offset:1536
	global_load_ushort v165, v[4:5], off offset:1024
	global_load_ushort v166, v[4:5], off offset:512
	s_nop 0
	global_load_ushort v167, v[4:5], off
	v_add_co_u32_e32 v4, vcc, s87, v2
	s_nop 1
	v_addc_co_u32_e32 v5, vcc, 0, v3, vcc
	global_load_ushort v168, v[4:5], off offset:3584
	global_load_ushort v169, v[4:5], off offset:3072
	global_load_ushort v170, v[4:5], off offset:2560
	global_load_ushort v171, v[4:5], off offset:2048
	global_load_ushort v172, v[4:5], off offset:1536
	global_load_ushort v173, v[4:5], off offset:1024
	global_load_ushort v174, v[4:5], off offset:512
	s_nop 0
	global_load_ushort v175, v[4:5], off
	v_add_co_u32_e32 v4, vcc, s93, v2
	s_nop 1
	v_addc_co_u32_e32 v5, vcc, 0, v3, vcc
	global_load_ushort v176, v[4:5], off offset:3584
	global_load_ushort v177, v[4:5], off offset:3072
	global_load_ushort v178, v[4:5], off offset:2560
	global_load_ushort v179, v[4:5], off offset:2048
	global_load_ushort v192, v[4:5], off offset:1536
	global_load_ushort v193, v[4:5], off offset:1024
	global_load_ushort v194, v[4:5], off offset:512
	s_nop 0
	global_load_ushort v195, v[4:5], off
	v_add_co_u32_e32 v4, vcc, s15, v2
	s_nop 1
	v_addc_co_u32_e32 v5, vcc, 0, v3, vcc
	global_load_ushort v196, v[4:5], off offset:3584
	global_load_ushort v197, v[4:5], off offset:3072
	global_load_ushort v198, v[4:5], off offset:2560
	global_load_ushort v199, v[4:5], off offset:2048
	global_load_ushort v200, v[4:5], off offset:1536
	global_load_ushort v201, v[4:5], off offset:1024
	global_load_ushort v202, v[4:5], off offset:512
	s_nop 0
	global_load_ushort v203, v[4:5], off
	global_load_ushort v204, v[2:3], off offset:3584
	global_load_ushort v205, v[2:3], off offset:3072
	global_load_ushort v206, v[2:3], off offset:2560
	global_load_ushort v207, v[2:3], off offset:2048
	global_load_ushort v224, v[2:3], off offset:1536
	global_load_ushort v225, v[2:3], off offset:1024
	global_load_ushort v226, v[2:3], off offset:512
	s_nop 0
	global_load_ushort v227, v[2:3], off
	s_waitcnt vmcnt(0)
	v_lshl_or_b32 v34, v137, 16, v136
	v_lshl_or_b32 v35, v139, 16, v138
	v_lshl_or_b32 v36, v141, 16, v140
	v_lshl_or_b32 v37, v143, 16, v142
	v_lshl_or_b32 v38, v145, 16, v144
	v_lshl_or_b32 v39, v147, 16, v146
	v_lshl_or_b32 v40, v149, 16, v148
	v_lshl_or_b32 v41, v151, 16, v150
	v_lshl_or_b32 v42, v153, 16, v152
	v_lshl_or_b32 v43, v155, 16, v154
	v_lshl_or_b32 v44, v157, 16, v156
	v_lshl_or_b32 v45, v159, 16, v158
	v_lshl_or_b32 v46, v161, 16, v160
	v_lshl_or_b32 v47, v163, 16, v162
	v_lshl_or_b32 v48, v165, 16, v164
	v_lshl_or_b32 v49, v167, 16, v166
	v_lshl_or_b32 v50, v169, 16, v168
	v_lshl_or_b32 v51, v171, 16, v170
	v_lshl_or_b32 v52, v173, 16, v172
	v_lshl_or_b32 v53, v175, 16, v174
	v_lshl_or_b32 v54, v177, 16, v176
	v_lshl_or_b32 v55, v179, 16, v178
	v_lshl_or_b32 v56, v193, 16, v192
	v_lshl_or_b32 v57, v195, 16, v194
	v_lshl_or_b32 v58, v197, 16, v196
	v_lshl_or_b32 v59, v199, 16, v198
	v_lshl_or_b32 v60, v201, 16, v200
	v_lshl_or_b32 v61, v203, 16, v202
	v_lshl_or_b32 v62, v205, 16, v204
	v_lshl_or_b32 v63, v207, 16, v206
	v_lshl_or_b32 v64, v225, 16, v224
	v_lshl_or_b32 v65, v227, 16, v226
	v_mul_u32_u24_e32 v2, 0x48, v71
	v_lshl_add_u32 v75, v2, 1, s7
	v_lshl_add_u32 v73, v72, 4, v75
	ds_read_b128 v[18:21], v73 offset:4608
	ds_read_b128 v[2:5], v73 offset:9216
	ds_read_b128 v[22:25], v73 offset:13824
	ds_read_b128 v[66:69], v73 offset:18432
	ds_read_b128 v[76:79], v73
	ds_read_b128 v[80:83], v73 offset:32
	s_waitcnt lgkmcnt(3)
	v_mfma_f32_32x32x16_bf16 v[18:33], v[18:21], v[22:25], 0
	ds_read_b128 v[84:87], v73 offset:4640
	ds_read_b128 v[88:91], v73 offset:9248
	ds_read_b128 v[92:95], v73 offset:13856
	ds_read_b128 v[96:99], v73 offset:18464
	v_lshlrev_b32_e32 v72, 2, v72
	v_cmp_gt_i32_e32 vcc, v72, v71
	v_cmp_lt_i32_e64 s[40:41], v72, v71
	s_waitcnt lgkmcnt(5)
	v_mfma_f32_32x32x16_bf16 v[2:17], v[76:79], v[2:5], 0
	s_waitcnt lgkmcnt(1)
	v_mfma_f32_32x32x16_bf16 v[18:33], v[84:87], v[92:95], v[18:33]
	v_mfma_f32_32x32x16_bf16 v[2:17], v[80:83], v[88:91], v[2:17]
	ds_read_b128 v[84:87], v73 offset:64
	ds_read_b128 v[88:91], v73 offset:4672
	ds_read_b128 v[92:95], v73 offset:9280
	ds_read_b128 v[100:103], v73 offset:13888
	ds_read_b128 v[104:107], v73 offset:18496
	s_waitcnt lgkmcnt(1)
	v_mfma_f32_32x32x16_bf16 v[18:33], v[88:91], v[100:103], v[18:33]
	v_mfma_f32_32x32x16_bf16 v[2:17], v[84:87], v[92:95], v[2:17]
	ds_read_b128 v[88:91], v73 offset:96
	ds_read_b128 v[92:95], v73 offset:4704
	ds_read_b128 v[100:103], v73 offset:9312
	ds_read_b128 v[108:111], v73 offset:13920
	ds_read_b128 v[112:115], v73 offset:18528
	s_waitcnt lgkmcnt(1)
	v_mfma_f32_32x32x16_bf16 v[18:33], v[92:95], v[108:111], v[18:33]
	v_mfma_f32_32x32x16_bf16 v[2:17], v[88:91], v[100:103], v[2:17]
	s_nop 10
	v_cndmask_b32_e64 v92, v18, 0, vcc
	v_cndmask_b32_e64 v92, v92, v18, s[40:41]
	v_or_b32_e32 v18, 2, v72
	v_cmp_gt_i32_e64 s[42:43], v18, v71
	v_or_b32_e32 v18, 3, v72
	v_cmp_gt_i32_e64 s[44:45], v18, v71
	v_add_u32_e32 v18, 8, v72
	v_cmp_gt_i32_e64 s[46:47], v18, v71
	v_cmp_lt_i32_e64 s[48:49], v18, v71
	v_add_u32_e32 v18, 10, v72
	v_cmp_gt_i32_e64 s[50:51], v18, v71
	v_add_u32_e32 v18, 11, v72
	v_cmp_gt_i32_e64 s[54:55], v18, v71
	v_add_u32_e32 v18, 16, v72
	v_cmp_gt_i32_e64 s[56:57], v18, v71
	v_cmp_lt_i32_e64 s[58:59], v18, v71
	v_add_u32_e32 v18, 18, v72
	v_cmp_gt_i32_e64 s[60:61], v18, v71
	v_add_u32_e32 v18, 19, v72
	v_cmp_gt_i32_e64 s[62:63], v18, v71
	v_add_u32_e32 v18, 24, v72
	v_cndmask_b32_e64 v93, 0, v19, s[40:41]
	v_cndmask_b32_e64 v19, v22, 0, s[46:47]
	v_cmp_gt_i32_e64 s[64:65], v18, v71
	v_cmp_lt_i32_e64 s[66:67], v18, v71
	v_add_u32_e32 v18, 26, v72
	v_cndmask_b32_e64 v100, v19, v22, s[48:49]
	v_cndmask_b32_e64 v19, v26, 0, s[56:57]
	v_cmp_gt_i32_e64 s[68:69], v18, v71
	v_add_u32_e32 v18, 27, v72
	v_cndmask_b32_e64 v108, v19, v26, s[58:59]
	v_cndmask_b32_e64 v19, v30, 0, s[64:65]
	v_cmp_gt_i32_e64 s[70:71], v18, v71
	v_cndmask_b32_e64 v94, v20, 0, s[42:43]
	v_cndmask_b32_e64 v95, v21, 0, s[44:45]
	v_cndmask_b32_e64 v101, 0, v23, s[48:49]
	v_cndmask_b32_e64 v102, v24, 0, s[50:51]
	v_cndmask_b32_e64 v103, v25, 0, s[54:55]
	v_cndmask_b32_e64 v109, 0, v27, s[58:59]
	v_cndmask_b32_e64 v110, v28, 0, s[60:61]
	v_cndmask_b32_e64 v111, v29, 0, s[62:63]
	v_cndmask_b32_e64 v116, v19, v30, s[66:67]
	v_cndmask_b32_e64 v117, 0, v31, s[66:67]
	v_cndmask_b32_e64 v118, v32, 0, s[68:69]
	v_cndmask_b32_e64 v71, v33, 0, s[70:71]
	v_mfma_f32_32x32x16_bf16 v[18:33], v[76:79], v[66:69], 0
	v_mul_lo_u32 v66, v70, s14
	v_add_u32_e32 v66, s7, v66
	ds_write_b128 v66, v[34:37]
	ds_write_b128 v66, v[38:41] offset:16
	ds_write_b128 v66, v[42:45] offset:32
	ds_write_b128 v66, v[46:49] offset:48
	ds_write_b128 v66, v[50:53] offset:64
	ds_write_b128 v66, v[54:57] offset:80
	ds_write_b128 v66, v[58:61] offset:96
	ds_write_b128 v66, v[62:65] offset:112
	v_cndmask_b32_e64 v34, v2, 0, vcc
	v_cndmask_b32_e64 v2, v34, v2, s[40:41]
	v_cndmask_b32_e64 v34, v6, 0, s[46:47]
	v_cndmask_b32_e64 v6, v34, v6, s[48:49]
	v_mfma_f32_32x32x16_bf16 v[18:33], v[80:83], v[96:99], v[18:33]
	v_cndmask_b32_e64 v34, v10, 0, s[56:57]
	v_cndmask_b32_e64 v10, v34, v10, s[58:59]
	v_cndmask_b32_e64 v34, v14, 0, s[64:65]
	v_cndmask_b32_e64 v3, 0, v3, s[40:41]
	v_cndmask_b32_e64 v4, v4, 0, s[42:43]
	v_cndmask_b32_e64 v5, v5, 0, s[44:45]
	v_cndmask_b32_e64 v7, 0, v7, s[48:49]
	v_mfma_f32_32x32x16_bf16 v[18:33], v[84:87], v[104:107], v[18:33]
	v_cndmask_b32_e64 v8, v8, 0, s[50:51]
	v_cndmask_b32_e64 v9, v9, 0, s[54:55]
	v_cndmask_b32_e64 v11, 0, v11, s[58:59]
	v_cndmask_b32_e64 v12, v12, 0, s[60:61]
	v_cndmask_b32_e64 v13, v13, 0, s[62:63]
	v_cndmask_b32_e64 v14, v34, v14, s[66:67]
	v_cndmask_b32_e64 v15, 0, v15, s[66:67]
	s_waitcnt lgkmcnt(8)
	v_mfma_f32_32x32x16_bf16 v[18:33], v[88:91], v[112:115], v[18:33]
	v_cndmask_b32_e64 v16, v16, 0, s[68:69]
	v_cndmask_b32_e64 v17, v17, 0, s[70:71]
	v_add_u32_e32 v66, v75, v74
	v_cvt_pk_bf16_f32 v2, v2, v3
	v_cvt_pk_bf16_f32 v3, v4, v5
	v_cvt_pk_bf16_f32 v4, v6, v7
	v_cvt_pk_bf16_f32 v5, v8, v9
	s_nop 4
	v_cvt_pk_bf16_f32 v38, v18, v19
	v_cvt_pk_bf16_f32 v39, v20, v21
	v_cvt_pk_bf16_f32 v40, v22, v23
	v_cvt_pk_bf16_f32 v41, v24, v25
	v_cvt_pk_bf16_f32 v42, v10, v11
	v_cvt_pk_bf16_f32 v43, v12, v13
	v_cvt_pk_bf16_f32 v44, v14, v15
	v_cvt_pk_bf16_f32 v45, v16, v17
	ds_read2_b64 v[6:9], v66 offset0:8 offset1:10
	ds_read2_b64 v[10:13], v66 offset1:2
	ds_read2_b64 v[14:17], v66 offset0:4 offset1:6
	v_cvt_pk_bf16_f32 v34, v92, v93
	v_cvt_pk_bf16_f32 v35, v94, v95
	s_waitcnt lgkmcnt(1)
	v_mfma_f32_32x32x16_bf16 v[82:97], v[38:41], v[10:13], 0
	v_cvt_pk_bf16_f32 v36, v100, v101
	v_cvt_pk_bf16_f32 v37, v102, v103
	v_cvt_pk_bf16_f32 v50, v26, v27
	v_cvt_pk_bf16_f32 v51, v28, v29
	v_cvt_pk_bf16_f32 v52, v30, v31
	v_cvt_pk_bf16_f32 v53, v32, v33
	v_cvt_pk_bf16_f32 v46, v108, v109
	v_mfma_f32_32x32x16_bf16 v[82:97], v[34:37], v[6:9], v[82:97]
	v_cvt_pk_bf16_f32 v47, v110, v111
	v_cvt_pk_bf16_f32 v48, v116, v117
	v_cvt_pk_bf16_f32 v49, v118, v71
	ds_read2_b64 v[6:9], v66 offset0:12 offset1:14
	v_add_u32_e32 v122, v66, v74
	v_add_u32_e32 v123, 0x1000, v66
	v_readlane_b32 s40, v254, 56
	v_mfma_f32_32x32x16_bf16 v[18:33], v[2:5], v[10:13], 0
	v_readlane_b32 s41, v254, 57
	s_addc_u32 s5, s41, s1
	v_readlane_b32 s0, v254, 25
	v_readlane_b32 s1, v254, 26
	s_add_u32 s0, s0, s36
	s_addc_u32 s1, s1, s37
	s_add_u32 s0, s0, s10
	s_waitcnt lgkmcnt(1)
	v_mfma_f32_32x32x16_bf16 v[82:97], v[50:53], v[14:17], v[82:97]
	s_addc_u32 s1, s1, 0
	v_readlane_b32 s36, v254, 56
	v_readlane_b32 s37, v254, 57
	v_mfma_f32_32x32x16_bf16 v[18:33], v[42:45], v[14:17], v[18:33]
	s_waitcnt lgkmcnt(0)
	v_mfma_f32_32x32x16_bf16 v[82:97], v[46:49], v[6:9], v[82:97]
	ds_read_b128 v[54:57], v73 offset:18432
	ds_read_b128 v[6:9], v122 offset:23040
	ds_read_b128 v[10:13], v122 offset:23072
	ds_read_b128 v[58:61], v73 offset:9216
	ds_read_b128 v[62:65], v73 offset:9248
	ds_read_b128 v[98:101], v73 offset:18464
	s_waitcnt lgkmcnt(2)
	v_mfma_f32_32x32x16_bf16 v[18:33], v[58:61], v[6:9], v[18:33]
	v_mfma_f32_32x32x16_bf16 v[82:97], v[54:57], v[6:9], v[82:97]
	ds_read_b128 v[6:9], v122 offset:23104
	ds_read_b128 v[102:105], v73 offset:9280
	ds_read_b128 v[106:109], v73 offset:18496
	s_waitcnt lgkmcnt(4)
	v_mfma_f32_32x32x16_bf16 v[18:33], v[62:65], v[10:13], v[18:33]
	s_waitcnt lgkmcnt(3)
	v_mfma_f32_32x32x16_bf16 v[82:97], v[98:101], v[10:13], v[82:97]
	s_waitcnt lgkmcnt(1)
	v_mfma_f32_32x32x16_bf16 v[18:33], v[102:105], v[6:9], v[18:33]
	s_waitcnt lgkmcnt(0)
	v_mfma_f32_32x32x16_bf16 v[82:97], v[106:109], v[6:9], v[82:97]
	ds_read_b128 v[6:9], v122 offset:23136
	ds_read_b128 v[110:113], v73 offset:9312
	ds_read_b128 v[114:117], v73 offset:18528
	ds_read2_b64 v[66:69], v123 offset0:64 offset1:66
	ds_read2_b64 v[118:121], v123 offset0:72 offset1:74
	s_waitcnt lgkmcnt(3)
	v_mfma_f32_32x32x16_bf16 v[18:33], v[110:113], v[6:9], v[18:33]
	s_waitcnt lgkmcnt(2)
	v_mfma_f32_32x32x16_bf16 v[82:97], v[114:117], v[6:9], v[82:97]
	s_waitcnt lgkmcnt(1)
	v_mfma_f32_32x32x16_bf16 v[2:17], v[2:5], v[66:69], 0
	v_mfma_f32_32x32x16_bf16 v[66:81], v[38:41], v[66:69], 0
	s_waitcnt lgkmcnt(0)
	v_mfma_f32_32x32x16_bf16 v[66:81], v[34:37], v[118:121], v[66:81]
	ds_read2_b64 v[34:37], v123 offset0:68 offset1:70
	ds_read2_b64 v[38:41], v123 offset0:76 offset1:78
	s_waitcnt lgkmcnt(1)
	v_mfma_f32_32x32x16_bf16 v[66:81], v[50:53], v[34:37], v[66:81]
	v_mfma_f32_32x32x16_bf16 v[2:17], v[42:45], v[34:37], v[2:17]
	ds_read_b128 v[34:37], v122 offset:27648
	s_waitcnt lgkmcnt(1)
	v_mfma_f32_32x32x16_bf16 v[66:81], v[46:49], v[38:41], v[66:81]
	s_waitcnt lgkmcnt(0)
	v_mfma_f32_32x32x16_bf16 v[2:17], v[58:61], v[34:37], v[2:17]
	v_mfma_f32_32x32x16_bf16 v[66:81], v[54:57], v[34:37], v[66:81]
	ds_read_b128 v[34:37], v122 offset:27680
	s_waitcnt lgkmcnt(0)
	v_mfma_f32_32x32x16_bf16 v[2:17], v[62:65], v[34:37], v[2:17]
	v_mfma_f32_32x32x16_bf16 v[66:81], v[98:101], v[34:37], v[66:81]
	ds_read_b128 v[34:37], v122 offset:27712
	v_mov_b32_e32 v98, v223
	s_waitcnt lgkmcnt(0)
	v_mfma_f32_32x32x16_bf16 v[2:17], v[102:105], v[34:37], v[2:17]
	v_mfma_f32_32x32x16_bf16 v[66:81], v[106:109], v[34:37], v[66:81]
	ds_read_b128 v[34:37], v122 offset:27744
	s_waitcnt lgkmcnt(0)
	s_nop 0
	v_ashrrev_i32_e32 v99, 31, v98
	v_and_b32_e32 v176, 15, v98
	s_waitcnt lgkmcnt(0)
	v_mfma_f32_32x32x16_bf16 v[2:17], v[110:113], v[34:37], v[2:17]
	v_mfma_f32_32x32x16_bf16 v[66:81], v[114:117], v[34:37], v[66:81]
	v_lshlrev_b64 v[34:35], 2, v[98:99]
	v_lshl_add_u64 v[36:37], s[4:5], 0, v[34:35]
	v_add_co_u32_e32 v38, vcc, s16, v36
	global_load_dword v40, v[36:37], off
	s_nop 0
	v_addc_co_u32_e32 v39, vcc, 0, v37, vcc
	global_load_dword v41, v[38:39], off
	v_add_co_u32_e32 v38, vcc, s77, v36
	s_mov_b32 s4, 0x84000
	s_nop 0
	v_addc_co_u32_e32 v39, vcc, 0, v37, vcc
	global_load_dword v44, v[38:39], off
	v_add_co_u32_e32 v38, vcc, s24, v36
	s_nop 1
	v_addc_co_u32_e32 v39, vcc, 0, v37, vcc
	global_load_dword v45, v[38:39], off
	v_add_co_u32_e32 v38, vcc, s4, v36
	s_mov_b32 s4, 0xe7000
	s_nop 0
	v_addc_co_u32_e32 v39, vcc, 0, v37, vcc
	global_load_dword v46, v[38:39], off
	v_add_co_u32_e32 v38, vcc, s31, v36
	s_nop 1
	v_addc_co_u32_e32 v39, vcc, 0, v37, vcc
	global_load_dword v47, v[38:39], off
	v_add_co_u32_e32 v38, vcc, s38, v36
	s_waitcnt vmcnt(0)
	v_cvt_pk_bf16_f32 v144, v46, v47
	v_addc_co_u32_e32 v39, vcc, 0, v37, vcc
	global_load_dword v49, v[38:39], off
	v_add_co_u32_e32 v38, vcc, s4, v36
	s_mov_b32 s4, 0x108000
	s_nop 0
	v_addc_co_u32_e32 v39, vcc, 0, v37, vcc
	global_load_dword v52, v[38:39], off
	v_add_co_u32_e32 v38, vcc, s4, v36
	s_mov_b32 s4, 0x129000
	s_nop 0
	v_addc_co_u32_e32 v39, vcc, 0, v37, vcc
	global_load_dword v53, v[38:39], off
	v_add_co_u32_e32 v38, vcc, s4, v36
	s_mov_b32 s4, 0x14a000
	s_nop 0
	v_addc_co_u32_e32 v39, vcc, 0, v37, vcc
	global_load_dword v56, v[38:39], off
	v_add_co_u32_e32 v38, vcc, s4, v36
	s_mov_b32 s4, 0x16b000
	s_nop 0
	v_addc_co_u32_e32 v39, vcc, 0, v37, vcc
	global_load_dword v58, v[38:39], off
	v_add_co_u32_e32 v38, vcc, s4, v36
	s_mov_b32 s4, 0x18c000
	s_nop 0
	v_addc_co_u32_e32 v39, vcc, 0, v37, vcc
	global_load_dword v60, v[38:39], off
	v_add_co_u32_e32 v38, vcc, s4, v36
	s_mov_b32 s4, 0x1ad000
	s_nop 0
	v_addc_co_u32_e32 v39, vcc, 0, v37, vcc
	global_load_dword v62, v[38:39], off
	v_add_co_u32_e32 v38, vcc, s4, v36
	s_mov_b32 s4, 0x1ce000
	s_nop 0
	v_addc_co_u32_e32 v39, vcc, 0, v37, vcc
	global_load_dword v64, v[38:39], off
	v_add_co_u32_e32 v38, vcc, s4, v36
	s_mov_b32 s4, 0x1ef000
	s_nop 0
	v_addc_co_u32_e32 v39, vcc, 0, v37, vcc
	global_load_dword v100, v[38:39], off
	v_add_co_u32_e32 v38, vcc, s4, v36
	s_mov_b32 s4, 0x6b000
	s_nop 0
	v_addc_co_u32_e32 v39, vcc, 0, v37, vcc
	global_load_dword v102, v[38:39], off
	v_add_co_u32_e32 v38, vcc, s97, v36
	s_waitcnt vmcnt(8)
	v_cvt_pk_bf16_f32 v145, v49, v52
	v_addc_co_u32_e32 v39, vcc, 0, v37, vcc
	global_load_dword v48, v[38:39], off offset:1024
	v_add_co_u32_e32 v38, vcc, s17, v36
	s_waitcnt vmcnt(3)
	v_cvt_pk_bf16_f32 v46, v62, v64
	v_addc_co_u32_e32 v39, vcc, 0, v37, vcc
	global_load_dword v50, v[38:39], off offset:1024
	v_add_co_u32_e32 v38, vcc, s20, v36
	s_waitcnt vmcnt(2)
	v_cvt_pk_bf16_f32 v47, v100, v102
	v_addc_co_u32_e32 v39, vcc, 0, v37, vcc
	global_load_dword v51, v[38:39], off offset:1024
	v_add_co_u32_e32 v38, vcc, s4, v36
	s_mov_b32 s4, 0x8c000
	s_nop 0
	v_addc_co_u32_e32 v39, vcc, 0, v37, vcc
	global_load_dword v54, v[38:39], off offset:1024
	v_add_co_u32_e32 v38, vcc, s4, v36
	s_mov_b32 s4, 0xef000
	s_nop 0
	v_addc_co_u32_e32 v39, vcc, 0, v37, vcc
	global_load_dword v55, v[38:39], off offset:1024
	v_add_co_u32_e32 v38, vcc, s33, v36
	s_nop 1
	v_addc_co_u32_e32 v39, vcc, 0, v37, vcc
	global_load_dword v57, v[38:39], off offset:1024
	v_add_co_u32_e32 v38, vcc, s39, v36
	s_nop 1
	v_addc_co_u32_e32 v39, vcc, 0, v37, vcc
	global_load_dword v59, v[38:39], off offset:1024
	v_add_co_u32_e32 v38, vcc, s4, v36
	s_mov_b32 s4, 0x110000
	s_nop 0
	v_addc_co_u32_e32 v39, vcc, 0, v37, vcc
	global_load_dword v61, v[38:39], off offset:1024
	v_add_co_u32_e32 v38, vcc, s4, v36
	s_mov_b32 s4, 0x131000
	s_nop 0
	v_addc_co_u32_e32 v39, vcc, 0, v37, vcc
	global_load_dword v63, v[38:39], off offset:1024
	v_add_co_u32_e32 v38, vcc, s4, v36
	s_mov_b32 s4, 0x152000
	s_nop 0
	v_addc_co_u32_e32 v39, vcc, 0, v37, vcc
	global_load_dword v65, v[38:39], off offset:1024
	v_add_co_u32_e32 v38, vcc, s4, v36
	s_mov_b32 s4, 0x173000
	s_nop 0
	v_addc_co_u32_e32 v39, vcc, 0, v37, vcc
	global_load_dword v101, v[38:39], off offset:1024
	v_add_co_u32_e32 v38, vcc, s4, v36
	s_mov_b32 s4, 0x194000
	s_nop 0
	v_addc_co_u32_e32 v39, vcc, 0, v37, vcc
	global_load_dword v103, v[38:39], off offset:1024
	v_add_co_u32_e32 v38, vcc, s4, v36
	s_mov_b32 s4, 0x1b5000
	s_nop 0
	v_addc_co_u32_e32 v39, vcc, 0, v37, vcc
	global_load_dword v104, v[38:39], off offset:1024
	v_add_co_u32_e32 v38, vcc, s4, v36
	s_mov_b32 s4, 0x1d6000
	s_nop 0
	v_addc_co_u32_e32 v39, vcc, 0, v37, vcc
	global_load_dword v105, v[38:39], off offset:1024
	v_add_co_u32_e32 v38, vcc, s4, v36
	s_mov_b32 s4, 0x1f7000
	s_nop 0
	v_addc_co_u32_e32 v39, vcc, 0, v37, vcc
	global_load_dword v106, v[38:39], off offset:1024
	v_add_co_u32_e32 v38, vcc, s4, v36
	s_mov_b32 s4, 0x73000
	s_nop 0
	v_addc_co_u32_e32 v39, vcc, 0, v37, vcc
	global_load_dword v107, v[38:39], off offset:1024
	v_add_co_u32_e32 v38, vcc, s94, v36
	s_waitcnt vmcnt(4)
	v_cvt_pk_bf16_f32 v49, v101, v103
	v_addc_co_u32_e32 v39, vcc, 0, v37, vcc
	global_load_dword v108, v[38:39], off offset:2048
	v_add_co_u32_e32 v38, vcc, s18, v36
	s_nop 1
	v_addc_co_u32_e32 v39, vcc, 0, v37, vcc
	global_load_dword v109, v[38:39], off offset:2048
	v_add_co_u32_e32 v38, vcc, s21, v36
	s_nop 1
	v_addc_co_u32_e32 v39, vcc, 0, v37, vcc
	global_load_dword v110, v[38:39], off offset:2048
	v_add_co_u32_e32 v38, vcc, s4, v36
	s_mov_b32 s4, 0x94000
	s_nop 0
	v_addc_co_u32_e32 v39, vcc, 0, v37, vcc
	global_load_dword v111, v[38:39], off offset:2048
	v_add_co_u32_e32 v38, vcc, s4, v36
	s_mov_b32 s4, 0xf7000
	s_nop 0
	v_addc_co_u32_e32 v39, vcc, 0, v37, vcc
	global_load_dword v112, v[38:39], off offset:2048
	v_add_co_u32_e32 v38, vcc, s34, v36
	s_nop 1
	v_addc_co_u32_e32 v39, vcc, 0, v37, vcc
	global_load_dword v113, v[38:39], off offset:2048
	v_add_co_u32_e32 v38, vcc, s52, v36
	s_nop 1
	v_addc_co_u32_e32 v39, vcc, 0, v37, vcc
	global_load_dword v114, v[38:39], off offset:2048
	v_add_co_u32_e32 v38, vcc, s4, v36
	s_mov_b32 s4, 0x118000
	s_nop 0
	v_addc_co_u32_e32 v39, vcc, 0, v37, vcc
	global_load_dword v115, v[38:39], off offset:2048
	v_add_co_u32_e32 v38, vcc, s4, v36
	s_mov_b32 s4, 0x139000
	s_nop 0
	v_addc_co_u32_e32 v39, vcc, 0, v37, vcc
	global_load_dword v116, v[38:39], off offset:2048
	v_add_co_u32_e32 v38, vcc, s4, v36
	s_mov_b32 s4, 0x15a000
	s_nop 0
	v_addc_co_u32_e32 v39, vcc, 0, v37, vcc
	global_load_dword v117, v[38:39], off offset:2048
	v_add_co_u32_e32 v38, vcc, s4, v36
	s_mov_b32 s4, 0x17b000
	s_nop 0
	v_addc_co_u32_e32 v39, vcc, 0, v37, vcc
	global_load_dword v118, v[38:39], off offset:2048
	v_add_co_u32_e32 v38, vcc, s4, v36
	s_mov_b32 s4, 0x19c000
	s_nop 0
	v_addc_co_u32_e32 v39, vcc, 0, v37, vcc
	global_load_dword v119, v[38:39], off offset:2048
	v_add_co_u32_e32 v38, vcc, s4, v36
	s_mov_b32 s4, 0x1bd000
	s_nop 0
	v_addc_co_u32_e32 v39, vcc, 0, v37, vcc
	global_load_dword v120, v[38:39], off offset:2048
	v_add_co_u32_e32 v38, vcc, s4, v36
	s_mov_b32 s4, 0x1de000
	s_nop 0
	v_addc_co_u32_e32 v39, vcc, 0, v37, vcc
	global_load_dword v121, v[38:39], off offset:2048
	v_add_co_u32_e32 v38, vcc, s4, v36
	s_mov_b32 s4, 0x1ff000
	s_nop 0
	v_addc_co_u32_e32 v39, vcc, 0, v37, vcc
	global_load_dword v122, v[38:39], off offset:2048
	v_add_co_u32_e32 v38, vcc, s4, v36
	s_mov_b32 s4, 0x5a000
	s_nop 0
	v_addc_co_u32_e32 v39, vcc, 0, v37, vcc
	global_load_dword v123, v[38:39], off offset:2048
	v_add_co_u32_e32 v38, vcc, s96, v36
	s_nop 1
	v_addc_co_u32_e32 v39, vcc, 0, v37, vcc
	global_load_dword v124, v[38:39], off offset:3072
	v_add_co_u32_e32 v38, vcc, s19, v36
	s_nop 1
	v_addc_co_u32_e32 v39, vcc, 0, v37, vcc
	global_load_dword v125, v[38:39], off offset:3072
	v_add_co_u32_e32 v38, vcc, s4, v36
	s_mov_b32 s4, 0x7b000
	s_nop 0
	v_addc_co_u32_e32 v39, vcc, 0, v37, vcc
	global_load_dword v126, v[38:39], off offset:3072
	v_add_co_u32_e32 v38, vcc, s4, v36
	s_mov_b32 s4, 0x9c000
	s_nop 0
	v_addc_co_u32_e32 v39, vcc, 0, v37, vcc
	global_load_dword v127, v[38:39], off offset:3072
	v_add_co_u32_e32 v38, vcc, s4, v36
	s_mov_b32 s4, 0xff000
	s_nop 0
	v_addc_co_u32_e32 v39, vcc, 0, v37, vcc
	global_load_dword v128, v[38:39], off offset:3072
	v_add_co_u32_e32 v38, vcc, s35, v36
	s_nop 1
	v_addc_co_u32_e32 v39, vcc, 0, v37, vcc
	global_load_dword v129, v[38:39], off offset:3072
	v_add_co_u32_e32 v38, vcc, s53, v36
	s_nop 1
	v_addc_co_u32_e32 v39, vcc, 0, v37, vcc
	global_load_dword v131, v[38:39], off offset:3072
	v_add_co_u32_e32 v38, vcc, s4, v36
	s_nop 1
	v_addc_co_u32_e32 v39, vcc, 0, v37, vcc
	global_load_dword v132, v[38:39], off offset:3072
	v_add_co_u32_e32 v38, vcc, s30, v36
	s_nop 1
	v_addc_co_u32_e32 v39, vcc, 0, v37, vcc
	global_load_dword v133, v[38:39], off offset:3072
	v_add_co_u32_e32 v38, vcc, s29, v36
	s_nop 1
	v_addc_co_u32_e32 v39, vcc, 0, v37, vcc
	global_load_dword v134, v[38:39], off offset:3072
	v_add_co_u32_e32 v38, vcc, s28, v36
	s_nop 1
	v_addc_co_u32_e32 v39, vcc, 0, v37, vcc
	global_load_dword v135, v[38:39], off offset:3072
	v_add_co_u32_e32 v38, vcc, s27, v36
	s_nop 1
	v_addc_co_u32_e32 v39, vcc, 0, v37, vcc
	global_load_dword v136, v[38:39], off offset:3072
	v_add_co_u32_e32 v38, vcc, s26, v36
	s_nop 1
	v_addc_co_u32_e32 v39, vcc, 0, v37, vcc
	global_load_dword v137, v[38:39], off offset:3072
	v_add_co_u32_e32 v38, vcc, s25, v36
	s_nop 1
	v_addc_co_u32_e32 v39, vcc, 0, v37, vcc
	global_load_dword v138, v[38:39], off offset:3072
	v_add_co_u32_e32 v38, vcc, s23, v36
	s_nop 1
	v_addc_co_u32_e32 v39, vcc, 0, v37, vcc
	v_add_co_u32_e32 v36, vcc, s22, v36
	global_load_dword v139, v[38:39], off offset:3072
	s_nop 0
	v_addc_co_u32_e32 v37, vcc, 0, v37, vcc
	global_load_dword v140, v[36:37], off offset:3072
	v_lshl_add_u64 v[38:39], s[0:1], 0, v[34:35]
	v_add_co_u32_e32 v42, vcc, s15, v38
	v_lshlrev_b64 v[34:35], 1, v[98:99]
	s_nop 0
	v_addc_co_u32_e32 v43, vcc, 0, v39, vcc
	v_add_co_u32_e32 v142, vcc, s93, v38
	global_load_dword v99, v[38:39], off
	global_load_dword v141, v[38:39], off offset:1024
	global_load_dword v146, v[38:39], off offset:2048
	global_load_dword v147, v[38:39], off offset:3072
	v_addc_co_u32_e32 v143, vcc, 0, v39, vcc
	global_load_dword v148, v[142:143], off offset:-4096
	global_load_dword v149, v[42:43], off offset:1024
	global_load_dword v150, v[42:43], off offset:2048
	global_load_dword v151, v[42:43], off offset:3072
	global_load_dword v152, v[142:143], off
	global_load_dword v153, v[142:143], off offset:1024
	global_load_dword v154, v[142:143], off offset:2048
	global_load_dword v155, v[142:143], off offset:3072
	v_add_co_u32_e32 v42, vcc, s87, v38
	v_lshl_add_u64 v[36:37], s[2:3], 0, v[34:35]
	s_nop 0
	v_addc_co_u32_e32 v43, vcc, 0, v39, vcc
	v_add_co_u32_e32 v142, vcc, s81, v38
	v_lshl_add_u64 v[34:35], s[88:89], 0, v[34:35]
	s_nop 0
	v_addc_co_u32_e32 v143, vcc, 0, v39, vcc
	global_load_dword v156, v[142:143], off offset:-4096
	global_load_dword v157, v[42:43], off offset:1024
	global_load_dword v158, v[42:43], off offset:2048
	global_load_dword v159, v[42:43], off offset:3072
	global_load_dword v160, v[142:143], off
	global_load_dword v161, v[142:143], off offset:1024
	global_load_dword v162, v[142:143], off offset:2048
	global_load_dword v163, v[142:143], off offset:3072
	v_add_co_u32_e32 v42, vcc, s92, v38
	s_nop 1
	v_addc_co_u32_e32 v43, vcc, 0, v39, vcc
	v_add_co_u32_e32 v142, vcc, s95, v38
	s_nop 1
	v_addc_co_u32_e32 v143, vcc, 0, v39, vcc
	global_load_dword v164, v[142:143], off offset:-4096
	global_load_dword v165, v[42:43], off offset:1024
	global_load_dword v166, v[42:43], off offset:2048
	global_load_dword v167, v[42:43], off offset:3072
	global_load_dword v168, v[142:143], off
	global_load_dword v169, v[142:143], off offset:1024
	global_load_dword v170, v[142:143], off offset:2048
	global_load_dword v171, v[142:143], off offset:3072
	v_add_co_u32_e32 v142, vcc, s85, v38
	s_nop 1
	v_addc_co_u32_e32 v143, vcc, 0, v39, vcc
	v_add_co_u32_e32 v42, vcc, s97, v38
	s_nop 1
	v_addc_co_u32_e32 v43, vcc, 0, v39, vcc
	global_load_dword v172, v[42:43], off offset:-4096
	global_load_dword v173, v[142:143], off offset:1024
	global_load_dword v174, v[142:143], off offset:2048
	global_load_dword v175, v[142:143], off offset:3072
	v_and_b32_e32 v142, 0x7ffffff0, v98
	v_lshlrev_b32_e32 v177, 1, v142
	v_cvt_pk_bf16_f32 v142, v40, v41
	v_mul_u32_u24_e32 v40, 0x90, v176
	v_cvt_pk_bf16_f32 v143, v44, v45
	v_cvt_pk_bf16_f32 v44, v53, v56
	v_cvt_pk_bf16_f32 v45, v58, v60
	v_add3_u32 v56, s7, v177, v40
	global_load_ushort v58, v[36:37], off
	global_load_ushort v60, v[36:37], off offset:512
	global_load_ushort v62, v[36:37], off offset:1024
	global_load_ushort v64, v[36:37], off offset:1536
	global_load_ushort v100, v[36:37], off offset:2048
	global_load_ushort v102, v[36:37], off offset:2560
	global_load_ushort v176, v[36:37], off offset:3072
	global_load_ushort v177, v[36:37], off offset:3584
	v_add_co_u32_e32 v40, vcc, s15, v36
	s_nop 1
	v_addc_co_u32_e32 v41, vcc, 0, v37, vcc
	v_add_co_u32_e32 v52, vcc, s93, v36
	s_nop 1
	v_addc_co_u32_e32 v53, vcc, 0, v37, vcc
	global_load_ushort v178, v[52:53], off offset:-4096
	global_load_ushort v179, v[40:41], off offset:512
	global_load_ushort v180, v[40:41], off offset:1024
	global_load_ushort v181, v[40:41], off offset:1536
	global_load_ushort v186, v[40:41], off offset:2048
	global_load_ushort v187, v[40:41], off offset:2560
	global_load_ushort v189, v[40:41], off offset:3072
	global_load_ushort v192, v[40:41], off offset:3584
	global_load_ushort v193, v[52:53], off
	global_load_ushort v194, v[52:53], off offset:512
	global_load_ushort v195, v[52:53], off offset:1024
	global_load_ushort v196, v[52:53], off offset:1536
	global_load_ushort v197, v[52:53], off offset:2048
	global_load_ushort v198, v[52:53], off offset:2560
	global_load_ushort v199, v[52:53], off offset:3072
	global_load_ushort v200, v[52:53], off offset:3584
	v_add_co_u32_e32 v52, vcc, s87, v36
	s_nop 1
	v_addc_co_u32_e32 v53, vcc, 0, v37, vcc
	v_add_co_u32_e32 v40, vcc, s81, v36
	s_nop 1
	v_addc_co_u32_e32 v41, vcc, 0, v37, vcc
	global_load_ushort v201, v[40:41], off offset:-4096
	global_load_ushort v202, v[52:53], off offset:512
	global_load_ushort v203, v[52:53], off offset:1024
	global_load_ushort v204, v[52:53], off offset:1536
	global_load_ushort v205, v[52:53], off offset:2048
	global_load_ushort v206, v[52:53], off offset:2560
	global_load_ushort v207, v[52:53], off offset:3072
	s_nop 0
	global_load_ushort v52, v[52:53], off offset:3584
	ds_write_b128 v56, v[142:145] offset:23040
	ds_write_b128 v56, v[44:47] offset:23056
	v_cvt_pk_bf16_f32 v44, v48, v50
	v_cvt_pk_bf16_f32 v45, v51, v54
	v_cvt_pk_bf16_f32 v46, v55, v57
	v_cvt_pk_bf16_f32 v47, v59, v61
	v_cvt_pk_bf16_f32 v48, v63, v65
	s_waitcnt vmcnt(62)
	v_cvt_pk_bf16_f32 v50, v104, v105
	v_cvt_pk_bf16_f32 v51, v106, v107
	ds_write_b128 v56, v[44:47] offset:25344
	ds_write_b128 v56, v[48:51] offset:25360
	v_cvt_pk_bf16_f32 v44, v108, v109
	v_cvt_pk_bf16_f32 v45, v110, v111
	v_cvt_pk_bf16_f32 v46, v112, v113
	v_cvt_pk_bf16_f32 v47, v114, v115
	v_cvt_pk_bf16_f32 v48, v116, v117
	v_cvt_pk_bf16_f32 v49, v118, v119
	v_cvt_pk_bf16_f32 v50, v120, v121
	v_cvt_pk_bf16_f32 v51, v122, v123
	ds_write_b128 v56, v[44:47] offset:27648
	ds_write_b128 v56, v[48:51] offset:27664
	v_cvt_pk_bf16_f32 v44, v124, v125
	v_cvt_pk_bf16_f32 v45, v126, v127
	v_cvt_pk_bf16_f32 v46, v128, v129
	v_cvt_pk_bf16_f32 v47, v131, v132
	v_cvt_pk_bf16_f32 v48, v133, v134
	v_cvt_pk_bf16_f32 v49, v135, v136
	v_cvt_pk_bf16_f32 v50, v137, v138
	v_cvt_pk_bf16_f32 v51, v139, v140
	ds_write_b128 v56, v[44:47] offset:29952
	ds_write_b128 v56, v[48:51] offset:29968
	v_rcp_f32_e32 v47, v99
	v_sub_f32_e32 v46, 1.0, v99
	v_lshl_add_u32 v44, v98, 1, s7
	v_mul_f32_e32 v46, v46, v47
	v_sub_f32_e32 v47, 1.0, v141
	s_waitcnt vmcnt(31)
	v_lshlrev_b32_e32 v45, 16, v58
	v_mul_f32_e32 v45, v99, v45
	v_cvt_pk_bf16_f32 v45, v45, s0
	ds_write_b16 v44, v45 offset:9216
	v_cvt_pk_bf16_f32 v45, v46, s0
	v_mul_f32_e32 v46, v99, v141
	v_rcp_f32_e32 v48, v46
	ds_write_b16 v44, v45
	s_waitcnt vmcnt(30)
	v_lshlrev_b32_e32 v45, 16, v60
	v_mul_f32_e32 v45, v46, v45
	v_mul_f32_e32 v46, v46, v146
	v_mul_f32_e32 v47, v47, v48
	v_cvt_pk_bf16_f32 v45, v45, s0
	v_rcp_f32_e32 v48, v46
	ds_write_b16 v44, v45 offset:9360
	v_cvt_pk_bf16_f32 v45, v47, s0
	ds_write_b16 v44, v45 offset:144
	s_waitcnt vmcnt(29)
	v_lshlrev_b32_e32 v45, 16, v62
	v_mul_f32_e32 v45, v46, v45
	v_sub_f32_e32 v47, 1.0, v146
	v_mul_f32_e32 v46, v46, v147
	v_mul_f32_e32 v47, v47, v48
	v_cvt_pk_bf16_f32 v45, v45, s0
	v_rcp_f32_e32 v48, v46
	ds_write_b16 v44, v45 offset:9504
	v_cvt_pk_bf16_f32 v45, v47, s0
	ds_write_b16 v44, v45 offset:288
	s_waitcnt vmcnt(28)
	v_lshlrev_b32_e32 v45, 16, v64
	v_mul_f32_e32 v45, v46, v45
	v_sub_f32_e32 v47, 1.0, v147
	v_mul_f32_e32 v46, v46, v148
	v_mul_f32_e32 v47, v47, v48
	v_cvt_pk_bf16_f32 v45, v45, s0
	v_rcp_f32_e32 v48, v46
	ds_write_b16 v44, v45 offset:9648
	v_cvt_pk_bf16_f32 v45, v47, s0
	ds_write_b16 v44, v45 offset:432
	s_waitcnt vmcnt(27)
	v_lshlrev_b32_e32 v45, 16, v100
	v_mul_f32_e32 v45, v46, v45
	v_sub_f32_e32 v47, 1.0, v148
	v_mul_f32_e32 v46, v46, v149
	v_mul_f32_e32 v47, v47, v48
	v_cvt_pk_bf16_f32 v45, v45, s0
	v_rcp_f32_e32 v48, v46
	ds_write_b16 v44, v45 offset:9792
	v_cvt_pk_bf16_f32 v45, v47, s0
	ds_write_b16 v44, v45 offset:576
	s_waitcnt vmcnt(26)
	v_lshlrev_b32_e32 v45, 16, v102
	v_mul_f32_e32 v45, v46, v45
	v_sub_f32_e32 v47, 1.0, v149
	v_mul_f32_e32 v46, v46, v150
	v_mul_f32_e32 v47, v47, v48
	v_cvt_pk_bf16_f32 v45, v45, s0
	v_rcp_f32_e32 v48, v46
	ds_write_b16 v44, v45 offset:9936
	v_cvt_pk_bf16_f32 v45, v47, s0
	ds_write_b16 v44, v45 offset:720
	s_waitcnt vmcnt(25)
	v_lshlrev_b32_e32 v45, 16, v176
	v_mul_f32_e32 v45, v46, v45
	v_sub_f32_e32 v47, 1.0, v150
	v_mul_f32_e32 v46, v46, v151
	v_mul_f32_e32 v47, v47, v48
	v_cvt_pk_bf16_f32 v45, v45, s0
	v_rcp_f32_e32 v48, v46
	ds_write_b16 v44, v45 offset:10080
	v_cvt_pk_bf16_f32 v45, v47, s0
	ds_write_b16 v44, v45 offset:864
	s_waitcnt vmcnt(24)
	v_lshlrev_b32_e32 v45, 16, v177
	v_mul_f32_e32 v45, v46, v45
	v_sub_f32_e32 v47, 1.0, v151
	v_mul_f32_e32 v46, v46, v152
	v_mul_f32_e32 v47, v47, v48
	v_cvt_pk_bf16_f32 v45, v45, s0
	v_rcp_f32_e32 v48, v46
	ds_write_b16 v44, v45 offset:10224
	v_cvt_pk_bf16_f32 v45, v47, s0
	ds_write_b16 v44, v45 offset:1008
	s_waitcnt vmcnt(23)
	v_lshlrev_b32_e32 v45, 16, v178
	v_mul_f32_e32 v45, v46, v45
	v_sub_f32_e32 v47, 1.0, v152
	v_mul_f32_e32 v46, v46, v153
	v_mul_f32_e32 v47, v47, v48
	v_cvt_pk_bf16_f32 v45, v45, s0
	v_rcp_f32_e32 v48, v46
	ds_write_b16 v44, v45 offset:10368
	v_cvt_pk_bf16_f32 v45, v47, s0
	ds_write_b16 v44, v45 offset:1152
	s_waitcnt vmcnt(22)
	v_lshlrev_b32_e32 v45, 16, v179
	v_mul_f32_e32 v45, v46, v45
	v_sub_f32_e32 v47, 1.0, v153
	v_mul_f32_e32 v46, v46, v154
	v_mul_f32_e32 v47, v47, v48
	v_cvt_pk_bf16_f32 v45, v45, s0
	v_rcp_f32_e32 v48, v46
	ds_write_b16 v44, v45 offset:10512
	v_cvt_pk_bf16_f32 v45, v47, s0
	ds_write_b16 v44, v45 offset:1296
	s_waitcnt vmcnt(21)
	v_lshlrev_b32_e32 v45, 16, v180
	v_mul_f32_e32 v45, v46, v45
	v_sub_f32_e32 v47, 1.0, v154
	v_mul_f32_e32 v46, v46, v155
	v_mul_f32_e32 v47, v47, v48
	v_cvt_pk_bf16_f32 v45, v45, s0
	v_rcp_f32_e32 v48, v46
	ds_write_b16 v44, v45 offset:10656
	v_cvt_pk_bf16_f32 v45, v47, s0
	ds_write_b16 v44, v45 offset:1440
	s_waitcnt vmcnt(20)
	v_lshlrev_b32_e32 v45, 16, v181
	v_mul_f32_e32 v45, v46, v45
	v_sub_f32_e32 v47, 1.0, v155
	v_mul_f32_e32 v46, v46, v156
	v_mul_f32_e32 v47, v47, v48
	v_cvt_pk_bf16_f32 v45, v45, s0
	v_rcp_f32_e32 v48, v46
	ds_write_b16 v44, v45 offset:10800
	v_cvt_pk_bf16_f32 v45, v47, s0
	ds_write_b16 v44, v45 offset:1584
	s_waitcnt vmcnt(19)
	v_lshlrev_b32_e32 v45, 16, v186
	v_mul_f32_e32 v45, v46, v45
	v_sub_f32_e32 v47, 1.0, v156
	v_mul_f32_e32 v46, v46, v157
	v_mul_f32_e32 v47, v47, v48
	v_cvt_pk_bf16_f32 v45, v45, s0
	v_rcp_f32_e32 v48, v46
	ds_write_b16 v44, v45 offset:10944
	v_cvt_pk_bf16_f32 v45, v47, s0
	ds_write_b16 v44, v45 offset:1728
	s_waitcnt vmcnt(18)
	v_lshlrev_b32_e32 v45, 16, v187
	v_mul_f32_e32 v45, v46, v45
	v_sub_f32_e32 v47, 1.0, v157
	v_mul_f32_e32 v46, v46, v158
	v_mul_f32_e32 v47, v47, v48
	v_cvt_pk_bf16_f32 v45, v45, s0
	v_rcp_f32_e32 v48, v46
	ds_write_b16 v44, v45 offset:11088
	v_cvt_pk_bf16_f32 v45, v47, s0
	ds_write_b16 v44, v45 offset:1872
	s_waitcnt vmcnt(17)
	v_lshlrev_b32_e32 v45, 16, v189
	v_mul_f32_e32 v45, v46, v45
	v_sub_f32_e32 v47, 1.0, v158
	v_mul_f32_e32 v46, v46, v159
	v_mul_f32_e32 v47, v47, v48
	v_cvt_pk_bf16_f32 v45, v45, s0
	v_rcp_f32_e32 v48, v46
	ds_write_b16 v44, v45 offset:11232
	v_cvt_pk_bf16_f32 v45, v47, s0
	ds_write_b16 v44, v45 offset:2016
	s_waitcnt vmcnt(16)
	v_lshlrev_b32_e32 v45, 16, v192
	v_mul_f32_e32 v45, v46, v45
	v_sub_f32_e32 v47, 1.0, v159
	v_mul_f32_e32 v46, v46, v160
	v_mul_f32_e32 v47, v47, v48
	v_cvt_pk_bf16_f32 v45, v45, s0
	v_rcp_f32_e32 v48, v46
	ds_write_b16 v44, v45 offset:11376
	v_cvt_pk_bf16_f32 v45, v47, s0
	ds_write_b16 v44, v45 offset:2160
	s_waitcnt vmcnt(15)
	v_lshlrev_b32_e32 v45, 16, v193
	v_mul_f32_e32 v45, v46, v45
	v_sub_f32_e32 v47, 1.0, v160
	v_mul_f32_e32 v46, v46, v161
	v_mul_f32_e32 v47, v47, v48
	v_cvt_pk_bf16_f32 v45, v45, s0
	v_rcp_f32_e32 v48, v46
	ds_write_b16 v44, v45 offset:11520
	v_cvt_pk_bf16_f32 v45, v47, s0
	ds_write_b16 v44, v45 offset:2304
	s_waitcnt vmcnt(14)
	v_lshlrev_b32_e32 v45, 16, v194
	v_mul_f32_e32 v45, v46, v45
	v_sub_f32_e32 v47, 1.0, v161
	v_mul_f32_e32 v46, v46, v162
	v_mul_f32_e32 v47, v47, v48
	v_cvt_pk_bf16_f32 v45, v45, s0
	v_rcp_f32_e32 v48, v46
	ds_write_b16 v44, v45 offset:11664
	v_cvt_pk_bf16_f32 v45, v47, s0
	ds_write_b16 v44, v45 offset:2448
	s_waitcnt vmcnt(13)
	v_lshlrev_b32_e32 v45, 16, v195
	v_mul_f32_e32 v45, v46, v45
	v_sub_f32_e32 v47, 1.0, v162
	v_mul_f32_e32 v46, v46, v163
	v_mul_f32_e32 v47, v47, v48
	v_cvt_pk_bf16_f32 v45, v45, s0
	v_rcp_f32_e32 v48, v46
	ds_write_b16 v44, v45 offset:11808
	v_cvt_pk_bf16_f32 v45, v47, s0
	ds_write_b16 v44, v45 offset:2592
	s_waitcnt vmcnt(12)
	v_lshlrev_b32_e32 v45, 16, v196
	v_mul_f32_e32 v45, v46, v45
	v_sub_f32_e32 v47, 1.0, v163
	v_mul_f32_e32 v46, v46, v164
	v_mul_f32_e32 v47, v47, v48
	v_cvt_pk_bf16_f32 v45, v45, s0
	v_rcp_f32_e32 v48, v46
	ds_write_b16 v44, v45 offset:11952
	v_cvt_pk_bf16_f32 v45, v47, s0
	ds_write_b16 v44, v45 offset:2736
	s_waitcnt vmcnt(11)
	v_lshlrev_b32_e32 v45, 16, v197
	v_mul_f32_e32 v45, v46, v45
	v_sub_f32_e32 v47, 1.0, v164
	v_mul_f32_e32 v46, v46, v165
	v_mul_f32_e32 v47, v47, v48
	v_cvt_pk_bf16_f32 v45, v45, s0
	v_rcp_f32_e32 v48, v46
	ds_write_b16 v44, v45 offset:12096
	v_cvt_pk_bf16_f32 v45, v47, s0
	ds_write_b16 v44, v45 offset:2880
	s_waitcnt vmcnt(10)
	v_lshlrev_b32_e32 v45, 16, v198
	v_mul_f32_e32 v45, v46, v45
	v_sub_f32_e32 v47, 1.0, v165
	v_mul_f32_e32 v46, v46, v166
	v_mul_f32_e32 v47, v47, v48
	v_cvt_pk_bf16_f32 v45, v45, s0
	v_rcp_f32_e32 v48, v46
	ds_write_b16 v44, v45 offset:12240
	v_cvt_pk_bf16_f32 v45, v47, s0
	ds_write_b16 v44, v45 offset:3024
	s_waitcnt vmcnt(9)
	v_lshlrev_b32_e32 v45, 16, v199
	v_mul_f32_e32 v45, v46, v45
	v_sub_f32_e32 v47, 1.0, v166
	v_mul_f32_e32 v46, v46, v167
	v_mul_f32_e32 v47, v47, v48
	v_cvt_pk_bf16_f32 v45, v45, s0
	v_rcp_f32_e32 v48, v46
	ds_write_b16 v44, v45 offset:12384
	v_cvt_pk_bf16_f32 v45, v47, s0
	ds_write_b16 v44, v45 offset:3168
	s_waitcnt vmcnt(8)
	v_lshlrev_b32_e32 v45, 16, v200
	v_mul_f32_e32 v45, v46, v45
	v_sub_f32_e32 v47, 1.0, v167
	v_mul_f32_e32 v46, v46, v168
	v_mul_f32_e32 v47, v47, v48
	v_cvt_pk_bf16_f32 v45, v45, s0
	v_rcp_f32_e32 v48, v46
	ds_write_b16 v44, v45 offset:12528
	v_cvt_pk_bf16_f32 v45, v47, s0
	ds_write_b16 v44, v45 offset:3312
	s_waitcnt vmcnt(7)
	v_lshlrev_b32_e32 v45, 16, v201
	v_mul_f32_e32 v45, v46, v45
	v_sub_f32_e32 v47, 1.0, v168
	v_mul_f32_e32 v46, v46, v169
	v_mul_f32_e32 v47, v47, v48
	v_cvt_pk_bf16_f32 v45, v45, s0
	v_rcp_f32_e32 v48, v46
	ds_write_b16 v44, v45 offset:12672
	v_cvt_pk_bf16_f32 v45, v47, s0
	ds_write_b16 v44, v45 offset:3456
	s_waitcnt vmcnt(6)
	v_lshlrev_b32_e32 v45, 16, v202
	v_mul_f32_e32 v45, v46, v45
	v_sub_f32_e32 v47, 1.0, v169
	v_mul_f32_e32 v46, v46, v170
	v_mul_f32_e32 v47, v47, v48
	v_cvt_pk_bf16_f32 v45, v45, s0
	v_rcp_f32_e32 v48, v46
	ds_write_b16 v44, v45 offset:12816
	v_cvt_pk_bf16_f32 v45, v47, s0
	ds_write_b16 v44, v45 offset:3600
	s_waitcnt vmcnt(5)
	v_lshlrev_b32_e32 v45, 16, v203
	v_mul_f32_e32 v45, v46, v45
	v_sub_f32_e32 v47, 1.0, v170
	v_mul_f32_e32 v46, v46, v171
	v_mul_f32_e32 v47, v47, v48
	v_cvt_pk_bf16_f32 v45, v45, s0
	v_rcp_f32_e32 v48, v46
	ds_write_b16 v44, v45 offset:12960
	v_cvt_pk_bf16_f32 v45, v47, s0
	ds_write_b16 v44, v45 offset:3744
	s_waitcnt vmcnt(4)
	v_lshlrev_b32_e32 v45, 16, v204
	v_mul_f32_e32 v45, v46, v45
	v_sub_f32_e32 v47, 1.0, v171
	v_mul_f32_e32 v46, v46, v172
	v_mul_f32_e32 v47, v47, v48
	v_cvt_pk_bf16_f32 v45, v45, s0
	v_rcp_f32_e32 v48, v46
	ds_write_b16 v44, v45 offset:13104
	v_cvt_pk_bf16_f32 v45, v47, s0
	ds_write_b16 v44, v45 offset:3888
	s_waitcnt vmcnt(3)
	v_lshlrev_b32_e32 v45, 16, v205
	v_mul_f32_e32 v45, v46, v45
	v_sub_f32_e32 v47, 1.0, v172
	v_mul_f32_e32 v46, v46, v173
	v_mul_f32_e32 v47, v47, v48
	v_cvt_pk_bf16_f32 v45, v45, s0
	v_rcp_f32_e32 v48, v46
	ds_write_b16 v44, v45 offset:13248
	v_cvt_pk_bf16_f32 v45, v47, s0
	ds_write_b16 v44, v45 offset:4032
	s_waitcnt vmcnt(2)
	v_lshlrev_b32_e32 v45, 16, v206
	v_mul_f32_e32 v45, v46, v45
	v_sub_f32_e32 v47, 1.0, v173
	v_mul_f32_e32 v46, v46, v174
	v_mul_f32_e32 v47, v47, v48
	v_cvt_pk_bf16_f32 v45, v45, s0
	v_rcp_f32_e32 v48, v46
	ds_write_b16 v44, v45 offset:13392
	v_cvt_pk_bf16_f32 v45, v47, s0
	ds_write_b16 v44, v45 offset:4176
	s_waitcnt vmcnt(1)
	v_lshlrev_b32_e32 v45, 16, v207
	v_mul_f32_e32 v45, v46, v45
	v_sub_f32_e32 v47, 1.0, v174
	v_mul_f32_e32 v47, v47, v48
	v_cvt_pk_bf16_f32 v45, v45, s0
	ds_write_b16 v44, v45 offset:13536
	v_cvt_pk_bf16_f32 v45, v47, s0
	ds_write_b16 v44, v45 offset:4320
	v_mul_f32_e32 v45, v46, v175
	v_rcp_f32_e32 v48, v45
	s_waitcnt vmcnt(0)
	v_lshlrev_b32_e32 v47, 16, v52
	v_mul_f32_e32 v46, v45, v47
	v_sub_f32_e32 v47, 1.0, v175
	v_mul_f32_e32 v47, v47, v48
	v_cvt_pk_bf16_f32 v46, v46, s0
	ds_write_b16 v44, v46 offset:13680
	v_cvt_pk_bf16_f32 v46, v47, s0
	ds_write_b16 v44, v46 offset:4464
	s_mov_b32 s0, 0x9000
	global_load_dword v48, v[42:43], off
	global_load_dword v49, v[42:43], off offset:1024
	global_load_dword v50, v[42:43], off offset:2048
	global_load_dword v51, v[42:43], off offset:3072
	v_add_co_u32_e32 v42, vcc, s0, v38
	s_mov_b32 s0, 0xb000
	s_nop 0
	v_addc_co_u32_e32 v43, vcc, 0, v39, vcc
	v_add_co_u32_e32 v46, vcc, s72, v38
	s_nop 1
	v_addc_co_u32_e32 v47, vcc, 0, v39, vcc
	global_load_dword v52, v[46:47], off offset:-4096
	global_load_dword v53, v[42:43], off offset:1024
	global_load_dword v54, v[42:43], off offset:2048
	global_load_dword v55, v[42:43], off offset:3072
	global_load_dword v56, v[46:47], off
	global_load_dword v57, v[46:47], off offset:1024
	global_load_dword v58, v[46:47], off offset:2048
	global_load_dword v59, v[46:47], off offset:3072
	v_add_co_u32_e32 v42, vcc, s0, v38
	s_mov_b32 s0, 0xd000
	s_nop 0
	v_addc_co_u32_e32 v43, vcc, 0, v39, vcc
	v_add_co_u32_e32 v46, vcc, s74, v38
	s_nop 1
	v_addc_co_u32_e32 v47, vcc, 0, v39, vcc
	global_load_dword v60, v[46:47], off offset:-4096
	global_load_dword v61, v[42:43], off offset:1024
	global_load_dword v62, v[42:43], off offset:2048
	global_load_dword v63, v[42:43], off offset:3072
	global_load_dword v64, v[46:47], off
	global_load_dword v65, v[46:47], off offset:1024
	global_load_dword v99, v[46:47], off offset:2048
	global_load_dword v100, v[46:47], off offset:3072
	v_add_co_u32_e32 v42, vcc, s0, v38
	s_mov_b32 s0, 0xf000
	s_nop 0
	v_addc_co_u32_e32 v43, vcc, 0, v39, vcc
	v_add_co_u32_e32 v46, vcc, s75, v38
	s_nop 1
	v_addc_co_u32_e32 v47, vcc, 0, v39, vcc
	v_add_co_u32_e32 v38, vcc, s0, v38
	global_load_dword v101, v[46:47], off offset:-4096
	global_load_dword v102, v[42:43], off offset:1024
	global_load_dword v103, v[42:43], off offset:2048
	s_nop 0
	global_load_dword v42, v[42:43], off offset:3072
	s_nop 0
	global_load_dword v43, v[46:47], off
	global_load_dword v104, v[46:47], off offset:1024
	global_load_dword v105, v[46:47], off offset:2048
	s_nop 0
	global_load_dword v46, v[46:47], off offset:3072
	v_addc_co_u32_e32 v39, vcc, 0, v39, vcc
	global_load_dword v47, v[38:39], off
	global_load_dword v106, v[38:39], off offset:1024
	global_load_dword v107, v[38:39], off offset:2048
	global_load_dword v108, v[38:39], off offset:3072
	s_nop 0
	global_load_ushort v38, v[40:41], off
	global_load_ushort v112, v[40:41], off offset:512
	global_load_ushort v113, v[40:41], off offset:1024
	global_load_ushort v114, v[40:41], off offset:1536
	global_load_ushort v115, v[40:41], off offset:2048
	global_load_ushort v116, v[40:41], off offset:2560
	global_load_ushort v117, v[40:41], off offset:3072
	global_load_ushort v118, v[40:41], off offset:3584
	s_waitcnt vmcnt(39)
	v_rcp_f32_e32 v39, v48
	s_waitcnt vmcnt(7)
	v_lshlrev_b32_e32 v38, 16, v38
	v_mul_f32_e32 v109, v48, v38
	v_sub_f32_e32 v38, 1.0, v48
	v_mul_f32_e32 v110, v38, v39
	v_add_co_u32_e32 v38, vcc, s92, v36
	v_mul_f32_e32 v48, v48, v49
	s_nop 0
	v_addc_co_u32_e32 v39, vcc, 0, v37, vcc
	v_add_co_u32_e32 v40, vcc, s95, v36
	v_cvt_pk_bf16_f32 v111, v109, s0
	s_nop 0
	v_addc_co_u32_e32 v41, vcc, 0, v37, vcc
	global_load_ushort v119, v[40:41], off offset:-4096
	global_load_ushort v120, v[38:39], off offset:512
	global_load_ushort v121, v[38:39], off offset:1024
	global_load_ushort v122, v[38:39], off offset:1536
	global_load_ushort v123, v[38:39], off offset:2048
	global_load_ushort v124, v[38:39], off offset:2560
	global_load_ushort v125, v[38:39], off offset:3072
	s_nop 0
	global_load_ushort v38, v[38:39], off offset:3584
	s_nop 0
	global_load_ushort v39, v[40:41], off
	global_load_ushort v126, v[40:41], off offset:512
	global_load_ushort v127, v[40:41], off offset:1024
	global_load_ushort v128, v[40:41], off offset:1536
	global_load_ushort v129, v[40:41], off offset:2048
	global_load_ushort v131, v[40:41], off offset:2560
	global_load_ushort v132, v[40:41], off offset:3072
	s_nop 0
	global_load_ushort v40, v[40:41], off offset:3584
	v_add_co_u32_e32 v36, vcc, s85, v36
	v_sub_f32_e32 v49, 1.0, v49
	s_nop 0
	v_addc_co_u32_e32 v37, vcc, 0, v37, vcc
	global_load_ushort v41, v[36:37], off
	global_load_ushort v133, v[36:37], off offset:512
	global_load_ushort v134, v[36:37], off offset:1024
	global_load_ushort v135, v[36:37], off offset:1536
	global_load_ushort v136, v[36:37], off offset:2048
	global_load_ushort v137, v[36:37], off offset:2560
	global_load_ushort v138, v[36:37], off offset:3072
	s_nop 0
	global_load_ushort v36, v[36:37], off offset:3584
	v_cvt_pk_bf16_f32 v37, v110, s0
	ds_write_b16 v44, v37 offset:4608
	v_mul_f32_e32 v37, v45, v109
	v_rcp_f32_e32 v109, v48
	v_cvt_pk_bf16_f32 v37, v37, s0
	ds_write_b16 v44, v37 offset:18432
	s_waitcnt vmcnt(30)
	v_lshlrev_b32_e32 v37, 16, v112
	v_mul_f32_e32 v49, v49, v109
	v_mul_f32_e32 v37, v48, v37
	v_cvt_pk_bf16_f32 v49, v49, s0
	v_mul_f32_e32 v48, v48, v50
	v_cvt_pk_bf16_f32 v109, v37, s0
	ds_write_b16 v44, v49 offset:4752
	v_mul_f32_e32 v37, v45, v37
	v_sub_f32_e32 v49, 1.0, v50
	v_rcp_f32_e32 v50, v48
	v_cvt_pk_bf16_f32 v37, v37, s0
	ds_write_b16 v44, v37 offset:18576
	s_waitcnt vmcnt(29)
	v_lshlrev_b32_e32 v37, 16, v113
	v_mul_f32_e32 v37, v48, v37
	v_mul_f32_e32 v49, v49, v50
	v_cvt_pk_bf16_f32 v50, v37, s0
	v_mul_f32_e32 v48, v48, v51
	ds_write_b16 v44, v50 offset:14112
	v_mul_f32_e32 v37, v45, v37
	v_rcp_f32_e32 v50, v48
	v_cvt_pk_bf16_f32 v37, v37, s0
	v_cvt_pk_bf16_f32 v49, v49, s0
	ds_write_b16 v44, v37 offset:18720
	s_waitcnt vmcnt(28)
	v_lshlrev_b32_e32 v37, 16, v114
	ds_write_b16 v44, v49 offset:4896
	v_mul_f32_e32 v37, v48, v37
	v_sub_f32_e32 v49, 1.0, v51
	v_mul_f32_e32 v49, v49, v50
	v_cvt_pk_bf16_f32 v50, v37, s0
	v_mul_f32_e32 v48, v48, v52
	ds_write_b16 v44, v50 offset:14256
	v_mul_f32_e32 v37, v45, v37
	v_rcp_f32_e32 v50, v48
	v_cvt_pk_bf16_f32 v37, v37, s0
	v_cvt_pk_bf16_f32 v49, v49, s0
	ds_write_b16 v44, v37 offset:18864
	s_waitcnt vmcnt(27)
	v_lshlrev_b32_e32 v37, 16, v115
	ds_write_b16 v44, v49 offset:5040
	v_mul_f32_e32 v37, v48, v37
	v_sub_f32_e32 v49, 1.0, v52
	v_mul_f32_e32 v49, v49, v50
	v_cvt_pk_bf16_f32 v50, v37, s0
	v_mul_f32_e32 v48, v48, v53
	ds_write_b16 v44, v50 offset:14400
	v_mul_f32_e32 v37, v45, v37
	v_rcp_f32_e32 v50, v48
	v_cvt_pk_bf16_f32 v37, v37, s0
	v_cvt_pk_bf16_f32 v49, v49, s0
	ds_write_b16 v44, v37 offset:19008
	s_waitcnt vmcnt(26)
	v_lshlrev_b32_e32 v37, 16, v116
	ds_write_b16 v44, v49 offset:5184
	v_mul_f32_e32 v37, v48, v37
	v_sub_f32_e32 v49, 1.0, v53
	v_mul_f32_e32 v49, v49, v50
	v_cvt_pk_bf16_f32 v50, v37, s0
	v_mul_f32_e32 v48, v48, v54
	ds_write_b16 v44, v50 offset:14544
	v_mul_f32_e32 v37, v45, v37
	v_rcp_f32_e32 v50, v48
	v_cvt_pk_bf16_f32 v37, v37, s0
	v_cvt_pk_bf16_f32 v49, v49, s0
	ds_write_b16 v44, v37 offset:19152
	s_waitcnt vmcnt(25)
	v_lshlrev_b32_e32 v37, 16, v117
	ds_write_b16 v44, v49 offset:5328
	v_mul_f32_e32 v37, v48, v37
	v_sub_f32_e32 v49, 1.0, v54
	v_mul_f32_e32 v49, v49, v50
	v_cvt_pk_bf16_f32 v50, v37, s0
	v_mul_f32_e32 v48, v48, v55
	ds_write_b16 v44, v50 offset:14688
	v_mul_f32_e32 v37, v45, v37
	v_rcp_f32_e32 v50, v48
	v_cvt_pk_bf16_f32 v37, v37, s0
	v_cvt_pk_bf16_f32 v49, v49, s0
	ds_write_b16 v44, v37 offset:19296
	s_waitcnt vmcnt(24)
	v_lshlrev_b32_e32 v37, 16, v118
	ds_write_b16 v44, v49 offset:5472
	v_mul_f32_e32 v37, v48, v37
	v_sub_f32_e32 v49, 1.0, v55
	v_mul_f32_e32 v49, v49, v50
	v_cvt_pk_bf16_f32 v50, v37, s0
	v_mul_f32_e32 v48, v48, v56
	ds_write_b16 v44, v50 offset:14832
	v_mul_f32_e32 v37, v45, v37
	v_rcp_f32_e32 v50, v48
	v_cvt_pk_bf16_f32 v37, v37, s0
	v_cvt_pk_bf16_f32 v49, v49, s0
	ds_write_b16 v44, v37 offset:19440
	s_waitcnt vmcnt(23)
	v_lshlrev_b32_e32 v37, 16, v119
	ds_write_b16 v44, v49 offset:5616
	v_mul_f32_e32 v37, v48, v37
	v_sub_f32_e32 v49, 1.0, v56
	v_mul_f32_e32 v49, v49, v50
	v_cvt_pk_bf16_f32 v50, v37, s0
	v_mul_f32_e32 v48, v48, v57
	ds_write_b16 v44, v50 offset:14976
	v_mul_f32_e32 v37, v45, v37
	v_rcp_f32_e32 v50, v48
	v_cvt_pk_bf16_f32 v37, v37, s0
	v_cvt_pk_bf16_f32 v49, v49, s0
	ds_write_b16 v44, v37 offset:19584
	s_waitcnt vmcnt(22)
	v_lshlrev_b32_e32 v37, 16, v120
	ds_write_b16 v44, v49 offset:5760
	v_mul_f32_e32 v37, v48, v37
	v_sub_f32_e32 v49, 1.0, v57
	v_mul_f32_e32 v49, v49, v50
	v_cvt_pk_bf16_f32 v50, v37, s0
	v_mul_f32_e32 v48, v48, v58
	ds_write_b16 v44, v50 offset:15120
	v_mul_f32_e32 v37, v45, v37
	v_rcp_f32_e32 v50, v48
	v_cvt_pk_bf16_f32 v37, v37, s0
	v_cvt_pk_bf16_f32 v49, v49, s0
	ds_write_b16 v44, v37 offset:19728
	s_waitcnt vmcnt(21)
	v_lshlrev_b32_e32 v37, 16, v121
	ds_write_b16 v44, v49 offset:5904
	v_mul_f32_e32 v37, v48, v37
	v_sub_f32_e32 v49, 1.0, v58
	v_mul_f32_e32 v49, v49, v50
	v_cvt_pk_bf16_f32 v50, v37, s0
	v_mul_f32_e32 v48, v48, v59
	ds_write_b16 v44, v50 offset:15264
	v_mul_f32_e32 v37, v45, v37
	v_rcp_f32_e32 v50, v48
	v_cvt_pk_bf16_f32 v37, v37, s0
	v_cvt_pk_bf16_f32 v49, v49, s0
	ds_write_b16 v44, v37 offset:19872
	s_waitcnt vmcnt(20)
	v_lshlrev_b32_e32 v37, 16, v122
	ds_write_b16 v44, v49 offset:6048
	v_mul_f32_e32 v37, v48, v37
	v_sub_f32_e32 v49, 1.0, v59
	v_mul_f32_e32 v49, v49, v50
	v_cvt_pk_bf16_f32 v50, v37, s0
	v_mul_f32_e32 v48, v48, v60
	ds_write_b16 v44, v50 offset:15408
	v_mul_f32_e32 v37, v45, v37
	v_rcp_f32_e32 v50, v48
	v_cvt_pk_bf16_f32 v37, v37, s0
	v_cvt_pk_bf16_f32 v49, v49, s0
	ds_write_b16 v44, v37 offset:20016
	s_waitcnt vmcnt(19)
	v_lshlrev_b32_e32 v37, 16, v123
	ds_write_b16 v44, v49 offset:6192
	v_mul_f32_e32 v37, v48, v37
	v_sub_f32_e32 v49, 1.0, v60
	v_mul_f32_e32 v49, v49, v50
	v_cvt_pk_bf16_f32 v50, v37, s0
	v_mul_f32_e32 v48, v48, v61
	ds_write_b16 v44, v50 offset:15552
	v_mul_f32_e32 v37, v45, v37
	v_rcp_f32_e32 v50, v48
	v_cvt_pk_bf16_f32 v37, v37, s0
	v_cvt_pk_bf16_f32 v49, v49, s0
	ds_write_b16 v44, v37 offset:20160
	s_waitcnt vmcnt(18)
	v_lshlrev_b32_e32 v37, 16, v124
	ds_write_b16 v44, v49 offset:6336
	v_mul_f32_e32 v37, v48, v37
	v_sub_f32_e32 v49, 1.0, v61
	v_mul_f32_e32 v49, v49, v50
	v_cvt_pk_bf16_f32 v50, v37, s0
	v_mul_f32_e32 v48, v48, v62
	ds_write_b16 v44, v50 offset:15696
	v_mul_f32_e32 v37, v45, v37
	v_rcp_f32_e32 v50, v48
	v_cvt_pk_bf16_f32 v37, v37, s0
	v_cvt_pk_bf16_f32 v49, v49, s0
	ds_write_b16 v44, v37 offset:20304
	s_waitcnt vmcnt(17)
	v_lshlrev_b32_e32 v37, 16, v125
	ds_write_b16 v44, v49 offset:6480
	v_mul_f32_e32 v37, v48, v37
	v_sub_f32_e32 v49, 1.0, v62
	v_mul_f32_e32 v49, v49, v50
	v_cvt_pk_bf16_f32 v50, v37, s0
	v_mul_f32_e32 v37, v45, v37
	v_cvt_pk_bf16_f32 v37, v37, s0
	v_cvt_pk_bf16_f32 v49, v49, s0
	ds_write_b16 v44, v37 offset:20448
	s_waitcnt vmcnt(16)
	v_lshlrev_b32_e32 v37, 16, v38
	v_mul_f32_e32 v38, v48, v63
	ds_write_b16 v44, v49 offset:6624
	v_rcp_f32_e32 v49, v38
	v_sub_f32_e32 v48, 1.0, v63
	v_mul_f32_e32 v37, v38, v37
	v_mul_f32_e32 v38, v38, v64
	v_mul_f32_e32 v48, v48, v49
	v_cvt_pk_bf16_f32 v48, v48, s0
	v_cvt_pk_bf16_f32 v49, v37, s0
	ds_write_b16 v44, v48 offset:6768
	v_mul_f32_e32 v37, v45, v37
	v_rcp_f32_e32 v48, v38
	v_cvt_pk_bf16_f32 v37, v37, s0
	ds_write_b16 v44, v37 offset:20592
	s_waitcnt vmcnt(15)
	v_lshlrev_b32_e32 v37, 16, v39
	v_mul_f32_e32 v37, v38, v37
	v_sub_f32_e32 v39, 1.0, v64
	v_mul_f32_e32 v39, v39, v48
	v_cvt_pk_bf16_f32 v48, v37, s0
	v_mul_f32_e32 v38, v38, v65
	ds_write_b16 v44, v48 offset:16128
	v_mul_f32_e32 v37, v45, v37
	v_rcp_f32_e32 v48, v38
	v_cvt_pk_bf16_f32 v37, v37, s0
	v_cvt_pk_bf16_f32 v39, v39, s0
	ds_write_b16 v44, v37 offset:20736
	s_waitcnt vmcnt(14)
	v_lshlrev_b32_e32 v37, 16, v126
	ds_write_b16 v44, v39 offset:6912
	v_mul_f32_e32 v37, v38, v37
	v_sub_f32_e32 v39, 1.0, v65
	v_mul_f32_e32 v39, v39, v48
	v_cvt_pk_bf16_f32 v48, v37, s0
	v_mul_f32_e32 v38, v38, v99
	ds_write_b16 v44, v48 offset:16272
	v_mul_f32_e32 v37, v45, v37
	v_rcp_f32_e32 v48, v38
	v_cvt_pk_bf16_f32 v37, v37, s0
	v_cvt_pk_bf16_f32 v39, v39, s0
	ds_write_b16 v44, v37 offset:20880
	s_waitcnt vmcnt(13)
	v_lshlrev_b32_e32 v37, 16, v127
	ds_write_b16 v44, v39 offset:7056
	v_mul_f32_e32 v37, v38, v37
	v_sub_f32_e32 v39, 1.0, v99
	v_mul_f32_e32 v39, v39, v48
	v_cvt_pk_bf16_f32 v48, v37, s0
	v_mul_f32_e32 v38, v38, v100
	ds_write_b16 v44, v48 offset:16416
	v_mul_f32_e32 v37, v45, v37
	v_rcp_f32_e32 v48, v38
	v_cvt_pk_bf16_f32 v37, v37, s0
	v_cvt_pk_bf16_f32 v39, v39, s0
	ds_write_b16 v44, v37 offset:21024
	s_waitcnt vmcnt(12)
	v_lshlrev_b32_e32 v37, 16, v128
	ds_write_b16 v44, v39 offset:7200
	v_mul_f32_e32 v37, v38, v37
	v_sub_f32_e32 v39, 1.0, v100
	v_mul_f32_e32 v39, v39, v48
	v_cvt_pk_bf16_f32 v48, v37, s0
	v_mul_f32_e32 v38, v38, v101
	ds_write_b16 v44, v48 offset:16560
	v_mul_f32_e32 v37, v45, v37
	v_rcp_f32_e32 v48, v38
	v_cvt_pk_bf16_f32 v37, v37, s0
	v_cvt_pk_bf16_f32 v39, v39, s0
	ds_write_b16 v44, v37 offset:21168
	s_waitcnt vmcnt(11)
	v_lshlrev_b32_e32 v37, 16, v129
	ds_write_b16 v44, v39 offset:7344
	v_mul_f32_e32 v37, v38, v37
	v_sub_f32_e32 v39, 1.0, v101
	v_mul_f32_e32 v39, v39, v48
	v_cvt_pk_bf16_f32 v48, v37, s0
	v_mul_f32_e32 v38, v38, v102
	ds_write_b16 v44, v48 offset:16704
	v_mul_f32_e32 v37, v45, v37
	v_rcp_f32_e32 v48, v38
	v_cvt_pk_bf16_f32 v37, v37, s0
	v_cvt_pk_bf16_f32 v39, v39, s0
	ds_write_b16 v44, v37 offset:21312
	s_waitcnt vmcnt(10)
	v_lshlrev_b32_e32 v37, 16, v131
	ds_write_b16 v44, v39 offset:7488
	v_mul_f32_e32 v37, v38, v37
	v_sub_f32_e32 v39, 1.0, v102
	v_mul_f32_e32 v39, v39, v48
	v_cvt_pk_bf16_f32 v48, v37, s0
	v_mul_f32_e32 v38, v38, v103
	ds_write_b16 v44, v48 offset:16848
	v_mul_f32_e32 v37, v45, v37
	v_rcp_f32_e32 v48, v38
	v_cvt_pk_bf16_f32 v37, v37, s0
	v_cvt_pk_bf16_f32 v39, v39, s0
	ds_write_b16 v44, v37 offset:21456
	s_waitcnt vmcnt(9)
	v_lshlrev_b32_e32 v37, 16, v132
	ds_write_b16 v44, v39 offset:7632
	v_mul_f32_e32 v37, v38, v37
	v_sub_f32_e32 v39, 1.0, v103
	v_mul_f32_e32 v39, v39, v48
	v_cvt_pk_bf16_f32 v48, v37, s0
	v_mul_f32_e32 v37, v45, v37
	v_cvt_pk_bf16_f32 v37, v37, s0
	v_mul_f32_e32 v38, v38, v42
	ds_write_b16 v44, v37 offset:21600
	s_waitcnt vmcnt(8)
	v_lshlrev_b32_e32 v37, 16, v40
	v_rcp_f32_e32 v40, v38
	v_cvt_pk_bf16_f32 v39, v39, s0
	ds_write_b16 v44, v39 offset:7776
	v_mul_f32_e32 v37, v38, v37
	v_sub_f32_e32 v39, 1.0, v42
	v_mul_f32_e32 v39, v39, v40
	v_cvt_pk_bf16_f32 v40, v37, s0
	v_mul_f32_e32 v38, v38, v43
	ds_write_b16 v44, v40 offset:17136
	v_mul_f32_e32 v37, v45, v37
	v_rcp_f32_e32 v40, v38
	v_cvt_pk_bf16_f32 v37, v37, s0
	v_cvt_pk_bf16_f32 v39, v39, s0
	ds_write_b16 v44, v37 offset:21744
	s_waitcnt vmcnt(7)
	v_lshlrev_b32_e32 v37, 16, v41
	ds_write_b16 v44, v39 offset:7920
	v_mul_f32_e32 v37, v38, v37
	v_sub_f32_e32 v39, 1.0, v43
	v_mul_f32_e32 v39, v39, v40
	v_cvt_pk_bf16_f32 v40, v37, s0
	v_mul_f32_e32 v38, v38, v104
	ds_write_b16 v44, v40 offset:17280
	v_mul_f32_e32 v37, v45, v37
	v_rcp_f32_e32 v40, v38
	v_cvt_pk_bf16_f32 v37, v37, s0
	v_cvt_pk_bf16_f32 v39, v39, s0
	ds_write_b16 v44, v37 offset:21888
	s_waitcnt vmcnt(6)
	v_lshlrev_b32_e32 v37, 16, v133
	ds_write_b16 v44, v39 offset:8064
	v_mul_f32_e32 v37, v38, v37
	v_sub_f32_e32 v39, 1.0, v104
	v_mul_f32_e32 v39, v39, v40
	v_cvt_pk_bf16_f32 v40, v37, s0
	v_mul_f32_e32 v38, v38, v105
	ds_write_b16 v44, v40 offset:17424
	v_mul_f32_e32 v37, v45, v37
	v_rcp_f32_e32 v40, v38
	v_cvt_pk_bf16_f32 v37, v37, s0
	v_cvt_pk_bf16_f32 v39, v39, s0
	ds_write_b16 v44, v37 offset:22032
	s_waitcnt vmcnt(5)
	v_lshlrev_b32_e32 v37, 16, v134
	ds_write_b16 v44, v39 offset:8208
	v_mul_f32_e32 v37, v38, v37
	v_sub_f32_e32 v39, 1.0, v105
	v_mul_f32_e32 v39, v39, v40
	v_cvt_pk_bf16_f32 v40, v37, s0
	v_mul_f32_e32 v38, v38, v46
	ds_write_b16 v44, v40 offset:17568
	v_mul_f32_e32 v37, v45, v37
	v_rcp_f32_e32 v40, v38
	v_cvt_pk_bf16_f32 v37, v37, s0
	v_cvt_pk_bf16_f32 v39, v39, s0
	ds_write_b16 v44, v37 offset:22176
	s_waitcnt vmcnt(4)
	v_lshlrev_b32_e32 v37, 16, v135
	ds_write_b16 v44, v39 offset:8352
	v_mul_f32_e32 v37, v38, v37
	v_sub_f32_e32 v39, 1.0, v46
	v_mul_f32_e32 v39, v39, v40
	v_cvt_pk_bf16_f32 v40, v37, s0
	v_mul_f32_e32 v38, v38, v47
	ds_write_b16 v44, v40 offset:17712
	v_mul_f32_e32 v37, v45, v37
	v_rcp_f32_e32 v40, v38
	v_cvt_pk_bf16_f32 v37, v37, s0
	v_cvt_pk_bf16_f32 v39, v39, s0
	ds_write_b16 v44, v37 offset:22320
	s_waitcnt vmcnt(3)
	v_lshlrev_b32_e32 v37, 16, v136
	ds_write_b16 v44, v39 offset:8496
	v_mul_f32_e32 v37, v38, v37
	v_sub_f32_e32 v39, 1.0, v47
	v_mul_f32_e32 v39, v39, v40
	v_cvt_pk_bf16_f32 v40, v37, s0
	v_mul_f32_e32 v38, v38, v106
	ds_write_b16 v44, v40 offset:17856
	v_mul_f32_e32 v37, v45, v37
	v_rcp_f32_e32 v40, v38
	v_cvt_pk_bf16_f32 v37, v37, s0
	v_cvt_pk_bf16_f32 v39, v39, s0
	ds_write_b16 v44, v37 offset:22464
	s_waitcnt vmcnt(2)
	v_lshlrev_b32_e32 v37, 16, v137
	ds_write_b16 v44, v39 offset:8640
	v_mul_f32_e32 v37, v38, v37
	v_sub_f32_e32 v39, 1.0, v106
	v_mul_f32_e32 v39, v39, v40
	v_cvt_pk_bf16_f32 v40, v37, s0
	v_mul_f32_e32 v38, v38, v107
	ds_write_b16 v44, v40 offset:18000
	v_mul_f32_e32 v37, v45, v37
	v_rcp_f32_e32 v40, v38
	v_cvt_pk_bf16_f32 v37, v37, s0
	v_cvt_pk_bf16_f32 v39, v39, s0
	ds_write_b16 v44, v37 offset:22608
	s_waitcnt vmcnt(1)
	v_lshlrev_b32_e32 v37, 16, v138
	ds_write_b16 v44, v39 offset:8784
	v_mul_f32_e32 v37, v38, v37
	v_sub_f32_e32 v39, 1.0, v107
	v_mul_f32_e32 v39, v39, v40
	v_cvt_pk_bf16_f32 v40, v37, s0
	v_mul_f32_e32 v37, v45, v37
	v_cvt_pk_bf16_f32 v37, v37, s0
	ds_write_b16 v44, v37 offset:22752
	s_waitcnt vmcnt(0)
	v_lshlrev_b32_e32 v36, 16, v36
	v_mul_f32_e32 v37, v38, v108
	v_mul_f32_e32 v36, v37, v36
	v_rcp_f32_e32 v37, v37
	v_sub_f32_e32 v38, 1.0, v108
	v_cvt_pk_bf16_f32 v39, v39, s0
	ds_write_b16 v44, v111 offset:13824
	v_mul_f32_e32 v37, v38, v37
	v_cvt_pk_bf16_f32 v38, v36, s0
	v_mul_f32_e32 v36, v45, v36
	v_cvt_pk_bf16_f32 v37, v37, s0
	v_cvt_pk_bf16_f32 v36, v36, s0
	ds_write_b16 v44, v109 offset:13968
	ds_write_b16 v44, v50 offset:15840
	ds_write_b16 v44, v49 offset:15984
	ds_write_b16 v44, v48 offset:16992
	ds_write_b16 v44, v40 offset:18144
	ds_write_b16 v44, v39 offset:8928
	ds_write_b16 v44, v38 offset:18288
	ds_write_b16 v44, v37 offset:9072
	ds_write_b16 v44, v36 offset:22896
	s_waitcnt lgkmcnt(0)
	global_load_ushort v136, v[34:35], off
	global_load_ushort v137, v[34:35], off offset:512
	v_and_b32_e32 v99, 31, v98
	v_ashrrev_i32_e32 v128, 5, v98
	v_lshlrev_b32_e32 v131, 3, v128
	v_mul_lo_u32 v98, v98, s14
	v_add_u32_e32 v98, s7, v98
	global_load_ushort v138, v[34:35], off offset:1024
	global_load_ushort v139, v[34:35], off offset:1536
	global_load_ushort v140, v[34:35], off offset:2048
	global_load_ushort v141, v[34:35], off offset:2560
	global_load_ushort v142, v[34:35], off offset:3072
	global_load_ushort v143, v[34:35], off offset:3584
	v_add_co_u32_e32 v36, vcc, s15, v34
	s_nop 1
	v_addc_co_u32_e32 v37, vcc, 0, v35, vcc
	v_add_co_u32_e32 v38, vcc, s93, v34
	s_nop 1
	v_addc_co_u32_e32 v39, vcc, 0, v35, vcc
	global_load_ushort v144, v[38:39], off offset:-4096
	global_load_ushort v145, v[36:37], off offset:512
	global_load_ushort v146, v[36:37], off offset:1024
	global_load_ushort v147, v[36:37], off offset:1536
	global_load_ushort v148, v[36:37], off offset:2048
	global_load_ushort v149, v[36:37], off offset:2560
	global_load_ushort v150, v[36:37], off offset:3072
	s_nop 0
	global_load_ushort v151, v[36:37], off offset:3584
	global_load_ushort v152, v[38:39], off
	global_load_ushort v153, v[38:39], off offset:512
	global_load_ushort v154, v[38:39], off offset:1024
	global_load_ushort v155, v[38:39], off offset:1536
	global_load_ushort v156, v[38:39], off offset:2048
	global_load_ushort v157, v[38:39], off offset:2560
	global_load_ushort v158, v[38:39], off offset:3072
	global_load_ushort v159, v[38:39], off offset:3584
	v_add_co_u32_e32 v36, vcc, s87, v34
	s_nop 1
	v_addc_co_u32_e32 v37, vcc, 0, v35, vcc
	v_add_co_u32_e32 v38, vcc, s81, v34
	s_nop 1
	v_addc_co_u32_e32 v39, vcc, 0, v35, vcc
	global_load_ushort v160, v[38:39], off offset:-4096
	global_load_ushort v161, v[36:37], off offset:512
	global_load_ushort v162, v[36:37], off offset:1024
	global_load_ushort v163, v[36:37], off offset:1536
	global_load_ushort v164, v[36:37], off offset:2048
	global_load_ushort v165, v[36:37], off offset:2560
	global_load_ushort v166, v[36:37], off offset:3072
	s_nop 0
	global_load_ushort v167, v[36:37], off offset:3584
	global_load_ushort v168, v[38:39], off
	global_load_ushort v169, v[38:39], off offset:512
	global_load_ushort v170, v[38:39], off offset:1024
	global_load_ushort v171, v[38:39], off offset:1536
	global_load_ushort v172, v[38:39], off offset:2048
	global_load_ushort v173, v[38:39], off offset:2560
	global_load_ushort v174, v[38:39], off offset:3072
	global_load_ushort v175, v[38:39], off offset:3584
	v_add_co_u32_e32 v36, vcc, s92, v34
	s_nop 1
	v_addc_co_u32_e32 v37, vcc, 0, v35, vcc
	v_add_co_u32_e32 v38, vcc, s95, v34
	s_nop 1
	v_addc_co_u32_e32 v39, vcc, 0, v35, vcc
	global_load_ushort v176, v[38:39], off offset:-4096
	global_load_ushort v177, v[36:37], off offset:512
	v_add_co_u32_e32 v34, vcc, s85, v34
	s_mov_b32 s85, s13
	s_nop 0
	v_addc_co_u32_e32 v35, vcc, 0, v35, vcc
	global_load_ushort v178, v[36:37], off offset:1024
	global_load_ushort v179, v[36:37], off offset:1536
	global_load_ushort v192, v[36:37], off offset:2048
	global_load_ushort v193, v[36:37], off offset:2560
	global_load_ushort v194, v[36:37], off offset:3072
	s_nop 0
	global_load_ushort v195, v[36:37], off offset:3584
	global_load_ushort v196, v[38:39], off
	global_load_ushort v197, v[38:39], off offset:512
	global_load_ushort v198, v[38:39], off offset:1024
	global_load_ushort v199, v[38:39], off offset:1536
	global_load_ushort v200, v[38:39], off offset:2048
	global_load_ushort v201, v[38:39], off offset:2560
	global_load_ushort v202, v[38:39], off offset:3072
	global_load_ushort v203, v[38:39], off offset:3584
	global_load_ushort v204, v[34:35], off
	global_load_ushort v205, v[34:35], off offset:512
	global_load_ushort v206, v[34:35], off offset:1024
	global_load_ushort v207, v[34:35], off offset:1536
	global_load_ushort v224, v[34:35], off offset:2048
	global_load_ushort v225, v[34:35], off offset:2560
	global_load_ushort v226, v[34:35], off offset:3072
	s_nop 0
	global_load_ushort v227, v[34:35], off offset:3584
	s_waitcnt vmcnt(0)
	v_lshl_or_b32 v100, v137, 16, v136
	v_lshl_or_b32 v101, v139, 16, v138
	v_lshl_or_b32 v102, v141, 16, v140
	v_lshl_or_b32 v103, v143, 16, v142
	v_lshl_or_b32 v104, v145, 16, v144
	v_lshl_or_b32 v105, v147, 16, v146
	v_lshl_or_b32 v106, v149, 16, v148
	v_lshl_or_b32 v107, v151, 16, v150
	v_lshl_or_b32 v108, v153, 16, v152
	v_lshl_or_b32 v109, v155, 16, v154
	v_lshl_or_b32 v110, v157, 16, v156
	v_lshl_or_b32 v111, v159, 16, v158
	v_lshl_or_b32 v112, v161, 16, v160
	v_lshl_or_b32 v113, v163, 16, v162
	v_lshl_or_b32 v114, v165, 16, v164
	v_lshl_or_b32 v115, v167, 16, v166
	v_lshl_or_b32 v116, v169, 16, v168
	v_lshl_or_b32 v117, v171, 16, v170
	v_lshl_or_b32 v118, v173, 16, v172
	v_lshl_or_b32 v119, v175, 16, v174
	v_lshl_or_b32 v120, v177, 16, v176
	v_lshl_or_b32 v121, v179, 16, v178
	v_lshl_or_b32 v122, v193, 16, v192
	v_lshl_or_b32 v123, v195, 16, v194
	v_lshl_or_b32 v124, v197, 16, v196
	v_lshl_or_b32 v125, v199, 16, v198
	v_lshl_or_b32 v126, v201, 16, v200
	v_lshl_or_b32 v127, v203, 16, v202
	v_lshl_or_b32 v132, v205, 16, v204
	v_lshl_or_b32 v133, v207, 16, v206
	v_lshl_or_b32 v134, v225, 16, v224
	v_lshl_or_b32 v135, v227, 16, v226
	v_mul_u32_u24_e32 v34, 0x48, v99
	v_lshl_add_u32 v129, v34, 1, s7
	v_lshl_add_u32 v180, v128, 4, v129
	ds_read_b128 v[50:53], v180 offset:4608
	ds_read_b128 v[34:37], v180 offset:9216
	ds_read_b128 v[54:57], v180 offset:13824
	ds_read_b128 v[136:139], v180 offset:18432
	ds_read_b128 v[140:143], v180
	ds_read_b128 v[144:147], v180 offset:32
	s_waitcnt lgkmcnt(3)
	v_mfma_f32_32x32x16_bf16 v[50:65], v[50:53], v[54:57], 0
	ds_read_b128 v[148:151], v180 offset:4640
	ds_read_b128 v[152:155], v180 offset:9248
	ds_read_b128 v[156:159], v180 offset:13856
	ds_read_b128 v[160:163], v180 offset:18464
	v_lshlrev_b32_e32 v128, 2, v128
	v_cmp_gt_i32_e32 vcc, v128, v99
	v_cmp_lt_i32_e64 s[40:41], v128, v99
	s_waitcnt lgkmcnt(5)
	v_mfma_f32_32x32x16_bf16 v[34:49], v[140:143], v[34:37], 0
	s_waitcnt lgkmcnt(1)
	v_mfma_f32_32x32x16_bf16 v[50:65], v[148:151], v[156:159], v[50:65]
	v_mfma_f32_32x32x16_bf16 v[34:49], v[144:147], v[152:155], v[34:49]
	ds_read_b128 v[148:151], v180 offset:64
	ds_read_b128 v[152:155], v180 offset:4672
	ds_read_b128 v[156:159], v180 offset:9280
	ds_read_b128 v[164:167], v180 offset:13888
	ds_read_b128 v[168:171], v180 offset:18496
	s_waitcnt lgkmcnt(1)
	v_mfma_f32_32x32x16_bf16 v[50:65], v[152:155], v[164:167], v[50:65]
	v_mfma_f32_32x32x16_bf16 v[34:49], v[148:151], v[156:159], v[34:49]
	ds_read_b128 v[152:155], v180 offset:96
	ds_read_b128 v[156:159], v180 offset:4704
	ds_read_b128 v[164:167], v180 offset:9312
	ds_read_b128 v[172:175], v180 offset:13920
	ds_read_b128 v[176:179], v180 offset:18528
	ds_write_b128 v98, v[100:103]
	ds_write_b128 v98, v[104:107] offset:16
	ds_write_b128 v98, v[108:111] offset:32
	ds_write_b128 v98, v[112:115] offset:48
	ds_write_b128 v98, v[116:119] offset:64
	ds_write_b128 v98, v[120:123] offset:80
	ds_write_b128 v98, v[124:127] offset:96
	ds_write_b128 v98, v[132:135] offset:112
	v_add_u32_e32 v102, v129, v131
	v_add_u32_e32 v131, v102, v131
	s_waitcnt lgkmcnt(9)
	v_mfma_f32_32x32x16_bf16 v[50:65], v[156:159], v[172:175], v[50:65]
	v_mfma_f32_32x32x16_bf16 v[34:49], v[152:155], v[164:167], v[34:49]
	s_nop 10
	v_cndmask_b32_e64 v156, v50, 0, vcc
	v_cndmask_b32_e64 v156, v156, v50, s[40:41]
	v_or_b32_e32 v50, 2, v128
	v_cmp_gt_i32_e64 s[42:43], v50, v99
	v_or_b32_e32 v50, 3, v128
	v_cmp_gt_i32_e64 s[44:45], v50, v99
	v_add_u32_e32 v50, 8, v128
	v_cmp_gt_i32_e64 s[46:47], v50, v99
	v_cmp_lt_i32_e64 s[48:49], v50, v99
	v_add_u32_e32 v50, 10, v128
	v_cmp_gt_i32_e64 s[50:51], v50, v99
	v_add_u32_e32 v50, 11, v128
	v_cmp_gt_i32_e64 s[54:55], v50, v99
	v_add_u32_e32 v50, 16, v128
	v_cmp_gt_i32_e64 s[56:57], v50, v99
	v_cmp_lt_i32_e64 s[58:59], v50, v99
	v_add_u32_e32 v50, 18, v128
	v_cmp_gt_i32_e64 s[60:61], v50, v99
	v_add_u32_e32 v50, 19, v128
	v_cmp_gt_i32_e64 s[62:63], v50, v99
	v_add_u32_e32 v50, 24, v128
	v_cndmask_b32_e64 v157, 0, v51, s[40:41]
	v_cndmask_b32_e64 v51, v54, 0, s[46:47]
	v_cmp_gt_i32_e64 s[64:65], v50, v99
	v_cmp_lt_i32_e64 s[66:67], v50, v99
	v_add_u32_e32 v50, 26, v128
	v_cndmask_b32_e64 v164, v51, v54, s[48:49]
	v_cndmask_b32_e64 v51, v58, 0, s[56:57]
	v_cmp_gt_i32_e64 s[68:69], v50, v99
	v_add_u32_e32 v50, 27, v128
	v_cndmask_b32_e64 v172, v51, v58, s[58:59]
	v_cndmask_b32_e64 v51, v62, 0, s[64:65]
	v_cmp_gt_i32_e64 s[70:71], v50, v99
	v_cndmask_b32_e64 v158, v52, 0, s[42:43]
	v_cndmask_b32_e64 v159, v53, 0, s[44:45]
	v_cndmask_b32_e64 v165, 0, v55, s[48:49]
	v_cndmask_b32_e64 v166, v56, 0, s[50:51]
	v_cndmask_b32_e64 v167, v57, 0, s[54:55]
	v_cndmask_b32_e64 v173, 0, v59, s[58:59]
	v_cndmask_b32_e64 v174, v60, 0, s[60:61]
	v_cndmask_b32_e64 v175, v61, 0, s[62:63]
	v_cndmask_b32_e64 v181, v51, v62, s[66:67]
	v_cndmask_b32_e64 v186, 0, v63, s[66:67]
	v_cndmask_b32_e64 v187, v64, 0, s[68:69]
	v_cndmask_b32_e64 v99, v65, 0, s[70:71]
	v_mfma_f32_32x32x16_bf16 v[50:65], v[140:143], v[136:139], 0
	v_cndmask_b32_e64 v98, v34, 0, vcc
	v_cndmask_b32_e64 v34, v98, v34, s[40:41]
	v_cndmask_b32_e64 v98, v38, 0, s[46:47]
	v_cndmask_b32_e64 v38, v98, v38, s[48:49]
	v_cndmask_b32_e64 v98, v42, 0, s[56:57]
	v_cndmask_b32_e64 v35, 0, v35, s[40:41]
	v_cndmask_b32_e64 v36, v36, 0, s[42:43]
	v_mfma_f32_32x32x16_bf16 v[50:65], v[144:147], v[160:163], v[50:65]
	v_cndmask_b32_e64 v37, v37, 0, s[44:45]
	v_cndmask_b32_e64 v39, 0, v39, s[48:49]
	v_cndmask_b32_e64 v40, v40, 0, s[50:51]
	v_cndmask_b32_e64 v41, v41, 0, s[54:55]
	v_cndmask_b32_e64 v42, v98, v42, s[58:59]
	v_cndmask_b32_e64 v98, v46, 0, s[64:65]
	v_cndmask_b32_e64 v43, 0, v43, s[58:59]
	v_mfma_f32_32x32x16_bf16 v[50:65], v[148:151], v[168:171], v[50:65]
	v_cndmask_b32_e64 v44, v44, 0, s[60:61]
	v_cndmask_b32_e64 v45, v45, 0, s[62:63]
	v_cndmask_b32_e64 v46, v98, v46, s[66:67]
	v_cndmask_b32_e64 v47, 0, v47, s[66:67]
	v_cndmask_b32_e64 v48, v48, 0, s[68:69]
	v_cndmask_b32_e64 v49, v49, 0, s[70:71]
	v_cvt_pk_bf16_f32 v34, v34, v35
	s_waitcnt lgkmcnt(8)
	v_mfma_f32_32x32x16_bf16 v[50:65], v[152:155], v[176:179], v[50:65]
	v_cvt_pk_bf16_f32 v35, v36, v37
	v_cvt_pk_bf16_f32 v36, v38, v39
	v_cvt_pk_bf16_f32 v37, v40, v41
	v_cvt_pk_bf16_f32 v136, v42, v43
	v_cvt_pk_bf16_f32 v137, v44, v45
	v_cvt_pk_bf16_f32 v138, v46, v47
	v_cvt_pk_bf16_f32 v139, v48, v49
	s_nop 4
	v_cvt_pk_bf16_f32 v38, v50, v51
	v_cvt_pk_bf16_f32 v39, v52, v53
	v_cvt_pk_bf16_f32 v40, v54, v55
	v_cvt_pk_bf16_f32 v41, v56, v57
	v_cvt_pk_bf16_f32 v143, v187, v99
	ds_read2_b64 v[42:45], v102 offset0:8 offset1:10
	ds_read2_b64 v[46:49], v102 offset1:2
	ds_read2_b64 v[98:101], v102 offset0:4 offset1:6
	v_cvt_pk_bf16_f32 v144, v58, v59
	v_cvt_pk_bf16_f32 v145, v60, v61
	v_cvt_pk_bf16_f32 v146, v62, v63
	v_cvt_pk_bf16_f32 v147, v64, v65
	s_waitcnt lgkmcnt(1)
	v_mfma_f32_32x32x16_bf16 v[50:65], v[38:41], v[46:49], 0
	v_cvt_pk_bf16_f32 v132, v156, v157
	v_cvt_pk_bf16_f32 v133, v158, v159
	v_cvt_pk_bf16_f32 v134, v164, v165
	v_cvt_pk_bf16_f32 v135, v166, v167
	v_cvt_pk_bf16_f32 v140, v172, v173
	v_cvt_pk_bf16_f32 v141, v174, v175
	v_cvt_pk_bf16_f32 v142, v181, v186
	v_mfma_f32_32x32x16_bf16 v[50:65], v[132:135], v[42:45], v[50:65]
	ds_read2_b64 v[42:45], v102 offset0:12 offset1:14
	v_readlane_b32 s42, v254, 31
	v_readlane_b32 s43, v254, 32
	s_mov_b32 s44, s12
	v_readlane_b32 s54, v254, 12
	v_readlane_b32 s55, v254, 13
	v_cmp_gt_u32_e32 vcc, 32, v130
	v_mfma_f32_32x32x16_bf16 v[114:129], v[34:37], v[46:49], 0
	s_waitcnt lgkmcnt(1)
	v_mfma_f32_32x32x16_bf16 v[50:65], v[144:147], v[98:101], v[50:65]
	v_mfma_f32_32x32x16_bf16 v[114:129], v[136:139], v[98:101], v[114:129]
	s_waitcnt lgkmcnt(0)
	v_mfma_f32_32x32x16_bf16 v[50:65], v[140:143], v[42:45], v[50:65]
	ds_read_b128 v[148:151], v180 offset:18432
	ds_read_b128 v[42:45], v131 offset:23040
	ds_read_b128 v[46:49], v131 offset:23072
	ds_read_b128 v[152:155], v180 offset:9216
	ds_read_b128 v[156:159], v180 offset:9248
	ds_read_b128 v[160:163], v180 offset:18464
	s_waitcnt lgkmcnt(2)
	v_mfma_f32_32x32x16_bf16 v[114:129], v[152:155], v[42:45], v[114:129]
	v_mfma_f32_32x32x16_bf16 v[50:65], v[148:151], v[42:45], v[50:65]
	ds_read_b128 v[42:45], v131 offset:23104
	ds_read_b128 v[164:167], v180 offset:9280
	ds_read_b128 v[168:171], v180 offset:18496
	s_waitcnt lgkmcnt(4)
	v_mfma_f32_32x32x16_bf16 v[114:129], v[156:159], v[46:49], v[114:129]
	s_waitcnt lgkmcnt(3)
	v_mfma_f32_32x32x16_bf16 v[50:65], v[160:163], v[46:49], v[50:65]
	s_waitcnt lgkmcnt(1)
	v_mfma_f32_32x32x16_bf16 v[114:129], v[164:167], v[42:45], v[114:129]
	s_waitcnt lgkmcnt(0)
	v_mfma_f32_32x32x16_bf16 v[50:65], v[168:171], v[42:45], v[50:65]
	ds_read_b128 v[42:45], v131 offset:23136
	ds_read_b128 v[172:175], v180 offset:9312
	ds_read_b128 v[176:179], v180 offset:18528
	v_add_u32_e32 v180, 0x1000, v102
	s_waitcnt lgkmcnt(1)
	v_mfma_f32_32x32x16_bf16 v[114:129], v[172:175], v[42:45], v[114:129]
	s_waitcnt lgkmcnt(0)
	v_mfma_f32_32x32x16_bf16 v[50:65], v[176:179], v[42:45], v[50:65]
	ds_read2_b64 v[42:45], v180 offset0:64 offset1:66
	ds_read2_b64 v[192:195], v180 offset0:72 offset1:74
	s_waitcnt lgkmcnt(1)
	v_mfma_f32_32x32x16_bf16 v[98:113], v[34:37], v[42:45], 0
	v_mfma_f32_32x32x16_bf16 v[34:49], v[38:41], v[42:45], 0
	s_waitcnt lgkmcnt(0)
	v_mfma_f32_32x32x16_bf16 v[34:49], v[132:135], v[192:195], v[34:49]
	ds_read2_b64 v[132:135], v180 offset0:68 offset1:70
	ds_read2_b64 v[192:195], v180 offset0:76 offset1:78
	s_waitcnt lgkmcnt(1)
	v_mfma_f32_32x32x16_bf16 v[34:49], v[144:147], v[132:135], v[34:49]
	v_mfma_f32_32x32x16_bf16 v[98:113], v[136:139], v[132:135], v[98:113]
	ds_read_b128 v[132:135], v131 offset:27648
	s_waitcnt lgkmcnt(1)
	v_mfma_f32_32x32x16_bf16 v[34:49], v[140:143], v[192:195], v[34:49]
	s_waitcnt lgkmcnt(0)
	v_mfma_f32_32x32x16_bf16 v[98:113], v[152:155], v[132:135], v[98:113]
	v_mfma_f32_32x32x16_bf16 v[34:49], v[148:151], v[132:135], v[34:49]
	ds_read_b128 v[132:135], v131 offset:27680
	s_waitcnt lgkmcnt(0)
	v_mfma_f32_32x32x16_bf16 v[98:113], v[156:159], v[132:135], v[98:113]
	v_mfma_f32_32x32x16_bf16 v[34:49], v[160:163], v[132:135], v[34:49]
	ds_read_b128 v[132:135], v131 offset:27712
	s_waitcnt lgkmcnt(0)
	v_mfma_f32_32x32x16_bf16 v[98:113], v[164:167], v[132:135], v[98:113]
	v_mfma_f32_32x32x16_bf16 v[34:49], v[168:171], v[132:135], v[34:49]
	ds_read_b128 v[132:135], v131 offset:27744
	s_waitcnt lgkmcnt(0)
	s_load_dwordx2 s[0:1], s[42:43], 0x40
	v_ashrrev_i32_e32 v131, 3, v130
	v_and_b32_e32 v131, -4, v131
	s_waitcnt lgkmcnt(0)
	v_mfma_f32_32x32x16_bf16 v[98:113], v[172:175], v[132:135], v[98:113]
	v_mfma_f32_32x32x16_bf16 v[34:49], v[176:179], v[132:135], v[34:49]
	v_or_b32_e32 v132, s44, v0
	v_ashrrev_i32_e32 v133, 31, v132
	v_lshl_add_u64 v[132:133], v[132:133], 2, s[0:1]
	v_readlane_b32 s0, v254, 21
	global_load_dword v224, v[132:133], off
	global_load_dword v189, v[132:133], off offset:128
	v_add_u32_e32 v132, s76, v131
	v_readlane_b32 s1, v254, 22
	s_add_u32 s0, s0, s9
	s_addc_u32 s1, s1, 0
	v_lshlrev_b32_e32 v0, 1, v0
	v_ashrrev_i32_e32 v133, 31, v132
	v_or_b32_e32 v164, 1, v132
	v_lshl_add_u64 v[134:135], s[0:1], 0, v[0:1]
	v_lshlrev_b64 v[136:137], 9, v[132:133]
	v_ashrrev_i32_e32 v165, 31, v164
	v_or_b32_e32 v162, 2, v132
	v_lshl_add_u64 v[170:171], v[134:135], 0, v[136:137]
	v_lshlrev_b64 v[136:137], 9, v[164:165]
	v_ashrrev_i32_e32 v163, 31, v162
	v_or_b32_e32 v160, 3, v132
	v_lshl_add_u64 v[166:167], v[134:135], 0, v[136:137]
	v_lshlrev_b64 v[136:137], 9, v[162:163]
	v_ashrrev_i32_e32 v161, 31, v160
	v_add_u32_e32 v158, 8, v132
	v_lshl_add_u64 v[168:169], v[134:135], 0, v[136:137]
	v_lshlrev_b64 v[136:137], 9, v[160:161]
	v_ashrrev_i32_e32 v159, 31, v158
	v_add_u32_e32 v156, 9, v132
	v_lshl_add_u64 v[172:173], v[134:135], 0, v[136:137]
	v_lshlrev_b64 v[136:137], 9, v[158:159]
	v_ashrrev_i32_e32 v157, 31, v156
	v_add_u32_e32 v154, 10, v132
	v_lshl_add_u64 v[174:175], v[134:135], 0, v[136:137]
	v_lshlrev_b64 v[136:137], 9, v[156:157]
	v_ashrrev_i32_e32 v155, 31, v154
	v_add_u32_e32 v152, 11, v132
	v_lshl_add_u64 v[176:177], v[134:135], 0, v[136:137]
	v_lshlrev_b64 v[136:137], 9, v[154:155]
	v_ashrrev_i32_e32 v153, 31, v152
	v_add_u32_e32 v150, 16, v132
	v_lshl_add_u64 v[178:179], v[134:135], 0, v[136:137]
	v_lshlrev_b64 v[136:137], 9, v[152:153]
	v_ashrrev_i32_e32 v151, 31, v150
	v_add_u32_e32 v148, 17, v132
	v_lshl_add_u64 v[180:181], v[134:135], 0, v[136:137]
	v_lshlrev_b64 v[136:137], 9, v[150:151]
	v_ashrrev_i32_e32 v149, 31, v148
	v_add_u32_e32 v146, 18, v132
	v_lshl_add_u64 v[192:193], v[134:135], 0, v[136:137]
	v_lshlrev_b64 v[136:137], 9, v[148:149]
	v_ashrrev_i32_e32 v147, 31, v146
	v_add_u32_e32 v144, 19, v132
	v_lshl_add_u64 v[194:195], v[134:135], 0, v[136:137]
	v_lshlrev_b64 v[136:137], 9, v[146:147]
	v_ashrrev_i32_e32 v145, 31, v144
	v_add_u32_e32 v142, 24, v132
	v_lshl_add_u64 v[196:197], v[134:135], 0, v[136:137]
	v_lshlrev_b64 v[136:137], 9, v[144:145]
	v_ashrrev_i32_e32 v143, 31, v142
	v_add_u32_e32 v140, 25, v132
	v_lshl_add_u64 v[198:199], v[134:135], 0, v[136:137]
	v_lshlrev_b64 v[136:137], 9, v[142:143]
	v_ashrrev_i32_e32 v141, 31, v140
	v_add_u32_e32 v138, 26, v132
	v_lshl_add_u64 v[200:201], v[134:135], 0, v[136:137]
	v_lshlrev_b64 v[136:137], 9, v[140:141]
	v_ashrrev_i32_e32 v139, 31, v138
	v_lshl_add_u64 v[202:203], v[134:135], 0, v[136:137]
	v_lshlrev_b64 v[136:137], 9, v[138:139]
	v_lshl_add_u64 v[204:205], v[134:135], 0, v[136:137]
	v_add_u32_e32 v136, 27, v132
	v_ashrrev_i32_e32 v137, 31, v136
	s_add_u32 s0, s54, s9
	v_lshlrev_b64 v[186:187], 9, v[136:137]
	s_addc_u32 s1, s55, 0
	v_lshl_add_u64 v[206:207], v[134:135], 0, v[186:187]
	v_mov_b32_e32 v186, v81
	v_lshl_add_u64 v[130:131], s[0:1], 0, v[0:1]
	v_mov_b32_e32 v0, v97
	v_permlane32_swap_b32_e32 v81, v186
	s_nop 0
	v_permlane32_swap_b32_e32 v97, v0
	v_cndmask_b32_e32 v81, v81, v186, vcc
	v_cndmask_b32_e32 v0, v97, v0, vcc
	v_add_f32_e32 v81, v98, v81
	v_add_f32_e32 v0, v114, v0
	v_mul_f32_e32 v97, v81, v81
	v_fmac_f32_e32 v97, v0, v0
	v_lshlrev_b64 v[164:165], 11, v[164:165]
	v_lshl_add_u64 v[164:165], v[130:131], 0, v[164:165]
	v_add_f32_dpp v97, v97, v97 quad_perm:[1,0,3,2] row_mask:0xf bank_mask:0xf bound_ctrl:1
	v_lshlrev_b64 v[162:163], 11, v[162:163]
	v_lshl_add_u64 v[162:163], v[130:131], 0, v[162:163]
	v_add_f32_dpp v97, v97, v97 quad_perm:[2,3,0,1] row_mask:0xf bank_mask:0xf bound_ctrl:1
	s_add_i32 s6, s6, s13
	s_add_i32 s8, s8, s86
	v_add_f32_dpp v97, v97, v97 row_ror:4 row_mask:0xf bank_mask:0xf bound_ctrl:1
	s_cmpk_lt_i32 s6, 0x400
	s_nop 0
	v_add_f32_dpp v97, v97, v97 row_ror:8 row_mask:0xf bank_mask:0xf bound_ctrl:1
	v_mov_b32_e32 v98, v97
	s_nop 1
	v_permlane16_swap_b32_e32 v97, v98
	v_add_f32_e32 v97, v97, v98
	v_fmamk_f32 v97, v97, 0x3c800000, v208
	v_rsq_f32_e32 v97, v97
	global_load_ushort v98, v[170:171], off
	v_mul_f32_e32 v0, v0, v97
	v_mul_f32_e32 v81, v81, v97
	global_load_ushort v97, v[170:171], off offset:64
	s_waitcnt vmcnt(3)
	v_mul_f32_e32 v0, v224, v0
	s_waitcnt vmcnt(2)
	v_mul_f32_e32 v81, v189, v81
	v_lshlrev_b64 v[170:171], 11, v[132:133]
	v_lshl_add_u64 v[186:187], v[130:131], 0, v[170:171]
	s_waitcnt vmcnt(1)
	v_lshlrev_b32_e32 v98, 16, v98
	v_mul_f32_e32 v0, v0, v98
	v_cvt_pk_bf16_f32 v211, v0, s0
	s_waitcnt vmcnt(0)
	v_lshlrev_b32_e32 v97, 16, v97
	v_mul_f32_e32 v210, v81, v97
	global_load_ushort v228, v[166:167], off
	global_load_ushort v229, v[166:167], off offset:64
	global_load_ushort v230, v[168:169], off
	global_load_ushort v231, v[168:169], off offset:64
	global_load_ushort v232, v[172:173], off
	global_load_ushort v233, v[172:173], off offset:64
	global_load_ushort v234, v[174:175], off
	global_load_ushort v235, v[174:175], off offset:64
	global_load_ushort v227, v[176:177], off
	global_load_ushort v226, v[176:177], off offset:64
	global_load_ushort v225, v[178:179], off
	s_nop 0
	global_load_ushort v178, v[178:179], off offset:64
	s_nop 0
	global_load_ushort v177, v[180:181], off
	global_load_ushort v176, v[180:181], off offset:64
	global_load_ushort v175, v[192:193], off
	global_load_ushort v174, v[192:193], off offset:64
	global_load_ushort v173, v[194:195], off
	global_load_ushort v172, v[194:195], off offset:64
	global_load_ushort v171, v[196:197], off
	global_load_ushort v170, v[196:197], off offset:64
	global_load_ushort v169, v[198:199], off
	global_load_ushort v168, v[198:199], off offset:64
	global_load_ushort v167, v[200:201], off
	global_load_ushort v166, v[200:201], off offset:64
	global_load_ushort v133, v[202:203], off
	global_load_ushort v114, v[202:203], off offset:64
	global_load_ushort v98, v[204:205], off
	global_load_ushort v97, v[204:205], off offset:64
	global_load_ushort v81, v[206:207], off
	global_load_ushort v0, v[206:207], off offset:64
	v_cvt_pk_bf16_f32 v179, v210, s0
	v_mov_b32_e32 v180, v80
	global_store_short v[186:187], v179, off offset:64
	v_mov_b32_e32 v179, v96
	v_permlane32_swap_b32_e32 v80, v180
	s_nop 0
	v_permlane32_swap_b32_e32 v96, v179
	v_cndmask_b32_e32 v80, v80, v180, vcc
	v_cndmask_b32_e32 v96, v96, v179, vcc
	v_add_f32_e32 v80, v99, v80
	v_add_f32_e32 v96, v115, v96
	v_mul_f32_e32 v99, v80, v80
	v_fmac_f32_e32 v99, v96, v96
	global_store_short v[186:187], v211, off
	s_waitcnt vmcnt(2)
	v_lshlrev_b32_e32 v0, 16, v0
	v_add_f32_dpp v99, v99, v99 quad_perm:[1,0,3,2] row_mask:0xf bank_mask:0xf bound_ctrl:1
	s_nop 1
	v_add_f32_dpp v99, v99, v99 quad_perm:[2,3,0,1] row_mask:0xf bank_mask:0xf bound_ctrl:1
	s_nop 1
	v_add_f32_dpp v99, v99, v99 row_ror:4 row_mask:0xf bank_mask:0xf bound_ctrl:1
	s_nop 1
	v_add_f32_dpp v99, v99, v99 row_ror:8 row_mask:0xf bank_mask:0xf bound_ctrl:1
	v_mov_b32_e32 v115, v99
	s_nop 1
	v_permlane16_swap_b32_e32 v99, v115
	v_add_f32_e32 v99, v99, v115
	v_fmamk_f32 v99, v99, 0x3c800000, v208
	v_rsq_f32_e32 v99, v99
	v_lshlrev_b32_e32 v115, 16, v228
	v_mul_f32_e32 v96, v96, v99
	v_mul_f32_e32 v96, v224, v96
	v_mul_f32_e32 v80, v80, v99
	v_mul_f32_e32 v96, v96, v115
	v_mul_f32_e32 v80, v189, v80
	v_lshlrev_b32_e32 v99, 16, v229
	v_mul_f32_e32 v80, v80, v99
	v_cvt_pk_bf16_f32 v96, v96, s0
	global_store_short v[164:165], v96, off
	v_cvt_pk_bf16_f32 v80, v80, s0
	v_mov_b32_e32 v96, v79
	global_store_short v[164:165], v80, off offset:64
	v_mov_b32_e32 v80, v95
	v_permlane32_swap_b32_e32 v79, v96
	s_nop 0
	v_permlane32_swap_b32_e32 v95, v80
	v_cndmask_b32_e32 v79, v79, v96, vcc
	v_cndmask_b32_e32 v80, v95, v80, vcc
	v_add_f32_e32 v79, v100, v79
	v_add_f32_e32 v80, v116, v80
	v_mul_f32_e32 v95, v79, v79
	v_fmac_f32_e32 v95, v80, v80
	s_nop 1
	v_add_f32_dpp v95, v95, v95 quad_perm:[1,0,3,2] row_mask:0xf bank_mask:0xf bound_ctrl:1
	s_nop 1
	v_add_f32_dpp v95, v95, v95 quad_perm:[2,3,0,1] row_mask:0xf bank_mask:0xf bound_ctrl:1
	s_nop 1
	v_add_f32_dpp v95, v95, v95 row_ror:4 row_mask:0xf bank_mask:0xf bound_ctrl:1
	s_nop 1
	v_add_f32_dpp v95, v95, v95 row_ror:8 row_mask:0xf bank_mask:0xf bound_ctrl:1
	v_mov_b32_e32 v96, v95
	s_nop 1
	v_permlane16_swap_b32_e32 v95, v96
	v_add_f32_e32 v95, v95, v96
	v_fmamk_f32 v95, v95, 0x3c800000, v208
	v_rsq_f32_e32 v95, v95
	v_lshlrev_b32_e32 v96, 16, v230
	v_mul_f32_e32 v80, v80, v95
	v_mul_f32_e32 v80, v224, v80
	v_mul_f32_e32 v79, v79, v95
	v_mul_f32_e32 v80, v80, v96
	v_mul_f32_e32 v79, v189, v79
	v_lshlrev_b32_e32 v95, 16, v231
	v_mul_f32_e32 v79, v79, v95
	v_cvt_pk_bf16_f32 v80, v80, s0
	global_store_short v[162:163], v80, off
	v_cvt_pk_bf16_f32 v79, v79, s0
	v_mov_b32_e32 v80, v78
	global_store_short v[162:163], v79, off offset:64
	v_mov_b32_e32 v79, v94
	v_permlane32_swap_b32_e32 v78, v80
	s_nop 0
	v_permlane32_swap_b32_e32 v94, v79
	v_cndmask_b32_e32 v78, v78, v80, vcc
	v_cndmask_b32_e32 v79, v94, v79, vcc
	v_add_f32_e32 v78, v101, v78
	v_add_f32_e32 v79, v117, v79
	v_mul_f32_e32 v80, v78, v78
	v_fmac_f32_e32 v80, v79, v79
	v_add_u32_e32 v96, 32, v132
	s_nop 0
	v_add_f32_dpp v80, v80, v80 quad_perm:[1,0,3,2] row_mask:0xf bank_mask:0xf bound_ctrl:1
	s_nop 1
	v_add_f32_dpp v80, v80, v80 quad_perm:[2,3,0,1] row_mask:0xf bank_mask:0xf bound_ctrl:1
	s_nop 1
	v_add_f32_dpp v80, v80, v80 row_ror:4 row_mask:0xf bank_mask:0xf bound_ctrl:1
	s_nop 1
	v_add_f32_dpp v80, v80, v80 row_ror:8 row_mask:0xf bank_mask:0xf bound_ctrl:1
	v_mov_b32_e32 v94, v80
	s_nop 1
	v_permlane16_swap_b32_e32 v80, v94
	v_add_f32_e32 v80, v80, v94
	v_fmamk_f32 v80, v80, 0x3c800000, v208
	v_rsq_f32_e32 v80, v80
	v_lshlrev_b32_e32 v94, 16, v232
	v_mul_f32_e32 v79, v79, v80
	v_mul_f32_e32 v79, v224, v79
	v_mul_f32_e32 v78, v78, v80
	v_mul_f32_e32 v79, v79, v94
	v_mul_f32_e32 v78, v189, v78
	v_lshlrev_b32_e32 v80, 16, v233
	v_mul_f32_e32 v80, v78, v80
	v_cvt_pk_bf16_f32 v94, v79, s0
	v_lshlrev_b64 v[78:79], 11, v[160:161]
	v_lshl_add_u64 v[78:79], v[130:131], 0, v[78:79]
	v_cvt_pk_bf16_f32 v80, v80, s0
	global_store_short v[78:79], v94, off
	global_store_short v[78:79], v80, off offset:64
	v_mov_b32_e32 v79, v77
	v_mov_b32_e32 v78, v93
	s_nop 0
	v_permlane32_swap_b32_e32 v77, v79
	v_permlane32_swap_b32_e32 v93, v78
	v_cndmask_b32_e32 v77, v77, v79, vcc
	v_cndmask_b32_e32 v78, v93, v78, vcc
	v_add_f32_e32 v77, v102, v77
	v_add_f32_e32 v78, v118, v78
	v_mul_f32_e32 v79, v77, v77
	v_fmac_f32_e32 v79, v78, v78
	v_add_u32_e32 v94, 33, v132
	v_ashrrev_i32_e32 v95, 31, v94
	v_add_f32_dpp v79, v79, v79 quad_perm:[1,0,3,2] row_mask:0xf bank_mask:0xf bound_ctrl:1
	s_nop 1
	v_add_f32_dpp v79, v79, v79 quad_perm:[2,3,0,1] row_mask:0xf bank_mask:0xf bound_ctrl:1
	s_nop 1
	v_add_f32_dpp v79, v79, v79 row_ror:4 row_mask:0xf bank_mask:0xf bound_ctrl:1
	s_nop 1
	v_add_f32_dpp v79, v79, v79 row_ror:8 row_mask:0xf bank_mask:0xf bound_ctrl:1
	v_mov_b32_e32 v80, v79
	s_nop 1
	v_permlane16_swap_b32_e32 v79, v80
	v_add_f32_e32 v79, v79, v80
	v_fmamk_f32 v79, v79, 0x3c800000, v208
	v_rsq_f32_e32 v79, v79
	v_lshlrev_b32_e32 v80, 16, v234
	v_mul_f32_e32 v78, v78, v79
	v_mul_f32_e32 v78, v224, v78
	v_mul_f32_e32 v77, v77, v79
	v_mul_f32_e32 v78, v78, v80
	v_mul_f32_e32 v77, v189, v77
	v_lshlrev_b32_e32 v79, 16, v235
	v_mul_f32_e32 v77, v77, v79
	v_cvt_pk_bf16_f32 v80, v78, s0
	v_lshlrev_b64 v[78:79], 11, v[158:159]
	v_lshl_add_u64 v[78:79], v[130:131], 0, v[78:79]
	v_cvt_pk_bf16_f32 v77, v77, s0
	global_store_short v[78:79], v80, off
	global_store_short v[78:79], v77, off offset:64
	v_mov_b32_e32 v78, v76
	v_mov_b32_e32 v77, v92
	s_nop 0
	v_permlane32_swap_b32_e32 v76, v78
	v_permlane32_swap_b32_e32 v92, v77
	v_cndmask_b32_e32 v76, v76, v78, vcc
	v_cndmask_b32_e32 v77, v92, v77, vcc
	v_add_f32_e32 v76, v103, v76
	v_add_f32_e32 v77, v119, v77
	v_mul_f32_e32 v78, v76, v76
	v_fmac_f32_e32 v78, v77, v77
	v_add_u32_e32 v92, 34, v132
	v_ashrrev_i32_e32 v93, 31, v92
	v_add_f32_dpp v78, v78, v78 quad_perm:[1,0,3,2] row_mask:0xf bank_mask:0xf bound_ctrl:1
	v_add_u32_e32 v80, 48, v132
	s_nop 0
	v_add_f32_dpp v78, v78, v78 quad_perm:[2,3,0,1] row_mask:0xf bank_mask:0xf bound_ctrl:1
	s_nop 1
	v_add_f32_dpp v78, v78, v78 row_ror:4 row_mask:0xf bank_mask:0xf bound_ctrl:1
	s_nop 1
	v_add_f32_dpp v78, v78, v78 row_ror:8 row_mask:0xf bank_mask:0xf bound_ctrl:1
	v_mov_b32_e32 v79, v78
	s_nop 1
	v_permlane16_swap_b32_e32 v78, v79
	v_add_f32_e32 v78, v78, v79
	v_fmamk_f32 v78, v78, 0x3c800000, v208
	v_rsq_f32_e32 v78, v78
	v_lshlrev_b32_e32 v79, 16, v227
	v_mul_f32_e32 v77, v77, v78
	v_mul_f32_e32 v77, v224, v77
	v_mul_f32_e32 v76, v76, v78
	v_mul_f32_e32 v77, v77, v79
	v_mul_f32_e32 v76, v189, v76
	v_lshlrev_b32_e32 v78, 16, v226
	v_mul_f32_e32 v78, v76, v78
	v_cvt_pk_bf16_f32 v79, v77, s0
	v_lshlrev_b64 v[76:77], 11, v[156:157]
	v_lshl_add_u64 v[76:77], v[130:131], 0, v[76:77]
	v_cvt_pk_bf16_f32 v78, v78, s0
	global_store_short v[76:77], v79, off
	global_store_short v[76:77], v78, off offset:64
	v_mov_b32_e32 v77, v75
	v_mov_b32_e32 v76, v91
	s_nop 0
	v_permlane32_swap_b32_e32 v75, v77
	v_permlane32_swap_b32_e32 v91, v76
	v_cndmask_b32_e32 v75, v75, v77, vcc
	v_cndmask_b32_e32 v76, v91, v76, vcc
	v_add_f32_e32 v75, v104, v75
	v_add_f32_e32 v76, v120, v76
	v_mul_f32_e32 v77, v75, v75
	v_fmac_f32_e32 v77, v76, v76
	s_nop 1
	v_add_f32_dpp v77, v77, v77 quad_perm:[1,0,3,2] row_mask:0xf bank_mask:0xf bound_ctrl:1
	s_nop 1
	v_add_f32_dpp v77, v77, v77 quad_perm:[2,3,0,1] row_mask:0xf bank_mask:0xf bound_ctrl:1
	s_nop 1
	v_add_f32_dpp v77, v77, v77 row_ror:4 row_mask:0xf bank_mask:0xf bound_ctrl:1
	s_nop 1
	v_add_f32_dpp v77, v77, v77 row_ror:8 row_mask:0xf bank_mask:0xf bound_ctrl:1
	v_mov_b32_e32 v78, v77
	s_nop 1
	v_permlane16_swap_b32_e32 v77, v78
	v_add_f32_e32 v77, v77, v78
	v_fmamk_f32 v77, v77, 0x3c800000, v208
	v_rsq_f32_e32 v77, v77
	v_lshlrev_b32_e32 v78, 16, v225
	v_mul_f32_e32 v76, v76, v77
	v_mul_f32_e32 v76, v224, v76
	v_mul_f32_e32 v75, v75, v77
	v_mul_f32_e32 v76, v76, v78
	v_mul_f32_e32 v75, v189, v75
	v_lshlrev_b32_e32 v77, 16, v178
	v_mul_f32_e32 v75, v75, v77
	v_cvt_pk_bf16_f32 v78, v76, s0
	v_lshlrev_b64 v[76:77], 11, v[154:155]
	v_lshl_add_u64 v[76:77], v[130:131], 0, v[76:77]
	v_cvt_pk_bf16_f32 v75, v75, s0
	global_store_short v[76:77], v78, off
	global_store_short v[76:77], v75, off offset:64
	v_mov_b32_e32 v76, v74
	v_mov_b32_e32 v75, v90
	s_nop 0
	v_permlane32_swap_b32_e32 v74, v76
	v_permlane32_swap_b32_e32 v90, v75
	v_cndmask_b32_e32 v74, v74, v76, vcc
	v_cndmask_b32_e32 v75, v90, v75, vcc
	v_add_f32_e32 v74, v105, v74
	v_add_f32_e32 v75, v121, v75
	v_mul_f32_e32 v76, v74, v74
	v_fmac_f32_e32 v76, v75, v75
	v_add_u32_e32 v90, 35, v132
	v_ashrrev_i32_e32 v91, 31, v90
	v_add_f32_dpp v76, v76, v76 quad_perm:[1,0,3,2] row_mask:0xf bank_mask:0xf bound_ctrl:1
	v_add_u32_e32 v78, 49, v132
	v_ashrrev_i32_e32 v79, 31, v78
	v_add_f32_dpp v76, v76, v76 quad_perm:[2,3,0,1] row_mask:0xf bank_mask:0xf bound_ctrl:1
	s_nop 1
	v_add_f32_dpp v76, v76, v76 row_ror:4 row_mask:0xf bank_mask:0xf bound_ctrl:1
	s_nop 1
	v_add_f32_dpp v76, v76, v76 row_ror:8 row_mask:0xf bank_mask:0xf bound_ctrl:1
	v_mov_b32_e32 v77, v76
	s_nop 1
	v_permlane16_swap_b32_e32 v76, v77
	v_add_f32_e32 v76, v76, v77
	v_fmamk_f32 v76, v76, 0x3c800000, v208
	v_rsq_f32_e32 v76, v76
	v_lshlrev_b32_e32 v77, 16, v177
	v_mul_f32_e32 v75, v75, v76
	v_mul_f32_e32 v75, v224, v75
	v_mul_f32_e32 v74, v74, v76
	v_mul_f32_e32 v75, v75, v77
	v_mul_f32_e32 v74, v189, v74
	v_lshlrev_b32_e32 v76, 16, v176
	v_mul_f32_e32 v76, v74, v76
	v_cvt_pk_bf16_f32 v77, v75, s0
	v_lshlrev_b64 v[74:75], 11, v[152:153]
	v_lshl_add_u64 v[74:75], v[130:131], 0, v[74:75]
	v_cvt_pk_bf16_f32 v76, v76, s0
	global_store_short v[74:75], v77, off
	global_store_short v[74:75], v76, off offset:64
	v_mov_b32_e32 v75, v73
	v_mov_b32_e32 v74, v89
	s_nop 0
	v_permlane32_swap_b32_e32 v73, v75
	v_permlane32_swap_b32_e32 v89, v74
	v_cndmask_b32_e32 v73, v73, v75, vcc
	v_cndmask_b32_e32 v74, v89, v74, vcc
	v_add_f32_e32 v73, v106, v73
	v_add_f32_e32 v74, v122, v74
	v_mul_f32_e32 v75, v73, v73
	v_fmac_f32_e32 v75, v74, v74
	s_nop 1
	v_add_f32_dpp v75, v75, v75 quad_perm:[1,0,3,2] row_mask:0xf bank_mask:0xf bound_ctrl:1
	s_nop 1
	v_add_f32_dpp v75, v75, v75 quad_perm:[2,3,0,1] row_mask:0xf bank_mask:0xf bound_ctrl:1
	s_nop 1
	v_add_f32_dpp v75, v75, v75 row_ror:4 row_mask:0xf bank_mask:0xf bound_ctrl:1
	s_nop 1
	v_add_f32_dpp v75, v75, v75 row_ror:8 row_mask:0xf bank_mask:0xf bound_ctrl:1
	v_mov_b32_e32 v76, v75
	s_nop 1
	v_permlane16_swap_b32_e32 v75, v76
	v_add_f32_e32 v75, v75, v76
	v_fmamk_f32 v75, v75, 0x3c800000, v208
	v_rsq_f32_e32 v75, v75
	v_lshlrev_b32_e32 v76, 16, v175
	v_mul_f32_e32 v74, v74, v75
	v_mul_f32_e32 v74, v224, v74
	v_mul_f32_e32 v73, v73, v75
	v_mul_f32_e32 v74, v74, v76
	v_mul_f32_e32 v73, v189, v73
	v_lshlrev_b32_e32 v75, 16, v174
	v_mul_f32_e32 v73, v73, v75
	v_cvt_pk_bf16_f32 v76, v74, s0
	v_lshlrev_b64 v[74:75], 11, v[150:151]
	v_lshl_add_u64 v[74:75], v[130:131], 0, v[74:75]
	v_cvt_pk_bf16_f32 v73, v73, s0
	global_store_short v[74:75], v76, off
	global_store_short v[74:75], v73, off offset:64
	v_mov_b32_e32 v74, v72
	v_mov_b32_e32 v73, v88
	s_nop 0
	v_permlane32_swap_b32_e32 v72, v74
	v_permlane32_swap_b32_e32 v88, v73
	v_cndmask_b32_e32 v72, v72, v74, vcc
	v_cndmask_b32_e32 v73, v88, v73, vcc
	v_add_f32_e32 v72, v107, v72
	v_add_f32_e32 v73, v123, v73
	v_mul_f32_e32 v74, v72, v72
	v_fmac_f32_e32 v74, v73, v73
	v_add_u32_e32 v88, 40, v132
	v_ashrrev_i32_e32 v89, 31, v88
	v_add_f32_dpp v74, v74, v74 quad_perm:[1,0,3,2] row_mask:0xf bank_mask:0xf bound_ctrl:1
	v_add_u32_e32 v76, 50, v132
	v_ashrrev_i32_e32 v77, 31, v76
	v_add_f32_dpp v74, v74, v74 quad_perm:[2,3,0,1] row_mask:0xf bank_mask:0xf bound_ctrl:1
	s_nop 1
	v_add_f32_dpp v74, v74, v74 row_ror:4 row_mask:0xf bank_mask:0xf bound_ctrl:1
	s_nop 1
	v_add_f32_dpp v74, v74, v74 row_ror:8 row_mask:0xf bank_mask:0xf bound_ctrl:1
	v_mov_b32_e32 v75, v74
	s_nop 1
	v_permlane16_swap_b32_e32 v74, v75
	v_add_f32_e32 v74, v74, v75
	v_fmamk_f32 v74, v74, 0x3c800000, v208
	v_rsq_f32_e32 v74, v74
	v_lshlrev_b32_e32 v75, 16, v173
	v_mul_f32_e32 v73, v73, v74
	v_mul_f32_e32 v73, v224, v73
	v_mul_f32_e32 v72, v72, v74
	v_mul_f32_e32 v73, v73, v75
	v_mul_f32_e32 v72, v189, v72
	v_lshlrev_b32_e32 v74, 16, v172
	v_mul_f32_e32 v74, v72, v74
	v_cvt_pk_bf16_f32 v75, v73, s0
	v_lshlrev_b64 v[72:73], 11, v[148:149]
	v_lshl_add_u64 v[72:73], v[130:131], 0, v[72:73]
	v_cvt_pk_bf16_f32 v74, v74, s0
	global_store_short v[72:73], v75, off
	global_store_short v[72:73], v74, off offset:64
	v_mov_b32_e32 v73, v71
	v_mov_b32_e32 v72, v87
	s_nop 0
	v_permlane32_swap_b32_e32 v71, v73
	v_permlane32_swap_b32_e32 v87, v72
	v_cndmask_b32_e32 v71, v71, v73, vcc
	v_cndmask_b32_e32 v72, v87, v72, vcc
	v_add_f32_e32 v71, v108, v71
	v_add_f32_e32 v72, v124, v72
	v_mul_f32_e32 v73, v71, v71
	v_fmac_f32_e32 v73, v72, v72
	s_nop 1
	v_add_f32_dpp v73, v73, v73 quad_perm:[1,0,3,2] row_mask:0xf bank_mask:0xf bound_ctrl:1
	s_nop 1
	v_add_f32_dpp v73, v73, v73 quad_perm:[2,3,0,1] row_mask:0xf bank_mask:0xf bound_ctrl:1
	s_nop 1
	v_add_f32_dpp v73, v73, v73 row_ror:4 row_mask:0xf bank_mask:0xf bound_ctrl:1
	s_nop 1
	v_add_f32_dpp v73, v73, v73 row_ror:8 row_mask:0xf bank_mask:0xf bound_ctrl:1
	v_mov_b32_e32 v74, v73
	s_nop 1
	v_permlane16_swap_b32_e32 v73, v74
	v_add_f32_e32 v73, v73, v74
	v_fmamk_f32 v73, v73, 0x3c800000, v208
	v_rsq_f32_e32 v73, v73
	v_lshlrev_b32_e32 v74, 16, v171
	v_mul_f32_e32 v72, v72, v73
	v_mul_f32_e32 v72, v224, v72
	v_mul_f32_e32 v71, v71, v73
	v_mul_f32_e32 v72, v72, v74
	v_mul_f32_e32 v71, v189, v71
	v_lshlrev_b32_e32 v73, 16, v170
	v_mul_f32_e32 v71, v71, v73
	v_cvt_pk_bf16_f32 v74, v72, s0
	v_lshlrev_b64 v[72:73], 11, v[146:147]
	v_lshl_add_u64 v[72:73], v[130:131], 0, v[72:73]
	v_cvt_pk_bf16_f32 v71, v71, s0
	global_store_short v[72:73], v74, off
	global_store_short v[72:73], v71, off offset:64
	v_mov_b32_e32 v72, v70
	v_mov_b32_e32 v71, v86
	s_nop 0
	v_permlane32_swap_b32_e32 v70, v72
	v_permlane32_swap_b32_e32 v86, v71
	v_cndmask_b32_e32 v70, v70, v72, vcc
	v_cndmask_b32_e32 v71, v86, v71, vcc
	v_add_f32_e32 v70, v109, v70
	v_add_f32_e32 v71, v125, v71
	v_mul_f32_e32 v72, v70, v70
	v_fmac_f32_e32 v72, v71, v71
	v_add_u32_e32 v86, 41, v132
	v_ashrrev_i32_e32 v87, 31, v86
	v_add_f32_dpp v72, v72, v72 quad_perm:[1,0,3,2] row_mask:0xf bank_mask:0xf bound_ctrl:1
	v_add_u32_e32 v74, 51, v132
	v_ashrrev_i32_e32 v75, 31, v74
	v_add_f32_dpp v72, v72, v72 quad_perm:[2,3,0,1] row_mask:0xf bank_mask:0xf bound_ctrl:1
	s_nop 1
	v_add_f32_dpp v72, v72, v72 row_ror:4 row_mask:0xf bank_mask:0xf bound_ctrl:1
	s_nop 1
	v_add_f32_dpp v72, v72, v72 row_ror:8 row_mask:0xf bank_mask:0xf bound_ctrl:1
	v_mov_b32_e32 v73, v72
	s_nop 1
	v_permlane16_swap_b32_e32 v72, v73
	v_add_f32_e32 v72, v72, v73
	v_fmamk_f32 v72, v72, 0x3c800000, v208
	v_rsq_f32_e32 v72, v72
	v_lshlrev_b32_e32 v73, 16, v169
	v_mul_f32_e32 v71, v71, v72
	v_mul_f32_e32 v71, v224, v71
	v_mul_f32_e32 v70, v70, v72
	v_mul_f32_e32 v71, v71, v73
	v_mul_f32_e32 v70, v189, v70
	v_lshlrev_b32_e32 v72, 16, v168
	v_mul_f32_e32 v72, v70, v72
	v_cvt_pk_bf16_f32 v73, v71, s0
	v_lshlrev_b64 v[70:71], 11, v[144:145]
	v_lshl_add_u64 v[70:71], v[130:131], 0, v[70:71]
	v_cvt_pk_bf16_f32 v72, v72, s0
	global_store_short v[70:71], v73, off
	global_store_short v[70:71], v72, off offset:64
	v_mov_b32_e32 v71, v69
	v_mov_b32_e32 v70, v85
	s_nop 0
	v_permlane32_swap_b32_e32 v69, v71
	v_permlane32_swap_b32_e32 v85, v70
	v_cndmask_b32_e32 v69, v69, v71, vcc
	v_cndmask_b32_e32 v70, v85, v70, vcc
	v_add_f32_e32 v69, v110, v69
	v_add_f32_e32 v70, v126, v70
	v_mul_f32_e32 v71, v69, v69
	v_fmac_f32_e32 v71, v70, v70
	s_nop 1
	v_add_f32_dpp v71, v71, v71 quad_perm:[1,0,3,2] row_mask:0xf bank_mask:0xf bound_ctrl:1
	s_nop 1
	v_add_f32_dpp v71, v71, v71 quad_perm:[2,3,0,1] row_mask:0xf bank_mask:0xf bound_ctrl:1
	s_nop 1
	v_add_f32_dpp v71, v71, v71 row_ror:4 row_mask:0xf bank_mask:0xf bound_ctrl:1
	s_nop 1
	v_add_f32_dpp v71, v71, v71 row_ror:8 row_mask:0xf bank_mask:0xf bound_ctrl:1
	v_mov_b32_e32 v72, v71
	s_nop 1
	v_permlane16_swap_b32_e32 v71, v72
	v_add_f32_e32 v71, v71, v72
	v_fmamk_f32 v71, v71, 0x3c800000, v208
	v_rsq_f32_e32 v71, v71
	v_lshlrev_b32_e32 v72, 16, v167
	v_mul_f32_e32 v70, v70, v71
	v_mul_f32_e32 v70, v224, v70
	v_mul_f32_e32 v69, v69, v71
	v_mul_f32_e32 v70, v70, v72
	v_mul_f32_e32 v69, v189, v69
	v_lshlrev_b32_e32 v71, 16, v166
	v_mul_f32_e32 v69, v69, v71
	v_cvt_pk_bf16_f32 v72, v70, s0
	v_lshlrev_b64 v[70:71], 11, v[142:143]
	v_lshl_add_u64 v[70:71], v[130:131], 0, v[70:71]
	v_cvt_pk_bf16_f32 v69, v69, s0
	global_store_short v[70:71], v72, off
	global_store_short v[70:71], v69, off offset:64
	v_mov_b32_e32 v70, v68
	v_mov_b32_e32 v69, v84
	s_nop 0
	v_permlane32_swap_b32_e32 v68, v70
	v_permlane32_swap_b32_e32 v84, v69
	v_cndmask_b32_e32 v68, v68, v70, vcc
	v_cndmask_b32_e32 v69, v84, v69, vcc
	v_add_f32_e32 v68, v111, v68
	v_add_f32_e32 v69, v127, v69
	v_mul_f32_e32 v70, v68, v68
	v_fmac_f32_e32 v70, v69, v69
	v_add_u32_e32 v84, 42, v132
	v_ashrrev_i32_e32 v85, 31, v84
	v_add_f32_dpp v70, v70, v70 quad_perm:[1,0,3,2] row_mask:0xf bank_mask:0xf bound_ctrl:1
	v_add_u32_e32 v72, 56, v132
	v_ashrrev_i32_e32 v73, 31, v72
	v_add_f32_dpp v70, v70, v70 quad_perm:[2,3,0,1] row_mask:0xf bank_mask:0xf bound_ctrl:1
	s_nop 1
	v_add_f32_dpp v70, v70, v70 row_ror:4 row_mask:0xf bank_mask:0xf bound_ctrl:1
	s_nop 1
	v_add_f32_dpp v70, v70, v70 row_ror:8 row_mask:0xf bank_mask:0xf bound_ctrl:1
	v_mov_b32_e32 v71, v70
	s_nop 1
	v_permlane16_swap_b32_e32 v70, v71
	v_add_f32_e32 v70, v70, v71
	v_fmamk_f32 v70, v70, 0x3c800000, v208
	v_rsq_f32_e32 v70, v70
	v_lshlrev_b32_e32 v71, 16, v133
	v_mul_f32_e32 v69, v69, v70
	v_mul_f32_e32 v69, v224, v69
	v_mul_f32_e32 v68, v68, v70
	v_mul_f32_e32 v69, v69, v71
	v_mul_f32_e32 v68, v189, v68
	v_lshlrev_b32_e32 v70, 16, v114
	v_mul_f32_e32 v70, v68, v70
	v_cvt_pk_bf16_f32 v71, v69, s0
	v_lshlrev_b64 v[68:69], 11, v[140:141]
	v_lshl_add_u64 v[68:69], v[130:131], 0, v[68:69]
	v_cvt_pk_bf16_f32 v70, v70, s0
	global_store_short v[68:69], v71, off
	global_store_short v[68:69], v70, off offset:64
	v_mov_b32_e32 v69, v67
	v_mov_b32_e32 v68, v83
	s_nop 0
	v_permlane32_swap_b32_e32 v67, v69
	v_permlane32_swap_b32_e32 v83, v68
	v_cndmask_b32_e32 v67, v67, v69, vcc
	v_cndmask_b32_e32 v68, v83, v68, vcc
	v_add_f32_e32 v67, v112, v67
	v_add_f32_e32 v68, v128, v68
	v_mul_f32_e32 v69, v67, v67
	v_fmac_f32_e32 v69, v68, v68
	s_nop 1
	v_add_f32_dpp v69, v69, v69 quad_perm:[1,0,3,2] row_mask:0xf bank_mask:0xf bound_ctrl:1
	s_nop 1
	v_add_f32_dpp v69, v69, v69 quad_perm:[2,3,0,1] row_mask:0xf bank_mask:0xf bound_ctrl:1
	s_nop 1
	v_add_f32_dpp v69, v69, v69 row_ror:4 row_mask:0xf bank_mask:0xf bound_ctrl:1
	s_nop 1
	v_add_f32_dpp v69, v69, v69 row_ror:8 row_mask:0xf bank_mask:0xf bound_ctrl:1
	v_mov_b32_e32 v70, v69
	s_nop 1
	v_permlane16_swap_b32_e32 v69, v70
	v_add_f32_e32 v69, v69, v70
	v_fmamk_f32 v69, v69, 0x3c800000, v208
	v_rsq_f32_e32 v69, v69
	v_lshlrev_b32_e32 v70, 16, v98
	v_mul_f32_e32 v68, v68, v69
	v_mul_f32_e32 v68, v224, v68
	v_mul_f32_e32 v67, v67, v69
	v_mul_f32_e32 v68, v68, v70
	v_mul_f32_e32 v67, v189, v67
	v_lshlrev_b32_e32 v69, 16, v97
	v_mul_f32_e32 v67, v67, v69
	v_cvt_pk_bf16_f32 v70, v68, s0
	v_lshlrev_b64 v[68:69], 11, v[138:139]
	v_lshl_add_u64 v[68:69], v[130:131], 0, v[68:69]
	v_cvt_pk_bf16_f32 v67, v67, s0
	global_store_short v[68:69], v70, off
	global_store_short v[68:69], v67, off offset:64
	v_mov_b32_e32 v68, v66
	v_mov_b32_e32 v67, v82
	s_nop 0
	v_permlane32_swap_b32_e32 v66, v68
	v_permlane32_swap_b32_e32 v82, v67
	v_cndmask_b32_e32 v66, v66, v68, vcc
	v_cndmask_b32_e32 v67, v82, v67, vcc
	v_add_f32_e32 v66, v113, v66
	v_add_f32_e32 v67, v129, v67
	v_mul_f32_e32 v68, v66, v66
	v_fmac_f32_e32 v68, v67, v67
	v_ashrrev_i32_e32 v97, 31, v96
	v_add_u32_e32 v82, 43, v132
	v_add_f32_dpp v68, v68, v68 quad_perm:[1,0,3,2] row_mask:0xf bank_mask:0xf bound_ctrl:1
	v_ashrrev_i32_e32 v83, 31, v82
	v_add_u32_e32 v70, 57, v132
	v_add_f32_dpp v68, v68, v68 quad_perm:[2,3,0,1] row_mask:0xf bank_mask:0xf bound_ctrl:1
	v_ashrrev_i32_e32 v71, 31, v70
	s_nop 0
	v_add_f32_dpp v68, v68, v68 row_ror:4 row_mask:0xf bank_mask:0xf bound_ctrl:1
	s_nop 1
	v_add_f32_dpp v68, v68, v68 row_ror:8 row_mask:0xf bank_mask:0xf bound_ctrl:1
	v_mov_b32_e32 v69, v68
	s_nop 1
	v_permlane16_swap_b32_e32 v68, v69
	v_add_f32_e32 v68, v68, v69
	v_fmamk_f32 v68, v68, 0x3c800000, v208
	v_rsq_f32_e32 v68, v68
	v_lshlrev_b32_e32 v69, 16, v81
	v_ashrrev_i32_e32 v81, 31, v80
	v_mul_f32_e32 v67, v67, v68
	v_mul_f32_e32 v67, v224, v67
	v_mul_f32_e32 v66, v66, v68
	v_mul_f32_e32 v67, v67, v69
	v_mul_f32_e32 v66, v189, v66
	v_mul_f32_e32 v0, v66, v0
	v_cvt_pk_bf16_f32 v68, v67, s0
	v_lshlrev_b64 v[66:67], 11, v[136:137]
	v_lshl_add_u64 v[66:67], v[130:131], 0, v[66:67]
	v_cvt_pk_bf16_f32 v0, v0, s0
	global_store_short v[66:67], v68, off
	global_store_short v[66:67], v0, off offset:64
	v_lshlrev_b64 v[66:67], 9, v[96:97]
	v_lshl_add_u64 v[102:103], v[134:135], 0, v[66:67]
	v_lshlrev_b64 v[66:67], 9, v[94:95]
	v_lshl_add_u64 v[98:99], v[134:135], 0, v[66:67]
	v_lshlrev_b64 v[66:67], 9, v[92:93]
	v_lshl_add_u64 v[100:101], v[134:135], 0, v[66:67]
	v_lshlrev_b64 v[66:67], 9, v[90:91]
	v_lshl_add_u64 v[104:105], v[134:135], 0, v[66:67]
	v_lshlrev_b64 v[66:67], 9, v[88:89]
	v_lshl_add_u64 v[106:107], v[134:135], 0, v[66:67]
	v_lshlrev_b64 v[66:67], 9, v[86:87]
	v_lshl_add_u64 v[108:109], v[134:135], 0, v[66:67]
	v_lshlrev_b64 v[66:67], 9, v[84:85]
	v_lshl_add_u64 v[110:111], v[134:135], 0, v[66:67]
	v_lshlrev_b64 v[66:67], 9, v[82:83]
	v_lshl_add_u64 v[112:113], v[134:135], 0, v[66:67]
	v_lshlrev_b64 v[66:67], 9, v[80:81]
	v_lshl_add_u64 v[114:115], v[134:135], 0, v[66:67]
	v_lshlrev_b64 v[66:67], 9, v[78:79]
	v_lshl_add_u64 v[116:117], v[134:135], 0, v[66:67]
	v_lshlrev_b64 v[66:67], 9, v[76:77]
	v_lshl_add_u64 v[118:119], v[134:135], 0, v[66:67]
	v_lshlrev_b64 v[66:67], 9, v[74:75]
	v_lshl_add_u64 v[120:121], v[134:135], 0, v[66:67]
	v_lshlrev_b64 v[66:67], 9, v[72:73]
	v_add_u32_e32 v68, 58, v132
	v_lshl_add_u64 v[122:123], v[134:135], 0, v[66:67]
	v_lshlrev_b64 v[66:67], 9, v[70:71]
	v_ashrrev_i32_e32 v69, 31, v68
	v_lshl_add_u64 v[124:125], v[134:135], 0, v[66:67]
	v_lshlrev_b64 v[66:67], 9, v[68:69]
	v_lshl_add_u64 v[126:127], v[134:135], 0, v[66:67]
	v_add_u32_e32 v66, 59, v132
	v_mov_b32_e32 v132, v17
	v_mov_b32_e32 v0, v33
	s_nop 0
	v_permlane32_swap_b32_e32 v17, v132
	v_permlane32_swap_b32_e32 v33, v0
	v_cndmask_b32_e32 v17, v17, v132, vcc
	v_cndmask_b32_e32 v0, v33, v0, vcc
	v_add_f32_e32 v17, v34, v17
	v_add_f32_e32 v0, v50, v0
	v_mul_f32_e32 v33, v17, v17
	v_fmac_f32_e32 v33, v0, v0
	v_ashrrev_i32_e32 v67, 31, v66
	v_lshlrev_b64 v[128:129], 9, v[66:67]
	v_add_f32_dpp v33, v33, v33 quad_perm:[1,0,3,2] row_mask:0xf bank_mask:0xf bound_ctrl:1
	v_lshlrev_b64 v[96:97], 11, v[96:97]
	v_lshl_add_u64 v[128:129], v[134:135], 0, v[128:129]
	v_add_f32_dpp v33, v33, v33 quad_perm:[2,3,0,1] row_mask:0xf bank_mask:0xf bound_ctrl:1
	v_lshl_add_u64 v[140:141], v[130:131], 0, v[96:97]
	v_lshlrev_b64 v[94:95], 11, v[94:95]
	v_add_f32_dpp v33, v33, v33 row_ror:4 row_mask:0xf bank_mask:0xf bound_ctrl:1
	v_lshl_add_u64 v[94:95], v[130:131], 0, v[94:95]
	v_lshlrev_b64 v[92:93], 11, v[92:93]
	v_add_f32_dpp v33, v33, v33 row_ror:8 row_mask:0xf bank_mask:0xf bound_ctrl:1
	v_mov_b32_e32 v34, v33
	s_nop 1
	v_permlane16_swap_b32_e32 v33, v34
	v_add_f32_e32 v33, v33, v34
	v_fmamk_f32 v33, v33, 0x3c800000, v208
	v_rsq_f32_e32 v33, v33
	global_load_ushort v34, v[102:103], off
	v_lshl_add_u64 v[92:93], v[130:131], 0, v[92:93]
	v_mul_f32_e32 v0, v0, v33
	v_mul_f32_e32 v17, v17, v33
	global_load_ushort v33, v[102:103], off offset:64
	v_mul_f32_e32 v0, v224, v0
	v_mul_f32_e32 v17, v189, v17
	s_waitcnt vmcnt(1)
	v_lshlrev_b32_e32 v34, 16, v34
	v_mul_f32_e32 v0, v0, v34
	v_cvt_pk_bf16_f32 v142, v0, s0
	s_waitcnt vmcnt(0)
	v_lshlrev_b32_e32 v33, 16, v33
	v_mul_f32_e32 v139, v17, v33
	global_load_ushort v143, v[98:99], off
	global_load_ushort v144, v[98:99], off offset:64
	global_load_ushort v145, v[100:101], off
	global_load_ushort v146, v[100:101], off offset:64
	global_load_ushort v138, v[104:105], off
	global_load_ushort v137, v[104:105], off offset:64
	global_load_ushort v136, v[106:107], off
	global_load_ushort v135, v[106:107], off offset:64
	global_load_ushort v134, v[108:109], off
	global_load_ushort v133, v[108:109], off offset:64
	global_load_ushort v132, v[110:111], off
	s_nop 0
	global_load_ushort v109, v[110:111], off offset:64
	global_load_ushort v108, v[112:113], off
	global_load_ushort v107, v[112:113], off offset:64
	global_load_ushort v106, v[114:115], off
	global_load_ushort v105, v[114:115], off offset:64
	global_load_ushort v104, v[116:117], off
	global_load_ushort v103, v[116:117], off offset:64
	global_load_ushort v102, v[118:119], off
	global_load_ushort v101, v[118:119], off offset:64
	global_load_ushort v100, v[120:121], off
	global_load_ushort v99, v[120:121], off offset:64
	global_load_ushort v98, v[122:123], off
	global_load_ushort v97, v[122:123], off offset:64
	global_load_ushort v96, v[124:125], off
	global_load_ushort v50, v[124:125], off offset:64
	global_load_ushort v34, v[126:127], off
	global_load_ushort v33, v[126:127], off offset:64
	global_load_ushort v17, v[128:129], off
	global_load_ushort v0, v[128:129], off offset:64
	v_cvt_pk_bf16_f32 v110, v139, s0
	v_mov_b32_e32 v111, v16
	global_store_short v[140:141], v110, off offset:64
	v_mov_b32_e32 v110, v32
	v_permlane32_swap_b32_e32 v16, v111
	s_nop 0
	v_permlane32_swap_b32_e32 v32, v110
	v_cndmask_b32_e32 v16, v16, v111, vcc
	v_cndmask_b32_e32 v32, v32, v110, vcc
	v_add_f32_e32 v16, v35, v16
	v_add_f32_e32 v32, v51, v32
	v_mul_f32_e32 v35, v16, v16
	v_fmac_f32_e32 v35, v32, v32
	global_store_short v[140:141], v142, off
	s_waitcnt vmcnt(2)
	v_lshlrev_b32_e32 v0, 16, v0
	v_add_f32_dpp v35, v35, v35 quad_perm:[1,0,3,2] row_mask:0xf bank_mask:0xf bound_ctrl:1
	s_nop 1
	v_add_f32_dpp v35, v35, v35 quad_perm:[2,3,0,1] row_mask:0xf bank_mask:0xf bound_ctrl:1
	s_nop 1
	v_add_f32_dpp v35, v35, v35 row_ror:4 row_mask:0xf bank_mask:0xf bound_ctrl:1
	s_nop 1
	v_add_f32_dpp v35, v35, v35 row_ror:8 row_mask:0xf bank_mask:0xf bound_ctrl:1
	v_mov_b32_e32 v51, v35
	s_nop 1
	v_permlane16_swap_b32_e32 v35, v51
	v_add_f32_e32 v35, v35, v51
	v_fmamk_f32 v35, v35, 0x3c800000, v208
	v_rsq_f32_e32 v35, v35
	v_lshlrev_b32_e32 v51, 16, v143
	v_mul_f32_e32 v32, v32, v35
	v_mul_f32_e32 v32, v224, v32
	v_mul_f32_e32 v16, v16, v35
	v_mul_f32_e32 v32, v32, v51
	v_mul_f32_e32 v16, v189, v16
	v_lshlrev_b32_e32 v35, 16, v144
	v_mul_f32_e32 v16, v16, v35
	v_cvt_pk_bf16_f32 v32, v32, s0
	global_store_short v[94:95], v32, off
	v_cvt_pk_bf16_f32 v16, v16, s0
	v_mov_b32_e32 v32, v15
	global_store_short v[94:95], v16, off offset:64
	v_mov_b32_e32 v16, v31
	v_permlane32_swap_b32_e32 v15, v32
	s_nop 0
	v_permlane32_swap_b32_e32 v31, v16
	v_cndmask_b32_e32 v15, v15, v32, vcc
	v_cndmask_b32_e32 v16, v31, v16, vcc
	v_add_f32_e32 v15, v36, v15
	v_add_f32_e32 v16, v52, v16
	v_mul_f32_e32 v31, v15, v15
	v_fmac_f32_e32 v31, v16, v16
	s_nop 1
	v_add_f32_dpp v31, v31, v31 quad_perm:[1,0,3,2] row_mask:0xf bank_mask:0xf bound_ctrl:1
	s_nop 1
	v_add_f32_dpp v31, v31, v31 quad_perm:[2,3,0,1] row_mask:0xf bank_mask:0xf bound_ctrl:1
	s_nop 1
	v_add_f32_dpp v31, v31, v31 row_ror:4 row_mask:0xf bank_mask:0xf bound_ctrl:1
	s_nop 1
	v_add_f32_dpp v31, v31, v31 row_ror:8 row_mask:0xf bank_mask:0xf bound_ctrl:1
	v_mov_b32_e32 v32, v31
	s_nop 1
	v_permlane16_swap_b32_e32 v31, v32
	v_add_f32_e32 v31, v31, v32
	v_fmamk_f32 v31, v31, 0x3c800000, v208
	v_rsq_f32_e32 v31, v31
	v_lshlrev_b32_e32 v32, 16, v145
	v_mul_f32_e32 v16, v16, v31
	v_mul_f32_e32 v16, v224, v16
	v_mul_f32_e32 v15, v15, v31
	v_mul_f32_e32 v16, v16, v32
	v_mul_f32_e32 v15, v189, v15
	v_lshlrev_b32_e32 v31, 16, v146
	v_mul_f32_e32 v15, v15, v31
	v_cvt_pk_bf16_f32 v16, v16, s0
	global_store_short v[92:93], v16, off
	v_cvt_pk_bf16_f32 v15, v15, s0
	v_mov_b32_e32 v16, v14
	global_store_short v[92:93], v15, off offset:64
	v_mov_b32_e32 v15, v30
	v_permlane32_swap_b32_e32 v14, v16
	s_nop 0
	v_permlane32_swap_b32_e32 v30, v15
	v_cndmask_b32_e32 v14, v14, v16, vcc
	v_cndmask_b32_e32 v15, v30, v15, vcc
	v_add_f32_e32 v14, v37, v14
	v_add_f32_e32 v15, v53, v15
	v_mul_f32_e32 v16, v14, v14
	v_fmac_f32_e32 v16, v15, v15
	s_nop 1
	v_add_f32_dpp v16, v16, v16 quad_perm:[1,0,3,2] row_mask:0xf bank_mask:0xf bound_ctrl:1
	s_nop 1
	v_add_f32_dpp v16, v16, v16 quad_perm:[2,3,0,1] row_mask:0xf bank_mask:0xf bound_ctrl:1
	s_nop 1
	v_add_f32_dpp v16, v16, v16 row_ror:4 row_mask:0xf bank_mask:0xf bound_ctrl:1
	s_nop 1
	v_add_f32_dpp v16, v16, v16 row_ror:8 row_mask:0xf bank_mask:0xf bound_ctrl:1
	v_mov_b32_e32 v30, v16
	s_nop 1
	v_permlane16_swap_b32_e32 v16, v30
	v_add_f32_e32 v16, v16, v30
	v_fmamk_f32 v16, v16, 0x3c800000, v208
	v_rsq_f32_e32 v16, v16
	v_lshlrev_b32_e32 v30, 16, v138
	v_mul_f32_e32 v15, v15, v16
	v_mul_f32_e32 v15, v224, v15
	v_mul_f32_e32 v14, v14, v16
	v_mul_f32_e32 v15, v15, v30
	v_mul_f32_e32 v14, v189, v14
	v_lshlrev_b32_e32 v16, 16, v137
	v_mul_f32_e32 v16, v14, v16
	v_cvt_pk_bf16_f32 v30, v15, s0
	v_lshlrev_b64 v[14:15], 11, v[90:91]
	v_lshl_add_u64 v[14:15], v[130:131], 0, v[14:15]
	v_cvt_pk_bf16_f32 v16, v16, s0
	global_store_short v[14:15], v30, off
	global_store_short v[14:15], v16, off offset:64
	v_mov_b32_e32 v15, v13
	v_mov_b32_e32 v14, v29
	s_nop 0
	v_permlane32_swap_b32_e32 v13, v15
	v_permlane32_swap_b32_e32 v29, v14
	v_cndmask_b32_e32 v13, v13, v15, vcc
	v_cndmask_b32_e32 v14, v29, v14, vcc
	v_add_f32_e32 v13, v38, v13
	v_add_f32_e32 v14, v54, v14
	v_mul_f32_e32 v15, v13, v13
	v_fmac_f32_e32 v15, v14, v14
	s_nop 1
	v_add_f32_dpp v15, v15, v15 quad_perm:[1,0,3,2] row_mask:0xf bank_mask:0xf bound_ctrl:1
	s_nop 1
	v_add_f32_dpp v15, v15, v15 quad_perm:[2,3,0,1] row_mask:0xf bank_mask:0xf bound_ctrl:1
	s_nop 1
	v_add_f32_dpp v15, v15, v15 row_ror:4 row_mask:0xf bank_mask:0xf bound_ctrl:1
	s_nop 1
	v_add_f32_dpp v15, v15, v15 row_ror:8 row_mask:0xf bank_mask:0xf bound_ctrl:1
	v_mov_b32_e32 v16, v15
	s_nop 1
	v_permlane16_swap_b32_e32 v15, v16
	v_add_f32_e32 v15, v15, v16
	v_fmamk_f32 v15, v15, 0x3c800000, v208
	v_rsq_f32_e32 v15, v15
	v_lshlrev_b32_e32 v16, 16, v136
	v_mul_f32_e32 v14, v14, v15
	v_mul_f32_e32 v14, v224, v14
	v_mul_f32_e32 v13, v13, v15
	v_mul_f32_e32 v14, v14, v16
	v_mul_f32_e32 v13, v189, v13
	v_lshlrev_b32_e32 v15, 16, v135
	v_mul_f32_e32 v13, v13, v15
	v_cvt_pk_bf16_f32 v16, v14, s0
	v_lshlrev_b64 v[14:15], 11, v[88:89]
	v_lshl_add_u64 v[14:15], v[130:131], 0, v[14:15]
	v_cvt_pk_bf16_f32 v13, v13, s0
	global_store_short v[14:15], v16, off
	global_store_short v[14:15], v13, off offset:64
	v_mov_b32_e32 v14, v12
	v_mov_b32_e32 v13, v28
	s_nop 0
	v_permlane32_swap_b32_e32 v12, v14
	v_permlane32_swap_b32_e32 v28, v13
	v_cndmask_b32_e32 v12, v12, v14, vcc
	v_cndmask_b32_e32 v13, v28, v13, vcc
	v_add_f32_e32 v12, v39, v12
	v_add_f32_e32 v13, v55, v13
	v_mul_f32_e32 v14, v12, v12
	v_fmac_f32_e32 v14, v13, v13
	s_nop 1
	v_add_f32_dpp v14, v14, v14 quad_perm:[1,0,3,2] row_mask:0xf bank_mask:0xf bound_ctrl:1
	s_nop 1
	v_add_f32_dpp v14, v14, v14 quad_perm:[2,3,0,1] row_mask:0xf bank_mask:0xf bound_ctrl:1
	s_nop 1
	v_add_f32_dpp v14, v14, v14 row_ror:4 row_mask:0xf bank_mask:0xf bound_ctrl:1
	s_nop 1
	v_add_f32_dpp v14, v14, v14 row_ror:8 row_mask:0xf bank_mask:0xf bound_ctrl:1
	v_mov_b32_e32 v15, v14
	s_nop 1
	v_permlane16_swap_b32_e32 v14, v15
	v_add_f32_e32 v14, v14, v15
	v_fmamk_f32 v14, v14, 0x3c800000, v208
	v_rsq_f32_e32 v14, v14
	v_lshlrev_b32_e32 v15, 16, v134
	v_mul_f32_e32 v13, v13, v14
	v_mul_f32_e32 v13, v224, v13
	v_mul_f32_e32 v12, v12, v14
	v_mul_f32_e32 v13, v13, v15
	v_mul_f32_e32 v12, v189, v12
	v_lshlrev_b32_e32 v14, 16, v133
	v_mul_f32_e32 v14, v12, v14
	v_cvt_pk_bf16_f32 v15, v13, s0
	v_lshlrev_b64 v[12:13], 11, v[86:87]
	v_lshl_add_u64 v[12:13], v[130:131], 0, v[12:13]
	v_cvt_pk_bf16_f32 v14, v14, s0
	global_store_short v[12:13], v15, off
	global_store_short v[12:13], v14, off offset:64
	v_mov_b32_e32 v13, v11
	v_mov_b32_e32 v12, v27
	s_nop 0
	v_permlane32_swap_b32_e32 v11, v13
	v_permlane32_swap_b32_e32 v27, v12
	v_cndmask_b32_e32 v11, v11, v13, vcc
	v_cndmask_b32_e32 v12, v27, v12, vcc
	v_add_f32_e32 v11, v40, v11
	v_add_f32_e32 v12, v56, v12
	v_mul_f32_e32 v13, v11, v11
	v_fmac_f32_e32 v13, v12, v12
	s_nop 1
	v_add_f32_dpp v13, v13, v13 quad_perm:[1,0,3,2] row_mask:0xf bank_mask:0xf bound_ctrl:1
	s_nop 1
	v_add_f32_dpp v13, v13, v13 quad_perm:[2,3,0,1] row_mask:0xf bank_mask:0xf bound_ctrl:1
	s_nop 1
	v_add_f32_dpp v13, v13, v13 row_ror:4 row_mask:0xf bank_mask:0xf bound_ctrl:1
	s_nop 1
	v_add_f32_dpp v13, v13, v13 row_ror:8 row_mask:0xf bank_mask:0xf bound_ctrl:1
	v_mov_b32_e32 v14, v13
	s_nop 1
	v_permlane16_swap_b32_e32 v13, v14
	v_add_f32_e32 v13, v13, v14
	v_fmamk_f32 v13, v13, 0x3c800000, v208
	v_rsq_f32_e32 v13, v13
	v_lshlrev_b32_e32 v14, 16, v132
	v_mul_f32_e32 v12, v12, v13
	v_mul_f32_e32 v12, v224, v12
	v_mul_f32_e32 v11, v11, v13
	v_mul_f32_e32 v12, v12, v14
	v_mul_f32_e32 v11, v189, v11
	v_lshlrev_b32_e32 v13, 16, v109
	v_mul_f32_e32 v11, v11, v13
	v_cvt_pk_bf16_f32 v14, v12, s0
	v_lshlrev_b64 v[12:13], 11, v[84:85]
	v_lshl_add_u64 v[12:13], v[130:131], 0, v[12:13]
	v_cvt_pk_bf16_f32 v11, v11, s0
	global_store_short v[12:13], v14, off
	global_store_short v[12:13], v11, off offset:64
	v_mov_b32_e32 v12, v10
	v_mov_b32_e32 v11, v26
	s_nop 0
	v_permlane32_swap_b32_e32 v10, v12
	v_permlane32_swap_b32_e32 v26, v11
	v_cndmask_b32_e32 v10, v10, v12, vcc
	v_cndmask_b32_e32 v11, v26, v11, vcc
	v_add_f32_e32 v10, v41, v10
	v_add_f32_e32 v11, v57, v11
	v_mul_f32_e32 v12, v10, v10
	v_fmac_f32_e32 v12, v11, v11
	s_nop 1
	v_add_f32_dpp v12, v12, v12 quad_perm:[1,0,3,2] row_mask:0xf bank_mask:0xf bound_ctrl:1
	s_nop 1
	v_add_f32_dpp v12, v12, v12 quad_perm:[2,3,0,1] row_mask:0xf bank_mask:0xf bound_ctrl:1
	s_nop 1
	v_add_f32_dpp v12, v12, v12 row_ror:4 row_mask:0xf bank_mask:0xf bound_ctrl:1
	s_nop 1
	v_add_f32_dpp v12, v12, v12 row_ror:8 row_mask:0xf bank_mask:0xf bound_ctrl:1
	v_mov_b32_e32 v13, v12
	s_nop 1
	v_permlane16_swap_b32_e32 v12, v13
	v_add_f32_e32 v12, v12, v13
	v_fmamk_f32 v12, v12, 0x3c800000, v208
	v_rsq_f32_e32 v12, v12
	v_lshlrev_b32_e32 v13, 16, v108
	v_mul_f32_e32 v11, v11, v12
	v_mul_f32_e32 v11, v224, v11
	v_mul_f32_e32 v10, v10, v12
	v_mul_f32_e32 v11, v11, v13
	v_mul_f32_e32 v10, v189, v10
	v_lshlrev_b32_e32 v12, 16, v107
	v_mul_f32_e32 v12, v10, v12
	v_cvt_pk_bf16_f32 v13, v11, s0
	v_lshlrev_b64 v[10:11], 11, v[82:83]
	v_lshl_add_u64 v[10:11], v[130:131], 0, v[10:11]
	v_cvt_pk_bf16_f32 v12, v12, s0
	global_store_short v[10:11], v13, off
	global_store_short v[10:11], v12, off offset:64
	v_mov_b32_e32 v11, v9
	v_mov_b32_e32 v10, v25
	s_nop 0
	v_permlane32_swap_b32_e32 v9, v11
	v_permlane32_swap_b32_e32 v25, v10
	v_cndmask_b32_e32 v9, v9, v11, vcc
	v_cndmask_b32_e32 v10, v25, v10, vcc
	v_add_f32_e32 v9, v42, v9
	v_add_f32_e32 v10, v58, v10
	v_mul_f32_e32 v11, v9, v9
	v_fmac_f32_e32 v11, v10, v10
	s_nop 1
	v_add_f32_dpp v11, v11, v11 quad_perm:[1,0,3,2] row_mask:0xf bank_mask:0xf bound_ctrl:1
	s_nop 1
	v_add_f32_dpp v11, v11, v11 quad_perm:[2,3,0,1] row_mask:0xf bank_mask:0xf bound_ctrl:1
	s_nop 1
	v_add_f32_dpp v11, v11, v11 row_ror:4 row_mask:0xf bank_mask:0xf bound_ctrl:1
	s_nop 1
	v_add_f32_dpp v11, v11, v11 row_ror:8 row_mask:0xf bank_mask:0xf bound_ctrl:1
	v_mov_b32_e32 v12, v11
	s_nop 1
	v_permlane16_swap_b32_e32 v11, v12
	v_add_f32_e32 v11, v11, v12
	v_fmamk_f32 v11, v11, 0x3c800000, v208
	v_rsq_f32_e32 v11, v11
	v_lshlrev_b32_e32 v12, 16, v106
	v_mul_f32_e32 v10, v10, v11
	v_mul_f32_e32 v10, v224, v10
	v_mul_f32_e32 v9, v9, v11
	v_mul_f32_e32 v10, v10, v12
	v_mul_f32_e32 v9, v189, v9
	v_lshlrev_b32_e32 v11, 16, v105
	v_mul_f32_e32 v9, v9, v11
	v_cvt_pk_bf16_f32 v12, v10, s0
	v_lshlrev_b64 v[10:11], 11, v[80:81]
	v_lshl_add_u64 v[10:11], v[130:131], 0, v[10:11]
	v_cvt_pk_bf16_f32 v9, v9, s0
	global_store_short v[10:11], v12, off
	global_store_short v[10:11], v9, off offset:64
	v_mov_b32_e32 v10, v8
	v_mov_b32_e32 v9, v24
	s_nop 0
	v_permlane32_swap_b32_e32 v8, v10
	v_permlane32_swap_b32_e32 v24, v9
	v_cndmask_b32_e32 v8, v8, v10, vcc
	v_cndmask_b32_e32 v9, v24, v9, vcc
	v_add_f32_e32 v8, v43, v8
	v_add_f32_e32 v9, v59, v9
	v_mul_f32_e32 v10, v8, v8
	v_fmac_f32_e32 v10, v9, v9
	s_nop 1
	v_add_f32_dpp v10, v10, v10 quad_perm:[1,0,3,2] row_mask:0xf bank_mask:0xf bound_ctrl:1
	s_nop 1
	v_add_f32_dpp v10, v10, v10 quad_perm:[2,3,0,1] row_mask:0xf bank_mask:0xf bound_ctrl:1
	s_nop 1
	v_add_f32_dpp v10, v10, v10 row_ror:4 row_mask:0xf bank_mask:0xf bound_ctrl:1
	s_nop 1
	v_add_f32_dpp v10, v10, v10 row_ror:8 row_mask:0xf bank_mask:0xf bound_ctrl:1
	v_mov_b32_e32 v11, v10
	s_nop 1
	v_permlane16_swap_b32_e32 v10, v11
	v_add_f32_e32 v10, v10, v11
	v_fmamk_f32 v10, v10, 0x3c800000, v208
	v_rsq_f32_e32 v10, v10
	v_lshlrev_b32_e32 v11, 16, v104
	v_mul_f32_e32 v9, v9, v10
	v_mul_f32_e32 v9, v224, v9
	v_mul_f32_e32 v8, v8, v10
	v_mul_f32_e32 v9, v9, v11
	v_mul_f32_e32 v8, v189, v8
	v_lshlrev_b32_e32 v10, 16, v103
	v_mul_f32_e32 v10, v8, v10
	v_cvt_pk_bf16_f32 v11, v9, s0
	v_lshlrev_b64 v[8:9], 11, v[78:79]
	v_lshl_add_u64 v[8:9], v[130:131], 0, v[8:9]
	v_cvt_pk_bf16_f32 v10, v10, s0
	global_store_short v[8:9], v11, off
	global_store_short v[8:9], v10, off offset:64
	v_mov_b32_e32 v9, v7
	v_mov_b32_e32 v8, v23
	s_nop 0
	v_permlane32_swap_b32_e32 v7, v9
	v_permlane32_swap_b32_e32 v23, v8
	v_cndmask_b32_e32 v7, v7, v9, vcc
	v_cndmask_b32_e32 v8, v23, v8, vcc
	v_add_f32_e32 v7, v44, v7
	v_add_f32_e32 v8, v60, v8
	v_mul_f32_e32 v9, v7, v7
	v_fmac_f32_e32 v9, v8, v8
	s_nop 1
	v_add_f32_dpp v9, v9, v9 quad_perm:[1,0,3,2] row_mask:0xf bank_mask:0xf bound_ctrl:1
	s_nop 1
	v_add_f32_dpp v9, v9, v9 quad_perm:[2,3,0,1] row_mask:0xf bank_mask:0xf bound_ctrl:1
	s_nop 1
	v_add_f32_dpp v9, v9, v9 row_ror:4 row_mask:0xf bank_mask:0xf bound_ctrl:1
	s_nop 1
	v_add_f32_dpp v9, v9, v9 row_ror:8 row_mask:0xf bank_mask:0xf bound_ctrl:1
	v_mov_b32_e32 v10, v9
	s_nop 1
	v_permlane16_swap_b32_e32 v9, v10
	v_add_f32_e32 v9, v9, v10
	v_fmamk_f32 v9, v9, 0x3c800000, v208
	v_rsq_f32_e32 v9, v9
	v_lshlrev_b32_e32 v10, 16, v102
	v_mul_f32_e32 v8, v8, v9
	v_mul_f32_e32 v8, v224, v8
	v_mul_f32_e32 v7, v7, v9
	v_mul_f32_e32 v8, v8, v10
	v_mul_f32_e32 v7, v189, v7
	v_lshlrev_b32_e32 v9, 16, v101
	v_mul_f32_e32 v7, v7, v9
	v_cvt_pk_bf16_f32 v10, v8, s0
	v_lshlrev_b64 v[8:9], 11, v[76:77]
	v_lshl_add_u64 v[8:9], v[130:131], 0, v[8:9]
	v_cvt_pk_bf16_f32 v7, v7, s0
	global_store_short v[8:9], v10, off
	global_store_short v[8:9], v7, off offset:64
	v_mov_b32_e32 v8, v6
	v_mov_b32_e32 v7, v22
	s_nop 0
	v_permlane32_swap_b32_e32 v6, v8
	v_permlane32_swap_b32_e32 v22, v7
	v_cndmask_b32_e32 v6, v6, v8, vcc
	v_cndmask_b32_e32 v7, v22, v7, vcc
	v_add_f32_e32 v6, v45, v6
	v_add_f32_e32 v7, v61, v7
	v_mul_f32_e32 v8, v6, v6
	v_fmac_f32_e32 v8, v7, v7
	s_nop 1
	v_add_f32_dpp v8, v8, v8 quad_perm:[1,0,3,2] row_mask:0xf bank_mask:0xf bound_ctrl:1
	s_nop 1
	v_add_f32_dpp v8, v8, v8 quad_perm:[2,3,0,1] row_mask:0xf bank_mask:0xf bound_ctrl:1
	s_nop 1
	v_add_f32_dpp v8, v8, v8 row_ror:4 row_mask:0xf bank_mask:0xf bound_ctrl:1
	s_nop 1
	v_add_f32_dpp v8, v8, v8 row_ror:8 row_mask:0xf bank_mask:0xf bound_ctrl:1
	v_mov_b32_e32 v9, v8
	s_nop 1
	v_permlane16_swap_b32_e32 v8, v9
	v_add_f32_e32 v8, v8, v9
	v_fmamk_f32 v8, v8, 0x3c800000, v208
	v_rsq_f32_e32 v8, v8
	v_lshlrev_b32_e32 v9, 16, v100
	v_mul_f32_e32 v7, v7, v8
	v_mul_f32_e32 v7, v224, v7
	v_mul_f32_e32 v6, v6, v8
	v_mul_f32_e32 v7, v7, v9
	v_mul_f32_e32 v6, v189, v6
	v_lshlrev_b32_e32 v8, 16, v99
	v_mul_f32_e32 v8, v6, v8
	v_cvt_pk_bf16_f32 v9, v7, s0
	v_lshlrev_b64 v[6:7], 11, v[74:75]
	v_lshl_add_u64 v[6:7], v[130:131], 0, v[6:7]
	v_cvt_pk_bf16_f32 v8, v8, s0
	global_store_short v[6:7], v9, off
	global_store_short v[6:7], v8, off offset:64
	v_mov_b32_e32 v7, v5
	v_mov_b32_e32 v6, v21
	s_nop 0
	v_permlane32_swap_b32_e32 v5, v7
	v_permlane32_swap_b32_e32 v21, v6
	v_cndmask_b32_e32 v5, v5, v7, vcc
	v_cndmask_b32_e32 v6, v21, v6, vcc
	v_add_f32_e32 v5, v46, v5
	v_add_f32_e32 v6, v62, v6
	v_mul_f32_e32 v7, v5, v5
	v_fmac_f32_e32 v7, v6, v6
	s_nop 1
	v_add_f32_dpp v7, v7, v7 quad_perm:[1,0,3,2] row_mask:0xf bank_mask:0xf bound_ctrl:1
	s_nop 1
	v_add_f32_dpp v7, v7, v7 quad_perm:[2,3,0,1] row_mask:0xf bank_mask:0xf bound_ctrl:1
	s_nop 1
	v_add_f32_dpp v7, v7, v7 row_ror:4 row_mask:0xf bank_mask:0xf bound_ctrl:1
	s_nop 1
	v_add_f32_dpp v7, v7, v7 row_ror:8 row_mask:0xf bank_mask:0xf bound_ctrl:1
	v_mov_b32_e32 v8, v7
	s_nop 1
	v_permlane16_swap_b32_e32 v7, v8
	v_add_f32_e32 v7, v7, v8
	v_fmamk_f32 v7, v7, 0x3c800000, v208
	v_rsq_f32_e32 v7, v7
	v_lshlrev_b32_e32 v8, 16, v98
	v_mul_f32_e32 v6, v6, v7
	v_mul_f32_e32 v6, v224, v6
	v_mul_f32_e32 v5, v5, v7
	v_mul_f32_e32 v6, v6, v8
	v_mul_f32_e32 v5, v189, v5
	v_lshlrev_b32_e32 v7, 16, v97
	v_mul_f32_e32 v5, v5, v7
	v_cvt_pk_bf16_f32 v8, v6, s0
	v_lshlrev_b64 v[6:7], 11, v[72:73]
	v_lshl_add_u64 v[6:7], v[130:131], 0, v[6:7]
	v_cvt_pk_bf16_f32 v5, v5, s0
	global_store_short v[6:7], v8, off
	global_store_short v[6:7], v5, off offset:64
	v_mov_b32_e32 v6, v4
	v_mov_b32_e32 v5, v20
	s_nop 0
	v_permlane32_swap_b32_e32 v4, v6
	v_permlane32_swap_b32_e32 v20, v5
	v_cndmask_b32_e32 v4, v4, v6, vcc
	v_cndmask_b32_e32 v5, v20, v5, vcc
	v_add_f32_e32 v4, v47, v4
	v_add_f32_e32 v5, v63, v5
	v_mul_f32_e32 v6, v4, v4
	v_fmac_f32_e32 v6, v5, v5
	s_nop 1
	v_add_f32_dpp v6, v6, v6 quad_perm:[1,0,3,2] row_mask:0xf bank_mask:0xf bound_ctrl:1
	s_nop 1
	v_add_f32_dpp v6, v6, v6 quad_perm:[2,3,0,1] row_mask:0xf bank_mask:0xf bound_ctrl:1
	s_nop 1
	v_add_f32_dpp v6, v6, v6 row_ror:4 row_mask:0xf bank_mask:0xf bound_ctrl:1
	s_nop 1
	v_add_f32_dpp v6, v6, v6 row_ror:8 row_mask:0xf bank_mask:0xf bound_ctrl:1
	v_mov_b32_e32 v7, v6
	s_nop 1
	v_permlane16_swap_b32_e32 v6, v7
	v_add_f32_e32 v6, v6, v7
	v_fmamk_f32 v6, v6, 0x3c800000, v208
	v_rsq_f32_e32 v6, v6
	v_lshlrev_b32_e32 v7, 16, v96
	v_mul_f32_e32 v5, v5, v6
	v_mul_f32_e32 v5, v224, v5
	v_mul_f32_e32 v4, v4, v6
	v_mul_f32_e32 v5, v5, v7
	v_mul_f32_e32 v4, v189, v4
	v_lshlrev_b32_e32 v6, 16, v50
	v_mul_f32_e32 v6, v4, v6
	v_cvt_pk_bf16_f32 v7, v5, s0
	v_lshlrev_b64 v[4:5], 11, v[70:71]
	v_lshl_add_u64 v[4:5], v[130:131], 0, v[4:5]
	v_cvt_pk_bf16_f32 v6, v6, s0
	global_store_short v[4:5], v7, off
	global_store_short v[4:5], v6, off offset:64
	v_mov_b32_e32 v5, v3
	v_mov_b32_e32 v4, v19
	s_nop 0
	v_permlane32_swap_b32_e32 v3, v5
	v_permlane32_swap_b32_e32 v19, v4
	v_cndmask_b32_e32 v3, v3, v5, vcc
	v_cndmask_b32_e32 v4, v19, v4, vcc
	v_add_f32_e32 v3, v48, v3
	v_add_f32_e32 v4, v64, v4
	v_mul_f32_e32 v5, v3, v3
	v_fmac_f32_e32 v5, v4, v4
	s_nop 1
	v_add_f32_dpp v5, v5, v5 quad_perm:[1,0,3,2] row_mask:0xf bank_mask:0xf bound_ctrl:1
	s_nop 1
	v_add_f32_dpp v5, v5, v5 quad_perm:[2,3,0,1] row_mask:0xf bank_mask:0xf bound_ctrl:1
	s_nop 1
	v_add_f32_dpp v5, v5, v5 row_ror:4 row_mask:0xf bank_mask:0xf bound_ctrl:1
	s_nop 1
	v_add_f32_dpp v5, v5, v5 row_ror:8 row_mask:0xf bank_mask:0xf bound_ctrl:1
	v_mov_b32_e32 v6, v5
	s_nop 1
	v_permlane16_swap_b32_e32 v5, v6
	v_add_f32_e32 v5, v5, v6
	v_fmamk_f32 v5, v5, 0x3c800000, v208
	v_rsq_f32_e32 v5, v5
	v_lshlrev_b32_e32 v6, 16, v34
	v_mul_f32_e32 v4, v4, v5
	v_mul_f32_e32 v4, v224, v4
	v_mul_f32_e32 v3, v3, v5
	v_mul_f32_e32 v4, v4, v6
	v_mul_f32_e32 v3, v189, v3
	v_lshlrev_b32_e32 v5, 16, v33
	v_mul_f32_e32 v3, v3, v5
	v_cvt_pk_bf16_f32 v6, v4, s0
	v_lshlrev_b64 v[4:5], 11, v[68:69]
	v_lshl_add_u64 v[4:5], v[130:131], 0, v[4:5]
	v_cvt_pk_bf16_f32 v3, v3, s0
	global_store_short v[4:5], v3, off offset:64
	v_mov_b32_e32 v3, v2
	global_store_short v[4:5], v6, off
	v_mov_b32_e32 v4, v18
	v_permlane32_swap_b32_e32 v2, v3
	s_nop 0
	v_permlane32_swap_b32_e32 v18, v4
	v_cndmask_b32_e32 v2, v2, v3, vcc
	v_cndmask_b32_e32 v4, v18, v4, vcc
	v_add_f32_e32 v2, v49, v2
	v_add_f32_e32 v4, v65, v4
	v_mul_f32_e32 v3, v2, v2
	v_fmac_f32_e32 v3, v4, v4
	s_nop 1
	v_add_f32_dpp v3, v3, v3 quad_perm:[1,0,3,2] row_mask:0xf bank_mask:0xf bound_ctrl:1
	s_nop 1
	v_add_f32_dpp v3, v3, v3 quad_perm:[2,3,0,1] row_mask:0xf bank_mask:0xf bound_ctrl:1
	s_nop 1
	v_add_f32_dpp v3, v3, v3 row_ror:4 row_mask:0xf bank_mask:0xf bound_ctrl:1
	s_nop 1
	v_add_f32_dpp v3, v3, v3 row_ror:8 row_mask:0xf bank_mask:0xf bound_ctrl:1
	v_mov_b32_e32 v5, v3
	s_nop 1
	v_permlane16_swap_b32_e32 v3, v5
	v_add_f32_e32 v3, v3, v5
	v_fmamk_f32 v3, v3, 0x3c800000, v208
	v_rsq_f32_e32 v3, v3
	v_lshlrev_b32_e32 v5, 16, v17
	v_mul_f32_e32 v4, v4, v3
	v_mul_f32_e32 v4, v224, v4
	v_mul_f32_e32 v2, v2, v3
	v_mul_f32_e32 v4, v4, v5
	v_mul_f32_e32 v2, v189, v2
	v_mul_f32_e32 v0, v2, v0
	v_cvt_pk_bf16_f32 v2, v4, s0
	v_lshlrev_b64 v[4:5], 11, v[66:67]
	v_lshl_add_u64 v[4:5], v[130:131], 0, v[4:5]
	v_cvt_pk_bf16_f32 v0, v0, s0
	global_store_short v[4:5], v2, off
	global_store_short v[4:5], v0, off offset:64
	s_cbranch_scc1 .LBB0_590
	s_mov_b32 s76, 0x5a000
	s_movk_i32 s46, 0xffd0
	s_movk_i32 s50, 0xffc0
	s_mov_b32 s51, 0x41000000
	s_mov_b64 s[48:49], 0xca00100
	v_readlane_b32 s88, v254, 50
	v_readlane_b32 s89, v254, 51

.LBB0_1378:
	s_add_i32 s54, s54, 1
	s_cmp_eq_u32 s54, 15
	s_cselect_b32 s54, s55, s54
	v_readlane_b32 s26, v254, 21
	v_readlane_b32 s36, v254, 25
	v_readlane_b32 s40, v254, 29
	s_cmp_ge_i32 s54, s55
	v_readlane_b32 s27, v254, 22
	v_readlane_b32 s37, v254, 26
	v_readlane_b32 s41, v254, 30
	s_cbranch_scc0 .LBB0_1379
	s_getpc_b64 s[98:99]
